# K-loop: all 192 loader VALU address adds removed (saddr LDS-DMA, offset:128, 2 spare SGPR pairs)
# speedup vs baseline: 1.0041x; 1.0041x over previous
.LBB0_556:
	ds_read_b128 v[0:3], v211
	ds_read_b128 v[4:7], v211 offset:1024
	ds_read_b128 v[8:11], v211 offset:2048
	ds_read_b128 v[12:15], v211 offset:3072
	ds_read_b128 v[144:147], v212
	ds_read_b128 v[170:173], v212 offset:1024
	ds_read_b128 v[174:177], v212 offset:2048
	ds_read_b128 v[178:181], v212 offset:3072
	s_add_u32 s8, s6, 0xfff80080
	s_addc_u32 s9, s7, -1
	s_cmp_eq_u32 s61, 28
	s_cselect_b32 s11, s55, s9
	s_cselect_b32 s10, s54, s8
	s_cselect_b32 s9, s57, s60
	s_cselect_b32 s8, s56, s5
	s_nop 0
	s_add_i32 m0, s17, 0xc000
	ds_read_b128 v[182:185], v213
	ds_read_b128 v[186:189], v213 offset:1024
	ds_read_b128 v[190:193], v213 offset:2048
	ds_read_b128 v[194:197], v213 offset:3072
	ds_read_b128 v[198:201], v213 offset:4096
	ds_read_b128 v[218:221], v213 offset:5120
	ds_read_b128 v[222:225], v213 offset:6144
	ds_read_b128 v[226:229], v213 offset:7168
	global_load_lds_dwordx4 v162, s[6:7]
	s_nop 0
	s_add_i32 m0, s17, 0xe000
	s_nop 0
	global_load_lds_dwordx4 v160, s[6:7]
	s_waitcnt vmcnt(8)
	s_waitcnt lgkmcnt(0)
	s_setprio 1
	s_barrier
	v_mfma_f32_16x16x32_bf16 v[92:95], v[0:3], v[182:185], v[92:95]
	v_mfma_f32_16x16x32_bf16 v[88:91], v[8:11], v[182:185], v[88:91]
	v_mfma_f32_16x16x32_bf16 v[116:119], v[0:3], v[190:193], v[116:119]
	v_mfma_f32_16x16x32_bf16 v[108:111], v[8:11], v[190:193], v[108:111]
	v_mfma_f32_16x16x32_bf16 v[124:127], v[0:3], v[198:201], v[124:127]
	v_mfma_f32_16x16x32_bf16 v[120:123], v[8:11], v[198:201], v[120:123]
	v_mfma_f32_16x16x32_bf16 v[100:103], v[0:3], v[222:225], v[100:103]
	v_mfma_f32_16x16x32_bf16 v[96:99], v[8:11], v[222:225], v[96:99]
	v_mfma_f32_16x16x32_bf16 v[92:95], v[4:7], v[186:189], v[92:95]
	v_mfma_f32_16x16x32_bf16 v[88:91], v[12:15], v[186:189], v[88:91]
	v_mfma_f32_16x16x32_bf16 v[116:119], v[4:7], v[194:197], v[116:119]
	v_mfma_f32_16x16x32_bf16 v[108:111], v[12:15], v[194:197], v[108:111]
	v_mfma_f32_16x16x32_bf16 v[124:127], v[4:7], v[218:221], v[124:127]
	v_mfma_f32_16x16x32_bf16 v[120:123], v[12:15], v[218:221], v[120:123]
	v_mfma_f32_16x16x32_bf16 v[100:103], v[4:7], v[226:229], v[100:103]
	v_mfma_f32_16x16x32_bf16 v[96:99], v[12:15], v[226:229], v[96:99]
	v_mfma_f32_16x16x32_bf16 v[140:143], v[144:147], v[182:185], v[140:143]
	v_mfma_f32_16x16x32_bf16 v[136:139], v[174:177], v[182:185], v[136:139]
	v_mfma_f32_16x16x32_bf16 v[132:135], v[144:147], v[190:193], v[132:135]
	v_mfma_f32_16x16x32_bf16 v[128:131], v[174:177], v[190:193], v[128:131]
	v_mfma_f32_16x16x32_bf16 v[112:115], v[144:147], v[198:201], v[112:115]
	v_mfma_f32_16x16x32_bf16 v[104:107], v[174:177], v[198:201], v[104:107]
	v_mfma_f32_16x16x32_bf16 v[84:87], v[144:147], v[222:225], v[84:87]
	v_mfma_f32_16x16x32_bf16 v[80:83], v[174:177], v[222:225], v[80:83]
	v_mfma_f32_16x16x32_bf16 v[140:143], v[170:173], v[186:189], v[140:143]
	v_mfma_f32_16x16x32_bf16 v[136:139], v[178:181], v[186:189], v[136:139]
	v_mfma_f32_16x16x32_bf16 v[132:135], v[170:173], v[194:197], v[132:135]
	v_mfma_f32_16x16x32_bf16 v[128:131], v[178:181], v[194:197], v[128:131]
	v_mfma_f32_16x16x32_bf16 v[112:115], v[170:173], v[218:221], v[112:115]
	v_mfma_f32_16x16x32_bf16 v[104:107], v[178:181], v[218:221], v[104:107]
	v_mfma_f32_16x16x32_bf16 v[84:87], v[170:173], v[226:229], v[84:87]
	v_mfma_f32_16x16x32_bf16 v[80:83], v[178:181], v[226:229], v[80:83]
	s_barrier
	s_setprio 0
	s_add_i32 s62, s77, s23
	s_nop 0
	s_mov_b32 m0, s62
	ds_read_b128 v[182:185], v213 offset:16384
	ds_read_b128 v[186:189], v213 offset:17408
	ds_read_b128 v[190:193], v213 offset:18432
	ds_read_b128 v[194:197], v213 offset:19456
	ds_read_b128 v[198:201], v213 offset:20480
	ds_read_b128 v[218:221], v213 offset:21504
	ds_read_b128 v[222:225], v213 offset:22528
	ds_read_b128 v[226:229], v213 offset:23552
	global_load_lds_dwordx4 v150, s[8:9]
	s_add_i32 m0, s62, 0x2000
	s_add_u32 s62, s8, 0x80000
	s_mov_b64 s[98:99], s[8:9]
	s_addc_u32 s63, s9, 0
	s_add_i32 s92, s78, s23
	global_load_lds_dwordx4 v154, s[8:9]
	s_nop 0
	s_mov_b32 m0, s92
	s_mov_b64 s[100:101], s[10:11]
	global_load_lds_dwordx4 v150, s[62:63]
	s_nop 0
	s_add_i32 m0, s92, 0x2000
	s_nop 0
	global_load_lds_dwordx4 v154, s[62:63]
	s_nop 0
	s_mov_b32 m0, s17
	s_nop 0
	global_load_lds_dwordx4 v148, s[10:11]
	s_mov_b32 m0, s53
	s_nop 0
	global_load_lds_dwordx4 v152, s[10:11]
	s_waitcnt vmcnt(8)
	s_waitcnt lgkmcnt(0)
	s_setprio 1
	s_barrier
	v_mfma_f32_16x16x32_bf16 v[76:79], v[0:3], v[182:185], v[76:79]
	v_mfma_f32_16x16x32_bf16 v[72:75], v[8:11], v[182:185], v[72:75]
	v_mfma_f32_16x16x32_bf16 v[60:63], v[0:3], v[190:193], v[60:63]
	v_mfma_f32_16x16x32_bf16 v[56:59], v[8:11], v[190:193], v[56:59]
	v_mfma_f32_16x16x32_bf16 v[44:47], v[0:3], v[198:201], v[44:47]
	v_mfma_f32_16x16x32_bf16 v[40:43], v[8:11], v[198:201], v[40:43]
	v_mfma_f32_16x16x32_bf16 v[0:3], v[0:3], v[222:225], v[28:31]
	v_mfma_f32_16x16x32_bf16 v[76:79], v[4:7], v[186:189], v[76:79]
	v_mfma_f32_16x16x32_bf16 v[72:75], v[12:15], v[186:189], v[72:75]
	v_mfma_f32_16x16x32_bf16 v[60:63], v[4:7], v[194:197], v[60:63]
	v_mfma_f32_16x16x32_bf16 v[56:59], v[12:15], v[194:197], v[56:59]
	v_mfma_f32_16x16x32_bf16 v[44:47], v[4:7], v[218:221], v[44:47]
	v_mfma_f32_16x16x32_bf16 v[40:43], v[12:15], v[218:221], v[40:43]
	v_mfma_f32_16x16x32_bf16 v[0:3], v[4:7], v[226:229], v[0:3]
	v_mfma_f32_16x16x32_bf16 v[4:7], v[8:11], v[222:225], v[20:23]
	v_mfma_f32_16x16x32_bf16 v[4:7], v[12:15], v[226:229], v[4:7]
	v_mfma_f32_16x16x32_bf16 v[20:23], v[144:147], v[190:193], v[52:55]
	v_mfma_f32_16x16x32_bf16 v[52:55], v[170:173], v[194:197], v[20:23]
	v_mfma_f32_16x16x32_bf16 v[20:23], v[174:177], v[190:193], v[48:51]
	v_mfma_f32_16x16x32_bf16 v[48:51], v[178:181], v[194:197], v[20:23]
	v_mfma_f32_16x16x32_bf16 v[20:23], v[144:147], v[198:201], v[36:39]
	v_mfma_f32_16x16x32_bf16 v[36:39], v[170:173], v[218:221], v[20:23]
	v_mfma_f32_16x16x32_bf16 v[20:23], v[174:177], v[198:201], v[32:35]
	v_mfma_f32_16x16x32_bf16 v[32:35], v[178:181], v[218:221], v[20:23]
	v_mfma_f32_16x16x32_bf16 v[20:23], v[144:147], v[222:225], v[24:27]
	v_mfma_f32_16x16x32_bf16 v[16:19], v[174:177], v[222:225], v[16:19]
	v_mfma_f32_16x16x32_bf16 v[8:11], v[144:147], v[182:185], v[68:71]
	v_mfma_f32_16x16x32_bf16 v[12:15], v[174:177], v[182:185], v[64:67]
	v_mfma_f32_16x16x32_bf16 v[24:27], v[170:173], v[226:229], v[20:23]
	v_mfma_f32_16x16x32_bf16 v[16:19], v[178:181], v[226:229], v[16:19]
	v_mfma_f32_16x16x32_bf16 v[8:11], v[170:173], v[186:189], v[8:11]
	v_mfma_f32_16x16x32_bf16 v[12:15], v[178:181], v[186:189], v[12:15]
	s_barrier
	s_setprio 0
	ds_read_b128 v[20:23], v214
	ds_read_b128 v[28:31], v214 offset:1024
	ds_read_b128 v[64:67], v214 offset:2048
	ds_read_b128 v[68:71], v214 offset:3072
	ds_read_b128 v[144:147], v215
	ds_read_b128 v[170:173], v215 offset:1024
	ds_read_b128 v[174:177], v215 offset:2048
	ds_read_b128 v[178:181], v215 offset:3072
	s_add_u32 s10, s10, 0x80000
	s_addc_u32 s11, s11, 0
	s_mov_b32 m0, s64
	s_nop 0
	ds_read_b128 v[182:185], v213 offset:32768
	ds_read_b128 v[186:189], v213 offset:33792
	ds_read_b128 v[190:193], v213 offset:34816
	ds_read_b128 v[194:197], v213 offset:35840
	ds_read_b128 v[198:201], v213 offset:36864
	ds_read_b128 v[218:221], v213 offset:37888
	ds_read_b128 v[222:225], v213 offset:38912
	ds_read_b128 v[226:229], v213 offset:39936
	global_load_lds_dwordx4 v148, s[10:11]
	s_nop 0
	s_mov_b32 m0, s65
	s_nop 0
	global_load_lds_dwordx4 v152, s[10:11]
	s_waitcnt vmcnt(8)
	s_waitcnt lgkmcnt(0)
	s_setprio 1
	s_barrier
	v_mfma_f32_16x16x32_bf16 v[92:95], v[20:23], v[182:185], v[92:95]
	v_mfma_f32_16x16x32_bf16 v[88:91], v[64:67], v[182:185], v[88:91]
	v_mfma_f32_16x16x32_bf16 v[116:119], v[20:23], v[190:193], v[116:119]
	v_mfma_f32_16x16x32_bf16 v[108:111], v[64:67], v[190:193], v[108:111]
	v_mfma_f32_16x16x32_bf16 v[124:127], v[20:23], v[198:201], v[124:127]
	v_mfma_f32_16x16x32_bf16 v[120:123], v[64:67], v[198:201], v[120:123]
	v_mfma_f32_16x16x32_bf16 v[100:103], v[20:23], v[222:225], v[100:103]
	v_mfma_f32_16x16x32_bf16 v[96:99], v[64:67], v[222:225], v[96:99]
	v_mfma_f32_16x16x32_bf16 v[92:95], v[28:31], v[186:189], v[92:95]
	v_mfma_f32_16x16x32_bf16 v[88:91], v[68:71], v[186:189], v[88:91]
	v_mfma_f32_16x16x32_bf16 v[116:119], v[28:31], v[194:197], v[116:119]
	v_mfma_f32_16x16x32_bf16 v[108:111], v[68:71], v[194:197], v[108:111]
	v_mfma_f32_16x16x32_bf16 v[124:127], v[28:31], v[218:221], v[124:127]
	v_mfma_f32_16x16x32_bf16 v[120:123], v[68:71], v[218:221], v[120:123]
	v_mfma_f32_16x16x32_bf16 v[100:103], v[28:31], v[226:229], v[100:103]
	v_mfma_f32_16x16x32_bf16 v[96:99], v[68:71], v[226:229], v[96:99]
	v_mfma_f32_16x16x32_bf16 v[140:143], v[144:147], v[182:185], v[140:143]
	v_mfma_f32_16x16x32_bf16 v[136:139], v[174:177], v[182:185], v[136:139]
	v_mfma_f32_16x16x32_bf16 v[132:135], v[144:147], v[190:193], v[132:135]
	v_mfma_f32_16x16x32_bf16 v[128:131], v[174:177], v[190:193], v[128:131]
	v_mfma_f32_16x16x32_bf16 v[112:115], v[144:147], v[198:201], v[112:115]
	v_mfma_f32_16x16x32_bf16 v[104:107], v[174:177], v[198:201], v[104:107]
	v_mfma_f32_16x16x32_bf16 v[84:87], v[144:147], v[222:225], v[84:87]
	v_mfma_f32_16x16x32_bf16 v[80:83], v[174:177], v[222:225], v[80:83]
	v_mfma_f32_16x16x32_bf16 v[140:143], v[170:173], v[186:189], v[140:143]
	v_mfma_f32_16x16x32_bf16 v[136:139], v[178:181], v[186:189], v[136:139]
	v_mfma_f32_16x16x32_bf16 v[132:135], v[170:173], v[194:197], v[132:135]
	v_mfma_f32_16x16x32_bf16 v[128:131], v[178:181], v[194:197], v[128:131]
	v_mfma_f32_16x16x32_bf16 v[112:115], v[170:173], v[218:221], v[112:115]
	v_mfma_f32_16x16x32_bf16 v[104:107], v[178:181], v[218:221], v[104:107]
	v_mfma_f32_16x16x32_bf16 v[84:87], v[170:173], v[226:229], v[84:87]
	v_mfma_f32_16x16x32_bf16 v[80:83], v[178:181], v[226:229], v[80:83]
	s_barrier
	s_setprio 0
	s_add_i32 s10, s80, s23
	s_nop 0
	s_add_i32 m0, s10, 0xffffff80
	ds_read_b128 v[182:185], v213 offset:49152
	ds_read_b128 v[186:189], v213 offset:50176
	ds_read_b128 v[190:193], v213 offset:51200
	ds_read_b128 v[194:197], v213 offset:52224
	ds_read_b128 v[198:201], v213 offset:53248
	ds_read_b128 v[218:221], v213 offset:54272
	ds_read_b128 v[222:225], v213 offset:55296
	ds_read_b128 v[226:229], v213 offset:56320
	global_load_lds_dwordx4 v150, s[8:9] offset:128
	s_add_i32 m0, s10, 0x1f80
	s_add_u32 s8, s8, 0x80080
	s_nop 0
	s_addc_u32 s9, s9, 0
	s_add_i32 s10, s81, s23
	global_load_lds_dwordx4 v154, s[98:99] offset:128
	s_nop 0
	s_mov_b32 m0, s10
	s_nop 0
	global_load_lds_dwordx4 v150, s[8:9]
	s_nop 0
	s_add_i32 m0, s10, 0x2000
	s_nop 0
	global_load_lds_dwordx4 v154, s[8:9]
	s_nop 0
	s_add_i32 m0, s66, 0xffffff80
	s_nop 0
	global_load_lds_dwordx4 v148, s[100:101] offset:128
	s_nop 0
	s_add_i32 m0, s67, 0xffffff80
	s_nop 0
	global_load_lds_dwordx4 v152, s[100:101] offset:128
	s_waitcnt vmcnt(8)
	s_waitcnt lgkmcnt(0)
	s_setprio 1
	s_barrier
	v_mfma_f32_16x16x32_bf16 v[76:79], v[20:23], v[182:185], v[76:79]
	v_mfma_f32_16x16x32_bf16 v[60:63], v[20:23], v[190:193], v[60:63]
	v_mfma_f32_16x16x32_bf16 v[44:47], v[20:23], v[198:201], v[44:47]
	v_mfma_f32_16x16x32_bf16 v[0:3], v[20:23], v[222:225], v[0:3]
	v_mfma_f32_16x16x32_bf16 v[76:79], v[28:31], v[186:189], v[76:79]
	v_mfma_f32_16x16x32_bf16 v[72:75], v[64:67], v[182:185], v[72:75]
	v_mfma_f32_16x16x32_bf16 v[60:63], v[28:31], v[194:197], v[60:63]
	v_mfma_f32_16x16x32_bf16 v[56:59], v[64:67], v[190:193], v[56:59]
	v_mfma_f32_16x16x32_bf16 v[44:47], v[28:31], v[218:221], v[44:47]
	v_mfma_f32_16x16x32_bf16 v[40:43], v[64:67], v[198:201], v[40:43]
	v_mfma_f32_16x16x32_bf16 v[28:31], v[28:31], v[226:229], v[0:3]
	v_mfma_f32_16x16x32_bf16 v[0:3], v[64:67], v[222:225], v[4:7]
	v_mfma_f32_16x16x32_bf16 v[72:75], v[68:71], v[186:189], v[72:75]
	v_mfma_f32_16x16x32_bf16 v[56:59], v[68:71], v[194:197], v[56:59]
	v_mfma_f32_16x16x32_bf16 v[40:43], v[68:71], v[218:221], v[40:43]
	v_mfma_f32_16x16x32_bf16 v[20:23], v[68:71], v[226:229], v[0:3]
	v_mfma_f32_16x16x32_bf16 v[0:3], v[144:147], v[182:185], v[8:11]
	v_mfma_f32_16x16x32_bf16 v[68:71], v[170:173], v[186:189], v[0:3]
	v_mfma_f32_16x16x32_bf16 v[0:3], v[174:177], v[182:185], v[12:15]
	v_mfma_f32_16x16x32_bf16 v[64:67], v[178:181], v[186:189], v[0:3]
	v_mfma_f32_16x16x32_bf16 v[0:3], v[144:147], v[190:193], v[52:55]
	v_mfma_f32_16x16x32_bf16 v[52:55], v[170:173], v[194:197], v[0:3]
	v_mfma_f32_16x16x32_bf16 v[0:3], v[174:177], v[190:193], v[48:51]
	v_mfma_f32_16x16x32_bf16 v[48:51], v[178:181], v[194:197], v[0:3]
	v_mfma_f32_16x16x32_bf16 v[0:3], v[144:147], v[198:201], v[36:39]
	v_mfma_f32_16x16x32_bf16 v[36:39], v[170:173], v[218:221], v[0:3]
	v_mfma_f32_16x16x32_bf16 v[0:3], v[174:177], v[198:201], v[32:35]
	v_mfma_f32_16x16x32_bf16 v[32:35], v[178:181], v[218:221], v[0:3]
	v_mfma_f32_16x16x32_bf16 v[0:3], v[144:147], v[222:225], v[24:27]
	v_mfma_f32_16x16x32_bf16 v[24:27], v[170:173], v[226:229], v[0:3]
	v_mfma_f32_16x16x32_bf16 v[0:3], v[174:177], v[222:225], v[16:19]
	v_mfma_f32_16x16x32_bf16 v[16:19], v[178:181], v[226:229], v[0:3]
	s_barrier
	s_setprio 0
	s_add_i32 s61, s61, 2
	s_add_u32 s5, s5, 0x100
	s_addc_u32 s60, s60, 0
	s_add_u32 s6, s6, 0x100
	s_addc_u32 s7, s7, 0
	s_cmp_gt_u32 s61, 29
	s_cbranch_scc0 .LBB0_556
	s_and_b64 vcc, exec, s[34:35]
	s_cbranch_vccz .LBB0_559
	s_barrier

.LBB0_1778:
	s_or_b32 s42, s31, 1
	s_lshl_b64 s[92:93], s[42:43], 7
	s_add_i32 s42, s31, 2
	s_lshl_b64 vcc, s[42:43], 7
	s_add_u32 s40, s62, vcc_lo
	s_addc_u32 s41, s63, vcc_hi
	s_and_b64 s[72:73], s[70:71], exec
	s_cselect_b32 s73, s41, s57
	s_cselect_b32 s72, s40, s56
	s_add_u32 s40, s64, vcc_lo
	s_addc_u32 s41, s65, vcc_hi
	s_add_i32 s55, 0, 0x10000
	s_and_b64 s[70:71], s[70:71], exec
	s_cselect_b32 s71, s41, s59
	s_cselect_b32 s70, s40, s58
	s_add_i32 s40, 0, 0x14000
	v_add_u32_e32 v140, s55, v169
	v_add_u32_e32 v182, s40, v169
	ds_read_b128 v[128:131], v140
	ds_read_b128 v[132:135], v140 offset:1024
	ds_read_b128 v[136:139], v140 offset:2048
	ds_read_b128 v[140:143], v140 offset:3072
	ds_read_b128 v[160:163], v182
	ds_read_b128 v[174:177], v182 offset:1024
	ds_read_b128 v[178:181], v182 offset:2048
	ds_read_b128 v[182:185], v182 offset:3072
	s_add_u32 s41, s62, s92
	s_addc_u32 s61, s63, s93
	s_add_u32 s92, s41, 0x80000
	s_addc_u32 s93, s61, 0
	s_nop 0
	s_add_i32 m0, s7, 0xc000
	ds_read_b128 v[186:189], v173
	ds_read_b128 v[190:193], v173 offset:1024
	ds_read_b128 v[194:197], v173 offset:2048
	ds_read_b128 v[198:201], v173 offset:3072
	ds_read_b128 v[206:209], v173 offset:4096
	ds_read_b128 v[210:213], v173 offset:5120
	ds_read_b128 v[214:217], v173 offset:6144
	ds_read_b128 v[218:221], v173 offset:7168
	global_load_lds_dwordx4 v152, s[92:93]
	s_nop 0
	s_add_i32 m0, s7, 0xe000
	s_nop 0
	global_load_lds_dwordx4 v154, s[92:93]
	s_waitcnt vmcnt(8)
	s_waitcnt lgkmcnt(0)
	s_setprio 1
	s_barrier
	v_mfma_f32_16x16x32_bf16 v[124:127], v[128:131], v[186:189], v[124:127]
	v_mfma_f32_16x16x32_bf16 v[120:123], v[136:139], v[186:189], v[120:123]
	v_mfma_f32_16x16x32_bf16 v[108:111], v[128:131], v[194:197], v[108:111]
	v_mfma_f32_16x16x32_bf16 v[104:107], v[136:139], v[194:197], v[104:107]
	v_mfma_f32_16x16x32_bf16 v[92:95], v[128:131], v[206:209], v[92:95]
	v_mfma_f32_16x16x32_bf16 v[88:91], v[136:139], v[206:209], v[88:91]
	v_mfma_f32_16x16x32_bf16 v[76:79], v[128:131], v[214:217], v[76:79]
	v_mfma_f32_16x16x32_bf16 v[72:75], v[136:139], v[214:217], v[72:75]
	v_mfma_f32_16x16x32_bf16 v[124:127], v[132:135], v[190:193], v[124:127]
	v_mfma_f32_16x16x32_bf16 v[120:123], v[140:143], v[190:193], v[120:123]
	v_mfma_f32_16x16x32_bf16 v[108:111], v[132:135], v[198:201], v[108:111]
	v_mfma_f32_16x16x32_bf16 v[104:107], v[140:143], v[198:201], v[104:107]
	v_mfma_f32_16x16x32_bf16 v[92:95], v[132:135], v[210:213], v[92:95]
	v_mfma_f32_16x16x32_bf16 v[88:91], v[140:143], v[210:213], v[88:91]
	v_mfma_f32_16x16x32_bf16 v[76:79], v[132:135], v[218:221], v[76:79]
	v_mfma_f32_16x16x32_bf16 v[72:75], v[140:143], v[218:221], v[72:75]
	v_mfma_f32_16x16x32_bf16 v[116:119], v[160:163], v[186:189], v[116:119]
	v_mfma_f32_16x16x32_bf16 v[112:115], v[178:181], v[186:189], v[112:115]
	v_mfma_f32_16x16x32_bf16 v[100:103], v[160:163], v[194:197], v[100:103]
	v_mfma_f32_16x16x32_bf16 v[96:99], v[178:181], v[194:197], v[96:99]
	v_mfma_f32_16x16x32_bf16 v[84:87], v[160:163], v[206:209], v[84:87]
	v_mfma_f32_16x16x32_bf16 v[80:83], v[178:181], v[206:209], v[80:83]
	v_mfma_f32_16x16x32_bf16 v[68:71], v[160:163], v[214:217], v[68:71]
	v_mfma_f32_16x16x32_bf16 v[64:67], v[178:181], v[214:217], v[64:67]
	v_mfma_f32_16x16x32_bf16 v[116:119], v[174:177], v[190:193], v[116:119]
	v_mfma_f32_16x16x32_bf16 v[112:115], v[182:185], v[190:193], v[112:115]
	v_mfma_f32_16x16x32_bf16 v[100:103], v[174:177], v[198:201], v[100:103]
	v_mfma_f32_16x16x32_bf16 v[96:99], v[182:185], v[198:201], v[96:99]
	v_mfma_f32_16x16x32_bf16 v[84:87], v[174:177], v[210:213], v[84:87]
	v_mfma_f32_16x16x32_bf16 v[80:83], v[182:185], v[210:213], v[80:83]
	v_mfma_f32_16x16x32_bf16 v[68:71], v[174:177], v[218:221], v[68:71]
	v_mfma_f32_16x16x32_bf16 v[64:67], v[182:185], v[218:221], v[64:67]
	s_barrier
	s_setprio 0
	s_add_i32 s41, s55, s6
	s_nop 0
	s_mov_b32 m0, s41
	ds_read_b128 v[186:189], v173 offset:16384
	ds_read_b128 v[190:193], v173 offset:17408
	ds_read_b128 v[194:197], v173 offset:18432
	ds_read_b128 v[198:201], v173 offset:19456
	ds_read_b128 v[206:209], v173 offset:20480
	ds_read_b128 v[210:213], v173 offset:21504
	ds_read_b128 v[214:217], v173 offset:22528
	ds_read_b128 v[218:221], v173 offset:23552
	global_load_lds_dwordx4 v144, s[70:71]
	s_add_i32 m0, s41, 0x2000
	s_add_u32 s92, s70, 0x80000
	s_mov_b64 s[98:99], s[70:71]
	s_addc_u32 s93, s71, 0
	s_add_i32 s40, s40, s6
	global_load_lds_dwordx4 v156, s[70:71]
	s_nop 0
	s_mov_b32 m0, s40
	s_mov_b64 s[100:101], s[72:73]
	global_load_lds_dwordx4 v144, s[92:93]
	s_nop 0
	s_add_i32 m0, s40, 0x2000
	s_nop 0
	global_load_lds_dwordx4 v156, s[92:93]
	s_nop 0
	s_mov_b32 m0, s7
	s_nop 0
	global_load_lds_dwordx4 v152, s[72:73]
	s_mov_b32 m0, s8
	s_nop 0
	global_load_lds_dwordx4 v154, s[72:73]
	s_waitcnt vmcnt(8)
	s_waitcnt lgkmcnt(0)
	s_setprio 1
	s_barrier
	v_mfma_f32_16x16x32_bf16 v[60:63], v[128:131], v[186:189], v[60:63]
	v_mfma_f32_16x16x32_bf16 v[56:59], v[136:139], v[186:189], v[56:59]
	v_mfma_f32_16x16x32_bf16 v[44:47], v[128:131], v[194:197], v[44:47]
	v_mfma_f32_16x16x32_bf16 v[40:43], v[136:139], v[194:197], v[40:43]
	v_mfma_f32_16x16x32_bf16 v[24:27], v[128:131], v[206:209], v[24:27]
	v_mfma_f32_16x16x32_bf16 v[16:19], v[136:139], v[206:209], v[16:19]
	v_mfma_f32_16x16x32_bf16 v[4:7], v[128:131], v[214:217], v[4:7]
	v_mfma_f32_16x16x32_bf16 v[0:3], v[136:139], v[214:217], v[0:3]
	v_mfma_f32_16x16x32_bf16 v[60:63], v[132:135], v[190:193], v[60:63]
	v_mfma_f32_16x16x32_bf16 v[56:59], v[140:143], v[190:193], v[56:59]
	v_mfma_f32_16x16x32_bf16 v[44:47], v[132:135], v[198:201], v[44:47]
	v_mfma_f32_16x16x32_bf16 v[40:43], v[140:143], v[198:201], v[40:43]
	v_mfma_f32_16x16x32_bf16 v[24:27], v[132:135], v[210:213], v[24:27]
	v_mfma_f32_16x16x32_bf16 v[16:19], v[140:143], v[210:213], v[16:19]
	v_mfma_f32_16x16x32_bf16 v[4:7], v[132:135], v[218:221], v[4:7]
	v_mfma_f32_16x16x32_bf16 v[0:3], v[140:143], v[218:221], v[0:3]
	v_mfma_f32_16x16x32_bf16 v[52:55], v[160:163], v[186:189], v[52:55]
	v_mfma_f32_16x16x32_bf16 v[48:51], v[178:181], v[186:189], v[48:51]
	v_mfma_f32_16x16x32_bf16 v[28:31], v[160:163], v[194:197], v[28:31]
	v_mfma_f32_16x16x32_bf16 v[20:23], v[178:181], v[194:197], v[20:23]
	v_mfma_f32_16x16x32_bf16 v[32:35], v[160:163], v[206:209], v[32:35]
	v_mfma_f32_16x16x32_bf16 v[36:39], v[178:181], v[206:209], v[36:39]
	v_mfma_f32_16x16x32_bf16 v[8:11], v[160:163], v[214:217], v[8:11]
	v_mfma_f32_16x16x32_bf16 v[12:15], v[178:181], v[214:217], v[12:15]
	v_mfma_f32_16x16x32_bf16 v[52:55], v[174:177], v[190:193], v[52:55]
	v_mfma_f32_16x16x32_bf16 v[48:51], v[182:185], v[190:193], v[48:51]
	v_mfma_f32_16x16x32_bf16 v[28:31], v[174:177], v[198:201], v[28:31]
	v_mfma_f32_16x16x32_bf16 v[20:23], v[182:185], v[198:201], v[20:23]
	v_mfma_f32_16x16x32_bf16 v[32:35], v[174:177], v[210:213], v[32:35]
	v_mfma_f32_16x16x32_bf16 v[36:39], v[182:185], v[210:213], v[36:39]
	v_mfma_f32_16x16x32_bf16 v[8:11], v[174:177], v[218:221], v[8:11]
	v_mfma_f32_16x16x32_bf16 v[12:15], v[182:185], v[218:221], v[12:15]
	s_barrier
	s_setprio 0
	s_add_i32 s40, 0, 0x18000
	s_add_i32 s41, 0, 0x1c000
	v_add_u32_e32 v140, s40, v169
	v_add_u32_e32 v182, s41, v169
	ds_read_b128 v[128:131], v140
	ds_read_b128 v[132:135], v140 offset:1024
	ds_read_b128 v[136:139], v140 offset:2048
	ds_read_b128 v[140:143], v140 offset:3072
	ds_read_b128 v[160:163], v182
	ds_read_b128 v[174:177], v182 offset:1024
	ds_read_b128 v[178:181], v182 offset:2048
	ds_read_b128 v[182:185], v182 offset:3072
	s_add_u32 s72, s72, 0x80000
	s_addc_u32 s73, s73, 0
	s_mov_b32 m0, s9
	s_nop 0
	ds_read_b128 v[186:189], v173 offset:32768
	ds_read_b128 v[190:193], v173 offset:33792
	ds_read_b128 v[194:197], v173 offset:34816
	ds_read_b128 v[198:201], v173 offset:35840
	ds_read_b128 v[206:209], v173 offset:36864
	ds_read_b128 v[210:213], v173 offset:37888
	ds_read_b128 v[214:217], v173 offset:38912
	ds_read_b128 v[218:221], v173 offset:39936
	global_load_lds_dwordx4 v152, s[72:73]
	s_nop 0
	s_mov_b32 m0, s10
	s_nop 0
	global_load_lds_dwordx4 v154, s[72:73]
	s_waitcnt vmcnt(8)
	s_waitcnt lgkmcnt(0)
	s_setprio 1
	s_barrier
	v_mfma_f32_16x16x32_bf16 v[124:127], v[128:131], v[186:189], v[124:127]
	v_mfma_f32_16x16x32_bf16 v[120:123], v[136:139], v[186:189], v[120:123]
	v_mfma_f32_16x16x32_bf16 v[108:111], v[128:131], v[194:197], v[108:111]
	v_mfma_f32_16x16x32_bf16 v[104:107], v[136:139], v[194:197], v[104:107]
	v_mfma_f32_16x16x32_bf16 v[92:95], v[128:131], v[206:209], v[92:95]
	v_mfma_f32_16x16x32_bf16 v[88:91], v[136:139], v[206:209], v[88:91]
	v_mfma_f32_16x16x32_bf16 v[76:79], v[128:131], v[214:217], v[76:79]
	v_mfma_f32_16x16x32_bf16 v[72:75], v[136:139], v[214:217], v[72:75]
	v_mfma_f32_16x16x32_bf16 v[124:127], v[132:135], v[190:193], v[124:127]
	v_mfma_f32_16x16x32_bf16 v[120:123], v[140:143], v[190:193], v[120:123]
	v_mfma_f32_16x16x32_bf16 v[108:111], v[132:135], v[198:201], v[108:111]
	v_mfma_f32_16x16x32_bf16 v[104:107], v[140:143], v[198:201], v[104:107]
	v_mfma_f32_16x16x32_bf16 v[92:95], v[132:135], v[210:213], v[92:95]
	v_mfma_f32_16x16x32_bf16 v[88:91], v[140:143], v[210:213], v[88:91]
	v_mfma_f32_16x16x32_bf16 v[76:79], v[132:135], v[218:221], v[76:79]
	v_mfma_f32_16x16x32_bf16 v[72:75], v[140:143], v[218:221], v[72:75]
	v_mfma_f32_16x16x32_bf16 v[116:119], v[160:163], v[186:189], v[116:119]
	v_mfma_f32_16x16x32_bf16 v[112:115], v[178:181], v[186:189], v[112:115]
	v_mfma_f32_16x16x32_bf16 v[100:103], v[160:163], v[194:197], v[100:103]
	v_mfma_f32_16x16x32_bf16 v[96:99], v[178:181], v[194:197], v[96:99]
	v_mfma_f32_16x16x32_bf16 v[84:87], v[160:163], v[206:209], v[84:87]
	v_mfma_f32_16x16x32_bf16 v[80:83], v[178:181], v[206:209], v[80:83]
	v_mfma_f32_16x16x32_bf16 v[68:71], v[160:163], v[214:217], v[68:71]
	v_mfma_f32_16x16x32_bf16 v[64:67], v[178:181], v[214:217], v[64:67]
	v_mfma_f32_16x16x32_bf16 v[116:119], v[174:177], v[190:193], v[116:119]
	v_mfma_f32_16x16x32_bf16 v[112:115], v[182:185], v[190:193], v[112:115]
	v_mfma_f32_16x16x32_bf16 v[100:103], v[174:177], v[198:201], v[100:103]
	v_mfma_f32_16x16x32_bf16 v[96:99], v[182:185], v[198:201], v[96:99]
	v_mfma_f32_16x16x32_bf16 v[84:87], v[174:177], v[210:213], v[84:87]
	v_mfma_f32_16x16x32_bf16 v[80:83], v[182:185], v[210:213], v[80:83]
	v_mfma_f32_16x16x32_bf16 v[68:71], v[174:177], v[218:221], v[68:71]
	v_mfma_f32_16x16x32_bf16 v[64:67], v[182:185], v[218:221], v[64:67]
	s_barrier
	s_setprio 0
	s_add_i32 s40, s40, s6
	s_nop 0
	s_add_i32 m0, s40, 0xffffff80
	ds_read_b128 v[186:189], v173 offset:49152
	ds_read_b128 v[190:193], v173 offset:50176
	ds_read_b128 v[194:197], v173 offset:51200
	ds_read_b128 v[198:201], v173 offset:52224
	ds_read_b128 v[206:209], v173 offset:53248
	ds_read_b128 v[210:213], v173 offset:54272
	ds_read_b128 v[214:217], v173 offset:55296
	ds_read_b128 v[218:221], v173 offset:56320
	global_load_lds_dwordx4 v144, s[70:71] offset:128
	s_add_i32 m0, s40, 0x1f80
	s_add_u32 s70, s70, 0x80080
	s_nop 0
	s_addc_u32 s71, s71, 0
	s_add_i32 s40, s41, s6
	global_load_lds_dwordx4 v156, s[98:99] offset:128
	s_nop 0
	s_mov_b32 m0, s40
	s_nop 0
	global_load_lds_dwordx4 v144, s[70:71]
	s_nop 0
	s_add_i32 m0, s40, 0x2000
	s_nop 0
	global_load_lds_dwordx4 v156, s[70:71]
	s_nop 0
	s_add_i32 m0, s11, 0xffffff80
	s_nop 0
	global_load_lds_dwordx4 v152, s[100:101] offset:128
	s_nop 0
	s_add_i32 m0, s12, 0xffffff80
	s_nop 0
	global_load_lds_dwordx4 v154, s[100:101] offset:128
	s_waitcnt vmcnt(8)
	s_waitcnt lgkmcnt(0)
	s_setprio 1
	s_barrier
	v_mfma_f32_16x16x32_bf16 v[60:63], v[128:131], v[186:189], v[60:63]
	v_mfma_f32_16x16x32_bf16 v[56:59], v[136:139], v[186:189], v[56:59]
	v_mfma_f32_16x16x32_bf16 v[44:47], v[128:131], v[194:197], v[44:47]
	v_mfma_f32_16x16x32_bf16 v[40:43], v[136:139], v[194:197], v[40:43]
	v_mfma_f32_16x16x32_bf16 v[24:27], v[128:131], v[206:209], v[24:27]
	v_mfma_f32_16x16x32_bf16 v[16:19], v[136:139], v[206:209], v[16:19]
	v_mfma_f32_16x16x32_bf16 v[4:7], v[128:131], v[214:217], v[4:7]
	v_mfma_f32_16x16x32_bf16 v[0:3], v[136:139], v[214:217], v[0:3]
	v_mfma_f32_16x16x32_bf16 v[60:63], v[132:135], v[190:193], v[60:63]
	v_mfma_f32_16x16x32_bf16 v[56:59], v[140:143], v[190:193], v[56:59]
	v_mfma_f32_16x16x32_bf16 v[44:47], v[132:135], v[198:201], v[44:47]
	v_mfma_f32_16x16x32_bf16 v[40:43], v[140:143], v[198:201], v[40:43]
	v_mfma_f32_16x16x32_bf16 v[24:27], v[132:135], v[210:213], v[24:27]
	v_mfma_f32_16x16x32_bf16 v[16:19], v[140:143], v[210:213], v[16:19]
	v_mfma_f32_16x16x32_bf16 v[4:7], v[132:135], v[218:221], v[4:7]
	v_mfma_f32_16x16x32_bf16 v[0:3], v[140:143], v[218:221], v[0:3]
	v_mfma_f32_16x16x32_bf16 v[52:55], v[160:163], v[186:189], v[52:55]
	v_mfma_f32_16x16x32_bf16 v[48:51], v[178:181], v[186:189], v[48:51]
	v_mfma_f32_16x16x32_bf16 v[28:31], v[160:163], v[194:197], v[28:31]
	v_mfma_f32_16x16x32_bf16 v[20:23], v[178:181], v[194:197], v[20:23]
	v_mfma_f32_16x16x32_bf16 v[32:35], v[160:163], v[206:209], v[32:35]
	v_mfma_f32_16x16x32_bf16 v[36:39], v[178:181], v[206:209], v[36:39]
	v_mfma_f32_16x16x32_bf16 v[8:11], v[160:163], v[214:217], v[8:11]
	v_mfma_f32_16x16x32_bf16 v[12:15], v[178:181], v[214:217], v[12:15]
	v_mfma_f32_16x16x32_bf16 v[52:55], v[174:177], v[190:193], v[52:55]
	v_mfma_f32_16x16x32_bf16 v[48:51], v[182:185], v[190:193], v[48:51]
	v_mfma_f32_16x16x32_bf16 v[28:31], v[174:177], v[198:201], v[28:31]
	v_mfma_f32_16x16x32_bf16 v[20:23], v[182:185], v[198:201], v[20:23]
	v_mfma_f32_16x16x32_bf16 v[32:35], v[174:177], v[210:213], v[32:35]
	v_mfma_f32_16x16x32_bf16 v[36:39], v[182:185], v[210:213], v[36:39]
	v_mfma_f32_16x16x32_bf16 v[8:11], v[174:177], v[218:221], v[8:11]
	v_mfma_f32_16x16x32_bf16 v[12:15], v[182:185], v[218:221], v[12:15]
	s_barrier
	s_setprio 0
	s_cmp_gt_u32 s31, 29
	s_cbranch_scc1 .LBB0_1780
	s_mov_b32 s31, s42
	s_branch .LBB0_1766

.LBB0_1933:
	s_add_i32 s77, s26, 2
	s_add_u32 s92, s22, 0x80
	s_addc_u32 s27, s23, 0
	s_add_i32 s40, 0, 0x10000
	s_cmp_eq_u32 s73, s26
	s_cselect_b32 s27, s36, s27
	s_cselect_b32 s26, s37, s92
	s_cselect_b32 s93, s42, vcc_hi
	s_cselect_b32 s92, s61, vcc_lo
	s_add_i32 s41, 0, 0x14000
	v_add_u32_e32 v158, s40, v168
	v_add_u32_e32 v162, s41, v168
	ds_read_b128 v[128:131], v158
	ds_read_b128 v[132:135], v158 offset:1024
	ds_read_b128 v[154:157], v158 offset:2048
	ds_read_b128 v[158:161], v158 offset:3072
	ds_read_b128 v[172:175], v162
	ds_read_b128 v[176:179], v162 offset:1024
	ds_read_b128 v[180:183], v162 offset:2048
	ds_read_b128 v[184:187], v162 offset:3072
	s_nop 0
	s_add_i32 m0, s12, 0xc000
	ds_read_b128 v[188:191], v171
	ds_read_b128 v[192:195], v171 offset:1024
	ds_read_b128 v[196:199], v171 offset:2048
	ds_read_b128 v[200:203], v171 offset:3072
	ds_read_b128 v[206:209], v171 offset:4096
	ds_read_b128 v[210:213], v171 offset:5120
	ds_read_b128 v[214:217], v171 offset:6144
	ds_read_b128 v[218:221], v171 offset:7168
	global_load_lds_dwordx4 v152, s[22:23]
	s_nop 0
	s_add_i32 m0, s12, 0xe000
	s_nop 0
	global_load_lds_dwordx4 v142, s[22:23]
	s_waitcnt vmcnt(8)
	s_waitcnt lgkmcnt(0)
	s_setprio 1
	s_barrier
	v_mfma_f32_16x16x32_bf16 v[124:127], v[128:131], v[188:191], v[124:127]
	v_mfma_f32_16x16x32_bf16 v[120:123], v[154:157], v[188:191], v[120:123]
	v_mfma_f32_16x16x32_bf16 v[108:111], v[128:131], v[196:199], v[108:111]
	v_mfma_f32_16x16x32_bf16 v[104:107], v[154:157], v[196:199], v[104:107]
	v_mfma_f32_16x16x32_bf16 v[92:95], v[128:131], v[206:209], v[92:95]
	v_mfma_f32_16x16x32_bf16 v[88:91], v[154:157], v[206:209], v[88:91]
	v_mfma_f32_16x16x32_bf16 v[76:79], v[128:131], v[214:217], v[76:79]
	v_mfma_f32_16x16x32_bf16 v[72:75], v[154:157], v[214:217], v[72:75]
	v_mfma_f32_16x16x32_bf16 v[124:127], v[132:135], v[192:195], v[124:127]
	v_mfma_f32_16x16x32_bf16 v[120:123], v[158:161], v[192:195], v[120:123]
	v_mfma_f32_16x16x32_bf16 v[108:111], v[132:135], v[200:203], v[108:111]
	v_mfma_f32_16x16x32_bf16 v[104:107], v[158:161], v[200:203], v[104:107]
	v_mfma_f32_16x16x32_bf16 v[92:95], v[132:135], v[210:213], v[92:95]
	v_mfma_f32_16x16x32_bf16 v[88:91], v[158:161], v[210:213], v[88:91]
	v_mfma_f32_16x16x32_bf16 v[76:79], v[132:135], v[218:221], v[76:79]
	v_mfma_f32_16x16x32_bf16 v[72:75], v[158:161], v[218:221], v[72:75]
	v_mfma_f32_16x16x32_bf16 v[116:119], v[172:175], v[188:191], v[116:119]
	v_mfma_f32_16x16x32_bf16 v[112:115], v[180:183], v[188:191], v[112:115]
	v_mfma_f32_16x16x32_bf16 v[100:103], v[172:175], v[196:199], v[100:103]
	v_mfma_f32_16x16x32_bf16 v[96:99], v[180:183], v[196:199], v[96:99]
	v_mfma_f32_16x16x32_bf16 v[84:87], v[172:175], v[206:209], v[84:87]
	v_mfma_f32_16x16x32_bf16 v[80:83], v[180:183], v[206:209], v[80:83]
	v_mfma_f32_16x16x32_bf16 v[68:71], v[172:175], v[214:217], v[68:71]
	v_mfma_f32_16x16x32_bf16 v[64:67], v[180:183], v[214:217], v[64:67]
	v_mfma_f32_16x16x32_bf16 v[116:119], v[176:179], v[192:195], v[116:119]
	v_mfma_f32_16x16x32_bf16 v[112:115], v[184:187], v[192:195], v[112:115]
	v_mfma_f32_16x16x32_bf16 v[100:103], v[176:179], v[200:203], v[100:103]
	v_mfma_f32_16x16x32_bf16 v[96:99], v[184:187], v[200:203], v[96:99]
	v_mfma_f32_16x16x32_bf16 v[84:87], v[176:179], v[210:213], v[84:87]
	v_mfma_f32_16x16x32_bf16 v[80:83], v[184:187], v[210:213], v[80:83]
	v_mfma_f32_16x16x32_bf16 v[68:71], v[176:179], v[218:221], v[68:71]
	v_mfma_f32_16x16x32_bf16 v[64:67], v[184:187], v[218:221], v[64:67]
	s_barrier
	s_setprio 0
	s_add_i32 s40, s40, s11
	s_mov_b64 s[98:99], s[92:93]
	s_mov_b32 m0, s40
	ds_read_b128 v[188:191], v171 offset:16384
	ds_read_b128 v[192:195], v171 offset:17408
	ds_read_b128 v[196:199], v171 offset:18432
	ds_read_b128 v[200:203], v171 offset:19456
	ds_read_b128 v[206:209], v171 offset:20480
	ds_read_b128 v[210:213], v171 offset:21504
	ds_read_b128 v[214:217], v171 offset:22528
	ds_read_b128 v[218:221], v171 offset:23552
	global_load_lds_dwordx4 v144, s[92:93]
	s_add_i32 m0, s40, 0x2000
	s_nop 0
	s_add_u32 s92, s92, s48
	s_addc_u32 s93, s93, 0
	s_add_i32 s40, s41, s11
	global_load_lds_dwordx4 v140, s[98:99]
	s_nop 0
	s_mov_b32 m0, s40
	s_nop 0
	global_load_lds_dwordx4 v144, s[92:93]
	s_add_i32 m0, s40, 0x2000
	s_mov_b64 s[100:101], s[26:27]
	global_load_lds_dwordx4 v140, s[92:93]
	s_mov_b32 m0, s12
	s_nop 0
	global_load_lds_dwordx4 v136, s[26:27]
	s_mov_b32 m0, s13
	s_nop 0
	global_load_lds_dwordx4 v138, s[26:27]
	s_waitcnt vmcnt(8)
	s_waitcnt lgkmcnt(0)
	s_setprio 1
	s_barrier
	v_mfma_f32_16x16x32_bf16 v[60:63], v[128:131], v[188:191], v[60:63]
	v_mfma_f32_16x16x32_bf16 v[56:59], v[154:157], v[188:191], v[56:59]
	v_mfma_f32_16x16x32_bf16 v[44:47], v[128:131], v[196:199], v[44:47]
	v_mfma_f32_16x16x32_bf16 v[40:43], v[154:157], v[196:199], v[40:43]
	v_mfma_f32_16x16x32_bf16 v[28:31], v[128:131], v[206:209], v[28:31]
	v_mfma_f32_16x16x32_bf16 v[24:27], v[154:157], v[206:209], v[24:27]
	v_mfma_f32_16x16x32_bf16 v[12:15], v[128:131], v[214:217], v[12:15]
	v_mfma_f32_16x16x32_bf16 v[8:11], v[154:157], v[214:217], v[8:11]
	v_mfma_f32_16x16x32_bf16 v[60:63], v[132:135], v[192:195], v[60:63]
	v_mfma_f32_16x16x32_bf16 v[56:59], v[158:161], v[192:195], v[56:59]
	v_mfma_f32_16x16x32_bf16 v[44:47], v[132:135], v[200:203], v[44:47]
	v_mfma_f32_16x16x32_bf16 v[40:43], v[158:161], v[200:203], v[40:43]
	v_mfma_f32_16x16x32_bf16 v[28:31], v[132:135], v[210:213], v[28:31]
	v_mfma_f32_16x16x32_bf16 v[24:27], v[158:161], v[210:213], v[24:27]
	v_mfma_f32_16x16x32_bf16 v[12:15], v[132:135], v[218:221], v[12:15]
	v_mfma_f32_16x16x32_bf16 v[8:11], v[158:161], v[218:221], v[8:11]
	v_mfma_f32_16x16x32_bf16 v[52:55], v[172:175], v[188:191], v[52:55]
	v_mfma_f32_16x16x32_bf16 v[48:51], v[180:183], v[188:191], v[48:51]
	v_mfma_f32_16x16x32_bf16 v[36:39], v[172:175], v[196:199], v[36:39]
	v_mfma_f32_16x16x32_bf16 v[32:35], v[180:183], v[196:199], v[32:35]
	v_mfma_f32_16x16x32_bf16 v[20:23], v[172:175], v[206:209], v[20:23]
	v_mfma_f32_16x16x32_bf16 v[16:19], v[180:183], v[206:209], v[16:19]
	v_mfma_f32_16x16x32_bf16 v[4:7], v[172:175], v[214:217], v[4:7]
	v_mfma_f32_16x16x32_bf16 v[0:3], v[180:183], v[214:217], v[0:3]
	v_mfma_f32_16x16x32_bf16 v[52:55], v[176:179], v[192:195], v[52:55]
	v_mfma_f32_16x16x32_bf16 v[48:51], v[184:187], v[192:195], v[48:51]
	v_mfma_f32_16x16x32_bf16 v[36:39], v[176:179], v[200:203], v[36:39]
	v_mfma_f32_16x16x32_bf16 v[32:35], v[184:187], v[200:203], v[32:35]
	v_mfma_f32_16x16x32_bf16 v[20:23], v[176:179], v[210:213], v[20:23]
	v_mfma_f32_16x16x32_bf16 v[16:19], v[184:187], v[210:213], v[16:19]
	v_mfma_f32_16x16x32_bf16 v[4:7], v[176:179], v[218:221], v[4:7]
	v_mfma_f32_16x16x32_bf16 v[0:3], v[184:187], v[218:221], v[0:3]
	s_barrier
	s_setprio 0
	s_add_i32 s40, 0, 0x18000
	s_add_i32 s41, 0, 0x1c000
	v_add_u32_e32 v158, s40, v168
	v_add_u32_e32 v184, s41, v168
	ds_read_b128 v[128:131], v158
	ds_read_b128 v[132:135], v158 offset:1024
	ds_read_b128 v[154:157], v158 offset:2048
	ds_read_b128 v[158:161], v158 offset:3072
	ds_read_b128 v[172:175], v184
	ds_read_b128 v[176:179], v184 offset:1024
	ds_read_b128 v[180:183], v184 offset:2048
	ds_read_b128 v[184:187], v184 offset:3072
	s_add_u32 s26, s26, s48
	s_addc_u32 s27, s27, 0
	s_mov_b32 m0, s28
	s_nop 0
	ds_read_b128 v[188:191], v171 offset:32768
	ds_read_b128 v[192:195], v171 offset:33792
	ds_read_b128 v[196:199], v171 offset:34816
	ds_read_b128 v[200:203], v171 offset:35840
	ds_read_b128 v[206:209], v171 offset:36864
	ds_read_b128 v[210:213], v171 offset:37888
	ds_read_b128 v[214:217], v171 offset:38912
	ds_read_b128 v[218:221], v171 offset:39936
	global_load_lds_dwordx4 v136, s[26:27]
	s_nop 0
	s_mov_b32 m0, s29
	s_nop 0
	global_load_lds_dwordx4 v138, s[26:27]
	s_waitcnt vmcnt(8)
	s_waitcnt lgkmcnt(0)
	s_setprio 1
	s_barrier
	v_mfma_f32_16x16x32_bf16 v[124:127], v[128:131], v[188:191], v[124:127]
	v_mfma_f32_16x16x32_bf16 v[120:123], v[154:157], v[188:191], v[120:123]
	v_mfma_f32_16x16x32_bf16 v[108:111], v[128:131], v[196:199], v[108:111]
	v_mfma_f32_16x16x32_bf16 v[104:107], v[154:157], v[196:199], v[104:107]
	v_mfma_f32_16x16x32_bf16 v[92:95], v[128:131], v[206:209], v[92:95]
	v_mfma_f32_16x16x32_bf16 v[88:91], v[154:157], v[206:209], v[88:91]
	v_mfma_f32_16x16x32_bf16 v[76:79], v[128:131], v[214:217], v[76:79]
	v_mfma_f32_16x16x32_bf16 v[72:75], v[154:157], v[214:217], v[72:75]
	v_mfma_f32_16x16x32_bf16 v[124:127], v[132:135], v[192:195], v[124:127]
	v_mfma_f32_16x16x32_bf16 v[120:123], v[158:161], v[192:195], v[120:123]
	v_mfma_f32_16x16x32_bf16 v[108:111], v[132:135], v[200:203], v[108:111]
	v_mfma_f32_16x16x32_bf16 v[104:107], v[158:161], v[200:203], v[104:107]
	v_mfma_f32_16x16x32_bf16 v[92:95], v[132:135], v[210:213], v[92:95]
	v_mfma_f32_16x16x32_bf16 v[88:91], v[158:161], v[210:213], v[88:91]
	v_mfma_f32_16x16x32_bf16 v[76:79], v[132:135], v[218:221], v[76:79]
	v_mfma_f32_16x16x32_bf16 v[72:75], v[158:161], v[218:221], v[72:75]
	v_mfma_f32_16x16x32_bf16 v[116:119], v[172:175], v[188:191], v[116:119]
	v_mfma_f32_16x16x32_bf16 v[112:115], v[180:183], v[188:191], v[112:115]
	v_mfma_f32_16x16x32_bf16 v[100:103], v[172:175], v[196:199], v[100:103]
	v_mfma_f32_16x16x32_bf16 v[96:99], v[180:183], v[196:199], v[96:99]
	v_mfma_f32_16x16x32_bf16 v[84:87], v[172:175], v[206:209], v[84:87]
	v_mfma_f32_16x16x32_bf16 v[80:83], v[180:183], v[206:209], v[80:83]
	v_mfma_f32_16x16x32_bf16 v[68:71], v[172:175], v[214:217], v[68:71]
	v_mfma_f32_16x16x32_bf16 v[64:67], v[180:183], v[214:217], v[64:67]
	v_mfma_f32_16x16x32_bf16 v[116:119], v[176:179], v[192:195], v[116:119]
	v_mfma_f32_16x16x32_bf16 v[112:115], v[184:187], v[192:195], v[112:115]
	v_mfma_f32_16x16x32_bf16 v[100:103], v[176:179], v[200:203], v[100:103]
	v_mfma_f32_16x16x32_bf16 v[96:99], v[184:187], v[200:203], v[96:99]
	v_mfma_f32_16x16x32_bf16 v[84:87], v[176:179], v[210:213], v[84:87]
	v_mfma_f32_16x16x32_bf16 v[80:83], v[184:187], v[210:213], v[80:83]
	v_mfma_f32_16x16x32_bf16 v[68:71], v[176:179], v[218:221], v[68:71]
	v_mfma_f32_16x16x32_bf16 v[64:67], v[184:187], v[218:221], v[64:67]
	s_barrier
	s_setprio 0
	s_add_i32 s26, s40, s11
	s_nop 0
	s_add_i32 m0, s26, 0xffffff80
	ds_read_b128 v[188:191], v171 offset:49152
	ds_read_b128 v[192:195], v171 offset:50176
	ds_read_b128 v[196:199], v171 offset:51200
	ds_read_b128 v[200:203], v171 offset:52224
	ds_read_b128 v[206:209], v171 offset:53248
	ds_read_b128 v[210:213], v171 offset:54272
	ds_read_b128 v[214:217], v171 offset:55296
	ds_read_b128 v[218:221], v171 offset:56320
	global_load_lds_dwordx4 v144, s[98:99] offset:128
	s_nop 0
	s_add_i32 m0, s26, 0x1f80
	s_add_i32 s26, s41, s11
	global_load_lds_dwordx4 v140, s[98:99] offset:128
	s_nop 0
	s_add_i32 m0, s26, 0xffffff80
	s_nop 0
	global_load_lds_dwordx4 v144, s[92:93] offset:128
	s_nop 0
	s_add_i32 m0, s26, 0x1f80
	s_nop 0
	global_load_lds_dwordx4 v140, s[92:93] offset:128
	s_nop 0
	s_add_i32 m0, s68, 0xffffff80
	s_nop 0
	global_load_lds_dwordx4 v136, s[100:101] offset:128
	s_nop 0
	s_add_i32 m0, s69, 0xffffff80
	s_nop 0
	global_load_lds_dwordx4 v138, s[100:101] offset:128
	s_waitcnt vmcnt(8)
	s_waitcnt lgkmcnt(0)
	s_setprio 1
	s_barrier
	v_mfma_f32_16x16x32_bf16 v[60:63], v[128:131], v[188:191], v[60:63]
	v_mfma_f32_16x16x32_bf16 v[56:59], v[154:157], v[188:191], v[56:59]
	v_mfma_f32_16x16x32_bf16 v[44:47], v[128:131], v[196:199], v[44:47]
	v_mfma_f32_16x16x32_bf16 v[40:43], v[154:157], v[196:199], v[40:43]
	v_mfma_f32_16x16x32_bf16 v[28:31], v[128:131], v[206:209], v[28:31]
	v_mfma_f32_16x16x32_bf16 v[24:27], v[154:157], v[206:209], v[24:27]
	v_mfma_f32_16x16x32_bf16 v[12:15], v[128:131], v[214:217], v[12:15]
	v_mfma_f32_16x16x32_bf16 v[8:11], v[154:157], v[214:217], v[8:11]
	v_mfma_f32_16x16x32_bf16 v[60:63], v[132:135], v[192:195], v[60:63]
	v_mfma_f32_16x16x32_bf16 v[56:59], v[158:161], v[192:195], v[56:59]
	v_mfma_f32_16x16x32_bf16 v[44:47], v[132:135], v[200:203], v[44:47]
	v_mfma_f32_16x16x32_bf16 v[40:43], v[158:161], v[200:203], v[40:43]
	v_mfma_f32_16x16x32_bf16 v[28:31], v[132:135], v[210:213], v[28:31]
	v_mfma_f32_16x16x32_bf16 v[24:27], v[158:161], v[210:213], v[24:27]
	v_mfma_f32_16x16x32_bf16 v[12:15], v[132:135], v[218:221], v[12:15]
	v_mfma_f32_16x16x32_bf16 v[8:11], v[158:161], v[218:221], v[8:11]
	v_mfma_f32_16x16x32_bf16 v[52:55], v[172:175], v[188:191], v[52:55]
	v_mfma_f32_16x16x32_bf16 v[48:51], v[180:183], v[188:191], v[48:51]
	v_mfma_f32_16x16x32_bf16 v[36:39], v[172:175], v[196:199], v[36:39]
	v_mfma_f32_16x16x32_bf16 v[32:35], v[180:183], v[196:199], v[32:35]
	v_mfma_f32_16x16x32_bf16 v[20:23], v[172:175], v[206:209], v[20:23]
	v_mfma_f32_16x16x32_bf16 v[16:19], v[180:183], v[206:209], v[16:19]
	v_mfma_f32_16x16x32_bf16 v[4:7], v[172:175], v[214:217], v[4:7]
	v_mfma_f32_16x16x32_bf16 v[0:3], v[180:183], v[214:217], v[0:3]
	v_mfma_f32_16x16x32_bf16 v[52:55], v[176:179], v[192:195], v[52:55]
	v_mfma_f32_16x16x32_bf16 v[48:51], v[184:187], v[192:195], v[48:51]
	v_mfma_f32_16x16x32_bf16 v[36:39], v[176:179], v[200:203], v[36:39]
	v_mfma_f32_16x16x32_bf16 v[32:35], v[184:187], v[200:203], v[32:35]
	v_mfma_f32_16x16x32_bf16 v[20:23], v[176:179], v[210:213], v[20:23]
	v_mfma_f32_16x16x32_bf16 v[16:19], v[184:187], v[210:213], v[16:19]
	v_mfma_f32_16x16x32_bf16 v[4:7], v[176:179], v[218:221], v[4:7]
	v_mfma_f32_16x16x32_bf16 v[0:3], v[184:187], v[218:221], v[0:3]
	s_barrier
	s_setprio 0
	s_add_u32 vcc_lo, vcc_lo, 0x100
	s_addc_u32 vcc_hi, vcc_hi, 0
	s_add_u32 s22, s22, 0x100
	s_addc_u32 s23, s23, 0
	s_cmp_ge_i32 s77, s1
	s_mov_b32 s26, s77
	s_cbranch_scc0 .LBB0_1933
	s_and_b64 vcc, exec, s[52:53]
	s_cbranch_vccz .LBB0_1936

.LBB0_2145:
	s_or_b32 s50, s23, 1
	s_lshl_b64 s[88:89], s[50:51], 7
	s_add_i32 s50, s23, 2
	s_lshl_b64 s[90:91], s[50:51], 7
	v_add_u32_e32 v116, s74, v197
	v_add_u32_e32 v174, s75, v197
	s_add_u32 s43, s26, s90
	ds_read_b128 v[104:107], v116
	ds_read_b128 v[108:111], v116 offset:1024
	ds_read_b128 v[112:115], v116 offset:2048
	ds_read_b128 v[116:119], v116 offset:3072
	ds_read_b128 v[144:147], v174
	ds_read_b128 v[166:169], v174 offset:1024
	ds_read_b128 v[170:173], v174 offset:2048
	ds_read_b128 v[174:177], v174 offset:3072
	s_addc_u32 s87, s27, s91
	s_and_b64 s[72:73], s[70:71], exec
	s_cselect_b32 s73, s87, s63
	s_cselect_b32 s72, s43, s62
	s_add_u32 s43, s40, s90
	s_addc_u32 s87, s41, s91
	s_and_b64 s[70:71], s[70:71], exec
	s_cselect_b32 s71, s87, s65
	s_cselect_b32 s70, s43, s64
	s_add_u32 s43, s26, s88
	s_addc_u32 s87, s27, s89
	s_add_u32 s88, s43, 0x80000
	s_addc_u32 s89, s87, 0
	s_nop 0
	s_add_i32 m0, s7, 0xc000
	ds_read_b128 v[178:181], v156
	ds_read_b128 v[182:185], v156 offset:1024
	ds_read_b128 v[186:189], v156 offset:2048
	ds_read_b128 v[190:193], v156 offset:3072
	ds_read_b128 v[200:203], v156 offset:4096
	ds_read_b128 v[206:209], v156 offset:5120
	ds_read_b128 v[210:213], v156 offset:6144
	ds_read_b128 v[214:217], v156 offset:7168
	global_load_lds_dwordx4 v148, s[88:89]
	s_nop 0
	s_add_i32 m0, s7, 0xe000
	s_nop 0
	global_load_lds_dwordx4 v152, s[88:89]
	s_waitcnt vmcnt(8)
	s_waitcnt lgkmcnt(0)
	s_setprio 1
	s_barrier
	v_mfma_f32_16x16x32_bf16 v[140:143], v[104:107], v[178:181], v[140:143]
	v_mfma_f32_16x16x32_bf16 v[136:139], v[112:115], v[178:181], v[136:139]
	v_mfma_f32_16x16x32_bf16 v[124:127], v[104:107], v[186:189], v[124:127]
	v_mfma_f32_16x16x32_bf16 v[120:123], v[112:115], v[186:189], v[120:123]
	v_mfma_f32_16x16x32_bf16 v[92:95], v[104:107], v[200:203], v[92:95]
	v_mfma_f32_16x16x32_bf16 v[88:91], v[112:115], v[200:203], v[88:91]
	v_mfma_f32_16x16x32_bf16 v[76:79], v[104:107], v[210:213], v[76:79]
	v_mfma_f32_16x16x32_bf16 v[72:75], v[112:115], v[210:213], v[72:75]
	v_mfma_f32_16x16x32_bf16 v[140:143], v[108:111], v[182:185], v[140:143]
	v_mfma_f32_16x16x32_bf16 v[136:139], v[116:119], v[182:185], v[136:139]
	v_mfma_f32_16x16x32_bf16 v[124:127], v[108:111], v[190:193], v[124:127]
	v_mfma_f32_16x16x32_bf16 v[120:123], v[116:119], v[190:193], v[120:123]
	v_mfma_f32_16x16x32_bf16 v[92:95], v[108:111], v[206:209], v[92:95]
	v_mfma_f32_16x16x32_bf16 v[88:91], v[116:119], v[206:209], v[88:91]
	v_mfma_f32_16x16x32_bf16 v[76:79], v[108:111], v[214:217], v[76:79]
	v_mfma_f32_16x16x32_bf16 v[72:75], v[116:119], v[214:217], v[72:75]
	v_mfma_f32_16x16x32_bf16 v[132:135], v[144:147], v[178:181], v[132:135]
	v_mfma_f32_16x16x32_bf16 v[128:131], v[170:173], v[178:181], v[128:131]
	v_mfma_f32_16x16x32_bf16 v[100:103], v[144:147], v[186:189], v[100:103]
	v_mfma_f32_16x16x32_bf16 v[96:99], v[170:173], v[186:189], v[96:99]
	v_mfma_f32_16x16x32_bf16 v[84:87], v[144:147], v[200:203], v[84:87]
	v_mfma_f32_16x16x32_bf16 v[80:83], v[170:173], v[200:203], v[80:83]
	v_mfma_f32_16x16x32_bf16 v[68:71], v[144:147], v[210:213], v[68:71]
	v_mfma_f32_16x16x32_bf16 v[64:67], v[170:173], v[210:213], v[64:67]
	v_mfma_f32_16x16x32_bf16 v[132:135], v[166:169], v[182:185], v[132:135]
	v_mfma_f32_16x16x32_bf16 v[128:131], v[174:177], v[182:185], v[128:131]
	v_mfma_f32_16x16x32_bf16 v[100:103], v[166:169], v[190:193], v[100:103]
	v_mfma_f32_16x16x32_bf16 v[96:99], v[174:177], v[190:193], v[96:99]
	v_mfma_f32_16x16x32_bf16 v[84:87], v[166:169], v[206:209], v[84:87]
	v_mfma_f32_16x16x32_bf16 v[80:83], v[174:177], v[206:209], v[80:83]
	v_mfma_f32_16x16x32_bf16 v[68:71], v[166:169], v[214:217], v[68:71]
	v_mfma_f32_16x16x32_bf16 v[64:67], v[174:177], v[214:217], v[64:67]
	s_barrier
	s_setprio 0
	s_add_i32 s43, s74, s6
	s_nop 0
	s_mov_b32 m0, s43
	ds_read_b128 v[178:181], v156 offset:16384
	ds_read_b128 v[182:185], v156 offset:17408
	ds_read_b128 v[186:189], v156 offset:18432
	ds_read_b128 v[190:193], v156 offset:19456
	ds_read_b128 v[200:203], v156 offset:20480
	ds_read_b128 v[206:209], v156 offset:21504
	ds_read_b128 v[210:213], v156 offset:22528
	ds_read_b128 v[214:217], v156 offset:23552
	global_load_lds_dwordx4 v150, s[70:71]
	s_add_i32 m0, s43, 0x2000
	s_add_u32 s88, s70, 0x80000
	s_mov_b64 s[98:99], s[70:71]
	s_addc_u32 s89, s71, 0
	s_add_i32 s43, s75, s6
	global_load_lds_dwordx4 v154, s[70:71]
	s_nop 0
	s_mov_b32 m0, s43
	s_mov_b64 s[100:101], s[72:73]
	global_load_lds_dwordx4 v150, s[88:89]
	s_nop 0
	s_add_i32 m0, s43, 0x2000
	s_nop 0
	global_load_lds_dwordx4 v154, s[88:89]
	s_nop 0
	s_mov_b32 m0, s7
	s_nop 0
	global_load_lds_dwordx4 v148, s[72:73]
	s_mov_b32 m0, s8
	s_nop 0
	global_load_lds_dwordx4 v152, s[72:73]
	s_waitcnt vmcnt(8)
	s_waitcnt lgkmcnt(0)
	s_setprio 1
	s_barrier
	v_mfma_f32_16x16x32_bf16 v[60:63], v[104:107], v[178:181], v[60:63]
	v_mfma_f32_16x16x32_bf16 v[56:59], v[112:115], v[178:181], v[56:59]
	v_mfma_f32_16x16x32_bf16 v[44:47], v[104:107], v[186:189], v[44:47]
	v_mfma_f32_16x16x32_bf16 v[40:43], v[112:115], v[186:189], v[40:43]
	v_mfma_f32_16x16x32_bf16 v[20:23], v[104:107], v[200:203], v[20:23]
	v_mfma_f32_16x16x32_bf16 v[16:19], v[112:115], v[200:203], v[16:19]
	v_mfma_f32_16x16x32_bf16 v[4:7], v[104:107], v[210:213], v[4:7]
	v_mfma_f32_16x16x32_bf16 v[0:3], v[112:115], v[210:213], v[0:3]
	v_mfma_f32_16x16x32_bf16 v[60:63], v[108:111], v[182:185], v[60:63]
	v_mfma_f32_16x16x32_bf16 v[56:59], v[116:119], v[182:185], v[56:59]
	v_mfma_f32_16x16x32_bf16 v[44:47], v[108:111], v[190:193], v[44:47]
	v_mfma_f32_16x16x32_bf16 v[40:43], v[116:119], v[190:193], v[40:43]
	v_mfma_f32_16x16x32_bf16 v[20:23], v[108:111], v[206:209], v[20:23]
	v_mfma_f32_16x16x32_bf16 v[16:19], v[116:119], v[206:209], v[16:19]
	v_mfma_f32_16x16x32_bf16 v[4:7], v[108:111], v[214:217], v[4:7]
	v_mfma_f32_16x16x32_bf16 v[0:3], v[116:119], v[214:217], v[0:3]
	v_mfma_f32_16x16x32_bf16 v[52:55], v[144:147], v[178:181], v[52:55]
	v_mfma_f32_16x16x32_bf16 v[48:51], v[170:173], v[178:181], v[48:51]
	v_mfma_f32_16x16x32_bf16 v[36:39], v[144:147], v[186:189], v[36:39]
	v_mfma_f32_16x16x32_bf16 v[32:35], v[170:173], v[186:189], v[32:35]
	v_mfma_f32_16x16x32_bf16 v[28:31], v[144:147], v[200:203], v[28:31]
	v_mfma_f32_16x16x32_bf16 v[24:27], v[170:173], v[200:203], v[24:27]
	v_mfma_f32_16x16x32_bf16 v[12:15], v[144:147], v[210:213], v[12:15]
	v_mfma_f32_16x16x32_bf16 v[8:11], v[170:173], v[210:213], v[8:11]
	v_mfma_f32_16x16x32_bf16 v[52:55], v[166:169], v[182:185], v[52:55]
	v_mfma_f32_16x16x32_bf16 v[48:51], v[174:177], v[182:185], v[48:51]
	v_mfma_f32_16x16x32_bf16 v[36:39], v[166:169], v[190:193], v[36:39]
	v_mfma_f32_16x16x32_bf16 v[32:35], v[174:177], v[190:193], v[32:35]
	v_mfma_f32_16x16x32_bf16 v[28:31], v[166:169], v[206:209], v[28:31]
	v_mfma_f32_16x16x32_bf16 v[24:27], v[174:177], v[206:209], v[24:27]
	v_mfma_f32_16x16x32_bf16 v[12:15], v[166:169], v[214:217], v[12:15]
	v_mfma_f32_16x16x32_bf16 v[8:11], v[174:177], v[214:217], v[8:11]
	s_barrier
	s_setprio 0
	v_add_u32_e32 v116, s76, v197
	v_add_u32_e32 v174, s77, v197
	ds_read_b128 v[104:107], v116
	ds_read_b128 v[108:111], v116 offset:1024
	ds_read_b128 v[112:115], v116 offset:2048
	ds_read_b128 v[116:119], v116 offset:3072
	ds_read_b128 v[144:147], v174
	ds_read_b128 v[166:169], v174 offset:1024
	ds_read_b128 v[170:173], v174 offset:2048
	ds_read_b128 v[174:177], v174 offset:3072
	s_add_u32 s72, s72, 0x80000
	s_addc_u32 s73, s73, 0
	s_mov_b32 m0, s9
	s_nop 0
	ds_read_b128 v[178:181], v156 offset:32768
	ds_read_b128 v[182:185], v156 offset:33792
	ds_read_b128 v[186:189], v156 offset:34816
	ds_read_b128 v[190:193], v156 offset:35840
	ds_read_b128 v[200:203], v156 offset:36864
	ds_read_b128 v[206:209], v156 offset:37888
	ds_read_b128 v[210:213], v156 offset:38912
	ds_read_b128 v[214:217], v156 offset:39936
	global_load_lds_dwordx4 v148, s[72:73]
	s_nop 0
	s_mov_b32 m0, s10
	s_nop 0
	global_load_lds_dwordx4 v152, s[72:73]
	s_waitcnt vmcnt(8)
	s_waitcnt lgkmcnt(0)
	s_setprio 1
	s_barrier
	v_mfma_f32_16x16x32_bf16 v[140:143], v[104:107], v[178:181], v[140:143]
	v_mfma_f32_16x16x32_bf16 v[136:139], v[112:115], v[178:181], v[136:139]
	v_mfma_f32_16x16x32_bf16 v[124:127], v[104:107], v[186:189], v[124:127]
	v_mfma_f32_16x16x32_bf16 v[120:123], v[112:115], v[186:189], v[120:123]
	v_mfma_f32_16x16x32_bf16 v[92:95], v[104:107], v[200:203], v[92:95]
	v_mfma_f32_16x16x32_bf16 v[88:91], v[112:115], v[200:203], v[88:91]
	v_mfma_f32_16x16x32_bf16 v[76:79], v[104:107], v[210:213], v[76:79]
	v_mfma_f32_16x16x32_bf16 v[72:75], v[112:115], v[210:213], v[72:75]
	v_mfma_f32_16x16x32_bf16 v[140:143], v[108:111], v[182:185], v[140:143]
	v_mfma_f32_16x16x32_bf16 v[136:139], v[116:119], v[182:185], v[136:139]
	v_mfma_f32_16x16x32_bf16 v[124:127], v[108:111], v[190:193], v[124:127]
	v_mfma_f32_16x16x32_bf16 v[120:123], v[116:119], v[190:193], v[120:123]
	v_mfma_f32_16x16x32_bf16 v[92:95], v[108:111], v[206:209], v[92:95]
	v_mfma_f32_16x16x32_bf16 v[88:91], v[116:119], v[206:209], v[88:91]
	v_mfma_f32_16x16x32_bf16 v[76:79], v[108:111], v[214:217], v[76:79]
	v_mfma_f32_16x16x32_bf16 v[72:75], v[116:119], v[214:217], v[72:75]
	v_mfma_f32_16x16x32_bf16 v[132:135], v[144:147], v[178:181], v[132:135]
	v_mfma_f32_16x16x32_bf16 v[128:131], v[170:173], v[178:181], v[128:131]
	v_mfma_f32_16x16x32_bf16 v[100:103], v[144:147], v[186:189], v[100:103]
	v_mfma_f32_16x16x32_bf16 v[96:99], v[170:173], v[186:189], v[96:99]
	v_mfma_f32_16x16x32_bf16 v[84:87], v[144:147], v[200:203], v[84:87]
	v_mfma_f32_16x16x32_bf16 v[80:83], v[170:173], v[200:203], v[80:83]
	v_mfma_f32_16x16x32_bf16 v[68:71], v[144:147], v[210:213], v[68:71]
	v_mfma_f32_16x16x32_bf16 v[64:67], v[170:173], v[210:213], v[64:67]
	v_mfma_f32_16x16x32_bf16 v[132:135], v[166:169], v[182:185], v[132:135]
	v_mfma_f32_16x16x32_bf16 v[128:131], v[174:177], v[182:185], v[128:131]
	v_mfma_f32_16x16x32_bf16 v[100:103], v[166:169], v[190:193], v[100:103]
	v_mfma_f32_16x16x32_bf16 v[96:99], v[174:177], v[190:193], v[96:99]
	v_mfma_f32_16x16x32_bf16 v[84:87], v[166:169], v[206:209], v[84:87]
	v_mfma_f32_16x16x32_bf16 v[80:83], v[174:177], v[206:209], v[80:83]
	v_mfma_f32_16x16x32_bf16 v[68:71], v[166:169], v[214:217], v[68:71]
	v_mfma_f32_16x16x32_bf16 v[64:67], v[174:177], v[214:217], v[64:67]
	s_barrier
	s_setprio 0
	s_add_i32 s43, s76, s6
	s_nop 0
	s_add_i32 m0, s43, 0xffffff80
	ds_read_b128 v[178:181], v156 offset:49152
	ds_read_b128 v[182:185], v156 offset:50176
	ds_read_b128 v[186:189], v156 offset:51200
	ds_read_b128 v[190:193], v156 offset:52224
	ds_read_b128 v[200:203], v156 offset:53248
	ds_read_b128 v[206:209], v156 offset:54272
	ds_read_b128 v[210:213], v156 offset:55296
	ds_read_b128 v[214:217], v156 offset:56320
	global_load_lds_dwordx4 v150, s[70:71] offset:128
	s_add_i32 m0, s43, 0x1f80
	s_add_u32 s70, s70, 0x80080
	s_nop 0
	s_addc_u32 s71, s71, 0
	s_add_i32 s43, s77, s6
	global_load_lds_dwordx4 v154, s[98:99] offset:128
	s_nop 0
	s_mov_b32 m0, s43
	s_nop 0
	global_load_lds_dwordx4 v150, s[70:71]
	s_nop 0
	s_add_i32 m0, s43, 0x2000
	s_nop 0
	global_load_lds_dwordx4 v154, s[70:71]
	s_nop 0
	s_add_i32 m0, s11, 0xffffff80
	s_nop 0
	global_load_lds_dwordx4 v148, s[100:101] offset:128
	s_nop 0
	s_add_i32 m0, s12, 0xffffff80
	s_nop 0
	global_load_lds_dwordx4 v152, s[100:101] offset:128
	s_waitcnt vmcnt(8)
	s_waitcnt lgkmcnt(0)
	s_setprio 1
	s_barrier
	v_mfma_f32_16x16x32_bf16 v[60:63], v[104:107], v[178:181], v[60:63]
	v_mfma_f32_16x16x32_bf16 v[56:59], v[112:115], v[178:181], v[56:59]
	v_mfma_f32_16x16x32_bf16 v[44:47], v[104:107], v[186:189], v[44:47]
	v_mfma_f32_16x16x32_bf16 v[40:43], v[112:115], v[186:189], v[40:43]
	v_mfma_f32_16x16x32_bf16 v[20:23], v[104:107], v[200:203], v[20:23]
	v_mfma_f32_16x16x32_bf16 v[16:19], v[112:115], v[200:203], v[16:19]
	v_mfma_f32_16x16x32_bf16 v[4:7], v[104:107], v[210:213], v[4:7]
	v_mfma_f32_16x16x32_bf16 v[0:3], v[112:115], v[210:213], v[0:3]
	v_mfma_f32_16x16x32_bf16 v[60:63], v[108:111], v[182:185], v[60:63]
	v_mfma_f32_16x16x32_bf16 v[56:59], v[116:119], v[182:185], v[56:59]
	v_mfma_f32_16x16x32_bf16 v[44:47], v[108:111], v[190:193], v[44:47]
	v_mfma_f32_16x16x32_bf16 v[40:43], v[116:119], v[190:193], v[40:43]
	v_mfma_f32_16x16x32_bf16 v[20:23], v[108:111], v[206:209], v[20:23]
	v_mfma_f32_16x16x32_bf16 v[16:19], v[116:119], v[206:209], v[16:19]
	v_mfma_f32_16x16x32_bf16 v[4:7], v[108:111], v[214:217], v[4:7]
	v_mfma_f32_16x16x32_bf16 v[0:3], v[116:119], v[214:217], v[0:3]
	v_mfma_f32_16x16x32_bf16 v[52:55], v[144:147], v[178:181], v[52:55]
	v_mfma_f32_16x16x32_bf16 v[48:51], v[170:173], v[178:181], v[48:51]
	v_mfma_f32_16x16x32_bf16 v[36:39], v[144:147], v[186:189], v[36:39]
	v_mfma_f32_16x16x32_bf16 v[32:35], v[170:173], v[186:189], v[32:35]
	v_mfma_f32_16x16x32_bf16 v[28:31], v[144:147], v[200:203], v[28:31]
	v_mfma_f32_16x16x32_bf16 v[24:27], v[170:173], v[200:203], v[24:27]
	v_mfma_f32_16x16x32_bf16 v[12:15], v[144:147], v[210:213], v[12:15]
	v_mfma_f32_16x16x32_bf16 v[8:11], v[170:173], v[210:213], v[8:11]
	v_mfma_f32_16x16x32_bf16 v[52:55], v[166:169], v[182:185], v[52:55]
	v_mfma_f32_16x16x32_bf16 v[48:51], v[174:177], v[182:185], v[48:51]
	v_mfma_f32_16x16x32_bf16 v[36:39], v[166:169], v[190:193], v[36:39]
	v_mfma_f32_16x16x32_bf16 v[32:35], v[174:177], v[190:193], v[32:35]
	v_mfma_f32_16x16x32_bf16 v[28:31], v[166:169], v[206:209], v[28:31]
	v_mfma_f32_16x16x32_bf16 v[24:27], v[174:177], v[206:209], v[24:27]
	v_mfma_f32_16x16x32_bf16 v[12:15], v[166:169], v[214:217], v[12:15]
	v_mfma_f32_16x16x32_bf16 v[8:11], v[174:177], v[214:217], v[8:11]
	s_barrier
	s_setprio 0
	s_cmp_gt_u32 s23, 29
	s_cbranch_scc1 .LBB0_2147
	s_mov_b32 s23, s50
	s_branch .LBB0_2133

.LBB0_3142:
	s_or_b32 s40, s31, 1
	s_lshl_b64 s[96:97], s[40:41], 7
	s_add_i32 s40, s31, 2
	s_lshl_b64 vcc, s[40:41], 7
	s_add_u32 s53, s60, vcc_lo
	s_addc_u32 s59, s61, vcc_hi
	s_and_b64 s[70:71], s[68:69], exec
	s_cselect_b32 s71, s59, s55
	s_cselect_b32 s70, s53, s54
	s_add_u32 s53, s62, vcc_lo
	s_addc_u32 s59, s63, vcc_hi
	s_add_i32 s65, 0, 0x10000
	s_and_b64 s[68:69], s[68:69], exec
	s_cselect_b32 s69, s59, s57
	s_cselect_b32 s68, s53, s56
	s_add_i32 s53, 0, 0x14000
	v_add_u32_e32 v140, s65, v169
	v_add_u32_e32 v182, s53, v169
	ds_read_b128 v[128:131], v140
	ds_read_b128 v[132:135], v140 offset:1024
	ds_read_b128 v[136:139], v140 offset:2048
	ds_read_b128 v[140:143], v140 offset:3072
	ds_read_b128 v[160:163], v182
	ds_read_b128 v[174:177], v182 offset:1024
	ds_read_b128 v[178:181], v182 offset:2048
	ds_read_b128 v[182:185], v182 offset:3072
	s_add_u32 s59, s60, s96
	s_addc_u32 s95, s61, s97
	s_add_u32 s96, s59, 0x80000
	s_addc_u32 s97, s95, 0
	s_nop 0
	s_add_i32 m0, s7, 0xc000
	ds_read_b128 v[186:189], v173
	ds_read_b128 v[190:193], v173 offset:1024
	ds_read_b128 v[194:197], v173 offset:2048
	ds_read_b128 v[198:201], v173 offset:3072
	ds_read_b128 v[206:209], v173 offset:4096
	ds_read_b128 v[210:213], v173 offset:5120
	ds_read_b128 v[214:217], v173 offset:6144
	ds_read_b128 v[218:221], v173 offset:7168
	global_load_lds_dwordx4 v152, s[96:97]
	s_nop 0
	s_add_i32 m0, s7, 0xe000
	s_nop 0
	global_load_lds_dwordx4 v154, s[96:97]
	s_waitcnt vmcnt(8)
	s_waitcnt lgkmcnt(0)
	s_setprio 1
	s_barrier
	v_mfma_f32_16x16x32_bf16 v[124:127], v[128:131], v[186:189], v[124:127]
	v_mfma_f32_16x16x32_bf16 v[120:123], v[136:139], v[186:189], v[120:123]
	v_mfma_f32_16x16x32_bf16 v[108:111], v[128:131], v[194:197], v[108:111]
	v_mfma_f32_16x16x32_bf16 v[104:107], v[136:139], v[194:197], v[104:107]
	v_mfma_f32_16x16x32_bf16 v[92:95], v[128:131], v[206:209], v[92:95]
	v_mfma_f32_16x16x32_bf16 v[88:91], v[136:139], v[206:209], v[88:91]
	v_mfma_f32_16x16x32_bf16 v[76:79], v[128:131], v[214:217], v[76:79]
	v_mfma_f32_16x16x32_bf16 v[72:75], v[136:139], v[214:217], v[72:75]
	v_mfma_f32_16x16x32_bf16 v[124:127], v[132:135], v[190:193], v[124:127]
	v_mfma_f32_16x16x32_bf16 v[120:123], v[140:143], v[190:193], v[120:123]
	v_mfma_f32_16x16x32_bf16 v[108:111], v[132:135], v[198:201], v[108:111]
	v_mfma_f32_16x16x32_bf16 v[104:107], v[140:143], v[198:201], v[104:107]
	v_mfma_f32_16x16x32_bf16 v[92:95], v[132:135], v[210:213], v[92:95]
	v_mfma_f32_16x16x32_bf16 v[88:91], v[140:143], v[210:213], v[88:91]
	v_mfma_f32_16x16x32_bf16 v[76:79], v[132:135], v[218:221], v[76:79]
	v_mfma_f32_16x16x32_bf16 v[72:75], v[140:143], v[218:221], v[72:75]
	v_mfma_f32_16x16x32_bf16 v[116:119], v[160:163], v[186:189], v[116:119]
	v_mfma_f32_16x16x32_bf16 v[112:115], v[178:181], v[186:189], v[112:115]
	v_mfma_f32_16x16x32_bf16 v[100:103], v[160:163], v[194:197], v[100:103]
	v_mfma_f32_16x16x32_bf16 v[96:99], v[178:181], v[194:197], v[96:99]
	v_mfma_f32_16x16x32_bf16 v[84:87], v[160:163], v[206:209], v[84:87]
	v_mfma_f32_16x16x32_bf16 v[80:83], v[178:181], v[206:209], v[80:83]
	v_mfma_f32_16x16x32_bf16 v[68:71], v[160:163], v[214:217], v[68:71]
	v_mfma_f32_16x16x32_bf16 v[64:67], v[178:181], v[214:217], v[64:67]
	v_mfma_f32_16x16x32_bf16 v[116:119], v[174:177], v[190:193], v[116:119]
	v_mfma_f32_16x16x32_bf16 v[112:115], v[182:185], v[190:193], v[112:115]
	v_mfma_f32_16x16x32_bf16 v[100:103], v[174:177], v[198:201], v[100:103]
	v_mfma_f32_16x16x32_bf16 v[96:99], v[182:185], v[198:201], v[96:99]
	v_mfma_f32_16x16x32_bf16 v[84:87], v[174:177], v[210:213], v[84:87]
	v_mfma_f32_16x16x32_bf16 v[80:83], v[182:185], v[210:213], v[80:83]
	v_mfma_f32_16x16x32_bf16 v[68:71], v[174:177], v[218:221], v[68:71]
	v_mfma_f32_16x16x32_bf16 v[64:67], v[182:185], v[218:221], v[64:67]
	s_barrier
	s_setprio 0
	s_add_i32 s59, s65, s6
	s_nop 0
	s_mov_b32 m0, s59
	ds_read_b128 v[186:189], v173 offset:16384
	ds_read_b128 v[190:193], v173 offset:17408
	ds_read_b128 v[194:197], v173 offset:18432
	ds_read_b128 v[198:201], v173 offset:19456
	ds_read_b128 v[206:209], v173 offset:20480
	ds_read_b128 v[210:213], v173 offset:21504
	ds_read_b128 v[214:217], v173 offset:22528
	ds_read_b128 v[218:221], v173 offset:23552
	global_load_lds_dwordx4 v144, s[68:69]
	s_add_i32 m0, s59, 0x2000
	s_add_u32 s96, s68, 0x80000
	s_mov_b64 s[98:99], s[68:69]
	s_addc_u32 s97, s69, 0
	s_add_i32 s53, s53, s6
	global_load_lds_dwordx4 v156, s[68:69]
	s_nop 0
	s_mov_b32 m0, s53
	s_mov_b64 s[100:101], s[70:71]
	global_load_lds_dwordx4 v144, s[96:97]
	s_nop 0
	s_add_i32 m0, s53, 0x2000
	s_nop 0
	global_load_lds_dwordx4 v156, s[96:97]
	s_nop 0
	s_mov_b32 m0, s7
	s_nop 0
	global_load_lds_dwordx4 v152, s[70:71]
	s_mov_b32 m0, s8
	s_nop 0
	global_load_lds_dwordx4 v154, s[70:71]
	s_waitcnt vmcnt(8)
	s_waitcnt lgkmcnt(0)
	s_setprio 1
	s_barrier
	v_mfma_f32_16x16x32_bf16 v[60:63], v[128:131], v[186:189], v[60:63]
	v_mfma_f32_16x16x32_bf16 v[56:59], v[136:139], v[186:189], v[56:59]
	v_mfma_f32_16x16x32_bf16 v[44:47], v[128:131], v[194:197], v[44:47]
	v_mfma_f32_16x16x32_bf16 v[40:43], v[136:139], v[194:197], v[40:43]
	v_mfma_f32_16x16x32_bf16 v[24:27], v[128:131], v[206:209], v[24:27]
	v_mfma_f32_16x16x32_bf16 v[16:19], v[136:139], v[206:209], v[16:19]
	v_mfma_f32_16x16x32_bf16 v[4:7], v[128:131], v[214:217], v[4:7]
	v_mfma_f32_16x16x32_bf16 v[0:3], v[136:139], v[214:217], v[0:3]
	v_mfma_f32_16x16x32_bf16 v[60:63], v[132:135], v[190:193], v[60:63]
	v_mfma_f32_16x16x32_bf16 v[56:59], v[140:143], v[190:193], v[56:59]
	v_mfma_f32_16x16x32_bf16 v[44:47], v[132:135], v[198:201], v[44:47]
	v_mfma_f32_16x16x32_bf16 v[40:43], v[140:143], v[198:201], v[40:43]
	v_mfma_f32_16x16x32_bf16 v[24:27], v[132:135], v[210:213], v[24:27]
	v_mfma_f32_16x16x32_bf16 v[16:19], v[140:143], v[210:213], v[16:19]
	v_mfma_f32_16x16x32_bf16 v[4:7], v[132:135], v[218:221], v[4:7]
	v_mfma_f32_16x16x32_bf16 v[0:3], v[140:143], v[218:221], v[0:3]
	v_mfma_f32_16x16x32_bf16 v[52:55], v[160:163], v[186:189], v[52:55]
	v_mfma_f32_16x16x32_bf16 v[48:51], v[178:181], v[186:189], v[48:51]
	v_mfma_f32_16x16x32_bf16 v[28:31], v[160:163], v[194:197], v[28:31]
	v_mfma_f32_16x16x32_bf16 v[20:23], v[178:181], v[194:197], v[20:23]
	v_mfma_f32_16x16x32_bf16 v[32:35], v[160:163], v[206:209], v[32:35]
	v_mfma_f32_16x16x32_bf16 v[36:39], v[178:181], v[206:209], v[36:39]
	v_mfma_f32_16x16x32_bf16 v[8:11], v[160:163], v[214:217], v[8:11]
	v_mfma_f32_16x16x32_bf16 v[12:15], v[178:181], v[214:217], v[12:15]
	v_mfma_f32_16x16x32_bf16 v[52:55], v[174:177], v[190:193], v[52:55]
	v_mfma_f32_16x16x32_bf16 v[48:51], v[182:185], v[190:193], v[48:51]
	v_mfma_f32_16x16x32_bf16 v[28:31], v[174:177], v[198:201], v[28:31]
	v_mfma_f32_16x16x32_bf16 v[20:23], v[182:185], v[198:201], v[20:23]
	v_mfma_f32_16x16x32_bf16 v[32:35], v[174:177], v[210:213], v[32:35]
	v_mfma_f32_16x16x32_bf16 v[36:39], v[182:185], v[210:213], v[36:39]
	v_mfma_f32_16x16x32_bf16 v[8:11], v[174:177], v[218:221], v[8:11]
	v_mfma_f32_16x16x32_bf16 v[12:15], v[182:185], v[218:221], v[12:15]
	s_barrier
	s_setprio 0
	s_add_i32 s53, 0, 0x18000
	s_add_i32 s59, 0, 0x1c000
	v_add_u32_e32 v140, s53, v169
	v_add_u32_e32 v182, s59, v169
	ds_read_b128 v[128:131], v140
	ds_read_b128 v[132:135], v140 offset:1024
	ds_read_b128 v[136:139], v140 offset:2048
	ds_read_b128 v[140:143], v140 offset:3072
	ds_read_b128 v[160:163], v182
	ds_read_b128 v[174:177], v182 offset:1024
	ds_read_b128 v[178:181], v182 offset:2048
	ds_read_b128 v[182:185], v182 offset:3072
	s_add_u32 s70, s70, 0x80000
	s_addc_u32 s71, s71, 0
	s_mov_b32 m0, s9
	s_nop 0
	ds_read_b128 v[186:189], v173 offset:32768
	ds_read_b128 v[190:193], v173 offset:33792
	ds_read_b128 v[194:197], v173 offset:34816
	ds_read_b128 v[198:201], v173 offset:35840
	ds_read_b128 v[206:209], v173 offset:36864
	ds_read_b128 v[210:213], v173 offset:37888
	ds_read_b128 v[214:217], v173 offset:38912
	ds_read_b128 v[218:221], v173 offset:39936
	global_load_lds_dwordx4 v152, s[70:71]
	s_nop 0
	s_mov_b32 m0, s10
	s_nop 0
	global_load_lds_dwordx4 v154, s[70:71]
	s_waitcnt vmcnt(8)
	s_waitcnt lgkmcnt(0)
	s_setprio 1
	s_barrier
	v_mfma_f32_16x16x32_bf16 v[124:127], v[128:131], v[186:189], v[124:127]
	v_mfma_f32_16x16x32_bf16 v[120:123], v[136:139], v[186:189], v[120:123]
	v_mfma_f32_16x16x32_bf16 v[108:111], v[128:131], v[194:197], v[108:111]
	v_mfma_f32_16x16x32_bf16 v[104:107], v[136:139], v[194:197], v[104:107]
	v_mfma_f32_16x16x32_bf16 v[92:95], v[128:131], v[206:209], v[92:95]
	v_mfma_f32_16x16x32_bf16 v[88:91], v[136:139], v[206:209], v[88:91]
	v_mfma_f32_16x16x32_bf16 v[76:79], v[128:131], v[214:217], v[76:79]
	v_mfma_f32_16x16x32_bf16 v[72:75], v[136:139], v[214:217], v[72:75]
	v_mfma_f32_16x16x32_bf16 v[124:127], v[132:135], v[190:193], v[124:127]
	v_mfma_f32_16x16x32_bf16 v[120:123], v[140:143], v[190:193], v[120:123]
	v_mfma_f32_16x16x32_bf16 v[108:111], v[132:135], v[198:201], v[108:111]
	v_mfma_f32_16x16x32_bf16 v[104:107], v[140:143], v[198:201], v[104:107]
	v_mfma_f32_16x16x32_bf16 v[92:95], v[132:135], v[210:213], v[92:95]
	v_mfma_f32_16x16x32_bf16 v[88:91], v[140:143], v[210:213], v[88:91]
	v_mfma_f32_16x16x32_bf16 v[76:79], v[132:135], v[218:221], v[76:79]
	v_mfma_f32_16x16x32_bf16 v[72:75], v[140:143], v[218:221], v[72:75]
	v_mfma_f32_16x16x32_bf16 v[116:119], v[160:163], v[186:189], v[116:119]
	v_mfma_f32_16x16x32_bf16 v[112:115], v[178:181], v[186:189], v[112:115]
	v_mfma_f32_16x16x32_bf16 v[100:103], v[160:163], v[194:197], v[100:103]
	v_mfma_f32_16x16x32_bf16 v[96:99], v[178:181], v[194:197], v[96:99]
	v_mfma_f32_16x16x32_bf16 v[84:87], v[160:163], v[206:209], v[84:87]
	v_mfma_f32_16x16x32_bf16 v[80:83], v[178:181], v[206:209], v[80:83]
	v_mfma_f32_16x16x32_bf16 v[68:71], v[160:163], v[214:217], v[68:71]
	v_mfma_f32_16x16x32_bf16 v[64:67], v[178:181], v[214:217], v[64:67]
	v_mfma_f32_16x16x32_bf16 v[116:119], v[174:177], v[190:193], v[116:119]
	v_mfma_f32_16x16x32_bf16 v[112:115], v[182:185], v[190:193], v[112:115]
	v_mfma_f32_16x16x32_bf16 v[100:103], v[174:177], v[198:201], v[100:103]
	v_mfma_f32_16x16x32_bf16 v[96:99], v[182:185], v[198:201], v[96:99]
	v_mfma_f32_16x16x32_bf16 v[84:87], v[174:177], v[210:213], v[84:87]
	v_mfma_f32_16x16x32_bf16 v[80:83], v[182:185], v[210:213], v[80:83]
	v_mfma_f32_16x16x32_bf16 v[68:71], v[174:177], v[218:221], v[68:71]
	v_mfma_f32_16x16x32_bf16 v[64:67], v[182:185], v[218:221], v[64:67]
	s_barrier
	s_setprio 0
	s_add_i32 s53, s53, s6
	s_nop 0
	s_add_i32 m0, s53, 0xffffff80
	ds_read_b128 v[186:189], v173 offset:49152
	ds_read_b128 v[190:193], v173 offset:50176
	ds_read_b128 v[194:197], v173 offset:51200
	ds_read_b128 v[198:201], v173 offset:52224
	ds_read_b128 v[206:209], v173 offset:53248
	ds_read_b128 v[210:213], v173 offset:54272
	ds_read_b128 v[214:217], v173 offset:55296
	ds_read_b128 v[218:221], v173 offset:56320
	global_load_lds_dwordx4 v144, s[68:69] offset:128
	s_add_i32 m0, s53, 0x1f80
	s_add_u32 s68, s68, 0x80080
	s_nop 0
	s_addc_u32 s69, s69, 0
	s_add_i32 s53, s59, s6
	global_load_lds_dwordx4 v156, s[98:99] offset:128
	s_nop 0
	s_mov_b32 m0, s53
	s_nop 0
	global_load_lds_dwordx4 v144, s[68:69]
	s_nop 0
	s_add_i32 m0, s53, 0x2000
	s_nop 0
	global_load_lds_dwordx4 v156, s[68:69]
	s_nop 0
	s_add_i32 m0, s11, 0xffffff80
	s_nop 0
	global_load_lds_dwordx4 v152, s[100:101] offset:128
	s_nop 0
	s_add_i32 m0, s12, 0xffffff80
	s_nop 0
	global_load_lds_dwordx4 v154, s[100:101] offset:128
	s_waitcnt vmcnt(8)
	s_waitcnt lgkmcnt(0)
	s_setprio 1
	s_barrier
	v_mfma_f32_16x16x32_bf16 v[60:63], v[128:131], v[186:189], v[60:63]
	v_mfma_f32_16x16x32_bf16 v[56:59], v[136:139], v[186:189], v[56:59]
	v_mfma_f32_16x16x32_bf16 v[44:47], v[128:131], v[194:197], v[44:47]
	v_mfma_f32_16x16x32_bf16 v[40:43], v[136:139], v[194:197], v[40:43]
	v_mfma_f32_16x16x32_bf16 v[24:27], v[128:131], v[206:209], v[24:27]
	v_mfma_f32_16x16x32_bf16 v[16:19], v[136:139], v[206:209], v[16:19]
	v_mfma_f32_16x16x32_bf16 v[4:7], v[128:131], v[214:217], v[4:7]
	v_mfma_f32_16x16x32_bf16 v[0:3], v[136:139], v[214:217], v[0:3]
	v_mfma_f32_16x16x32_bf16 v[60:63], v[132:135], v[190:193], v[60:63]
	v_mfma_f32_16x16x32_bf16 v[56:59], v[140:143], v[190:193], v[56:59]
	v_mfma_f32_16x16x32_bf16 v[44:47], v[132:135], v[198:201], v[44:47]
	v_mfma_f32_16x16x32_bf16 v[40:43], v[140:143], v[198:201], v[40:43]
	v_mfma_f32_16x16x32_bf16 v[24:27], v[132:135], v[210:213], v[24:27]
	v_mfma_f32_16x16x32_bf16 v[16:19], v[140:143], v[210:213], v[16:19]
	v_mfma_f32_16x16x32_bf16 v[4:7], v[132:135], v[218:221], v[4:7]
	v_mfma_f32_16x16x32_bf16 v[0:3], v[140:143], v[218:221], v[0:3]
	v_mfma_f32_16x16x32_bf16 v[52:55], v[160:163], v[186:189], v[52:55]
	v_mfma_f32_16x16x32_bf16 v[48:51], v[178:181], v[186:189], v[48:51]
	v_mfma_f32_16x16x32_bf16 v[28:31], v[160:163], v[194:197], v[28:31]
	v_mfma_f32_16x16x32_bf16 v[20:23], v[178:181], v[194:197], v[20:23]
	v_mfma_f32_16x16x32_bf16 v[32:35], v[160:163], v[206:209], v[32:35]
	v_mfma_f32_16x16x32_bf16 v[36:39], v[178:181], v[206:209], v[36:39]
	v_mfma_f32_16x16x32_bf16 v[8:11], v[160:163], v[214:217], v[8:11]
	v_mfma_f32_16x16x32_bf16 v[12:15], v[178:181], v[214:217], v[12:15]
	v_mfma_f32_16x16x32_bf16 v[52:55], v[174:177], v[190:193], v[52:55]
	v_mfma_f32_16x16x32_bf16 v[48:51], v[182:185], v[190:193], v[48:51]
	v_mfma_f32_16x16x32_bf16 v[28:31], v[174:177], v[198:201], v[28:31]
	v_mfma_f32_16x16x32_bf16 v[20:23], v[182:185], v[198:201], v[20:23]
	v_mfma_f32_16x16x32_bf16 v[32:35], v[174:177], v[210:213], v[32:35]
	v_mfma_f32_16x16x32_bf16 v[36:39], v[182:185], v[210:213], v[36:39]
	v_mfma_f32_16x16x32_bf16 v[8:11], v[174:177], v[218:221], v[8:11]
	v_mfma_f32_16x16x32_bf16 v[12:15], v[182:185], v[218:221], v[12:15]
	s_barrier
	s_setprio 0
	s_cmp_gt_u32 s31, 29
	s_cbranch_scc1 .LBB0_3144
	s_mov_b32 s31, s40
	s_branch .LBB0_3130

.LBB0_3613:
	s_add_i32 s70, s26, 2
	s_add_u32 s71, s22, 0x80
	s_addc_u32 s27, s23, 0
	s_add_i32 s95, 0, 0x10000
	s_cmp_eq_u32 s67, s26
	s_cselect_b32 s27, s40, s27
	s_cselect_b32 s26, s53, s71
	v_add_u32_e32 v155, s95, v143
	s_cselect_b32 s97, s58, s69
	s_cselect_b32 s96, s59, s68
	s_add_i32 s71, 0, 0x14000
	ds_read_b128 v[138:141], v155
	ds_read_b128 v[156:159], v155 offset:1024
	ds_read_b128 v[160:163], v155 offset:2048
	ds_read_b128 v[168:171], v155 offset:3072
	v_add_u32_e32 v155, s71, v143
	ds_read_b128 v[172:175], v155
	ds_read_b128 v[176:179], v155 offset:1024
	ds_read_b128 v[180:183], v155 offset:2048
	ds_read_b128 v[184:187], v155 offset:3072
	s_nop 0
	s_add_i32 m0, s12, 0xc000
	ds_read_b128 v[188:191], v154
	ds_read_b128 v[192:195], v154 offset:1024
	ds_read_b128 v[196:199], v154 offset:2048
	ds_read_b128 v[200:203], v154 offset:3072
	ds_read_b128 v[206:209], v154 offset:4096
	ds_read_b128 v[210:213], v154 offset:5120
	ds_read_b128 v[214:217], v154 offset:6144
	ds_read_b128 v[218:221], v154 offset:7168
	global_load_lds_dwordx4 v136, s[22:23]
	s_nop 0
	s_add_i32 m0, s12, 0xe000
	s_nop 0
	global_load_lds_dwordx4 v134, s[22:23]
	s_waitcnt vmcnt(8)
	s_waitcnt lgkmcnt(0)
	s_setprio 1
	s_barrier
	v_mfma_f32_16x16x32_bf16 v[124:127], v[138:141], v[188:191], v[124:127]
	v_mfma_f32_16x16x32_bf16 v[120:123], v[160:163], v[188:191], v[120:123]
	v_mfma_f32_16x16x32_bf16 v[108:111], v[138:141], v[196:199], v[108:111]
	v_mfma_f32_16x16x32_bf16 v[104:107], v[160:163], v[196:199], v[104:107]
	v_mfma_f32_16x16x32_bf16 v[92:95], v[138:141], v[206:209], v[92:95]
	v_mfma_f32_16x16x32_bf16 v[88:91], v[160:163], v[206:209], v[88:91]
	v_mfma_f32_16x16x32_bf16 v[76:79], v[138:141], v[214:217], v[76:79]
	v_mfma_f32_16x16x32_bf16 v[72:75], v[160:163], v[214:217], v[72:75]
	v_mfma_f32_16x16x32_bf16 v[124:127], v[156:159], v[192:195], v[124:127]
	v_mfma_f32_16x16x32_bf16 v[120:123], v[168:171], v[192:195], v[120:123]
	v_mfma_f32_16x16x32_bf16 v[108:111], v[156:159], v[200:203], v[108:111]
	v_mfma_f32_16x16x32_bf16 v[104:107], v[168:171], v[200:203], v[104:107]
	v_mfma_f32_16x16x32_bf16 v[92:95], v[156:159], v[210:213], v[92:95]
	v_mfma_f32_16x16x32_bf16 v[88:91], v[168:171], v[210:213], v[88:91]
	v_mfma_f32_16x16x32_bf16 v[76:79], v[156:159], v[218:221], v[76:79]
	v_mfma_f32_16x16x32_bf16 v[72:75], v[168:171], v[218:221], v[72:75]
	v_mfma_f32_16x16x32_bf16 v[116:119], v[172:175], v[188:191], v[116:119]
	v_mfma_f32_16x16x32_bf16 v[112:115], v[180:183], v[188:191], v[112:115]
	v_mfma_f32_16x16x32_bf16 v[100:103], v[172:175], v[196:199], v[100:103]
	v_mfma_f32_16x16x32_bf16 v[96:99], v[180:183], v[196:199], v[96:99]
	v_mfma_f32_16x16x32_bf16 v[84:87], v[172:175], v[206:209], v[84:87]
	v_mfma_f32_16x16x32_bf16 v[80:83], v[180:183], v[206:209], v[80:83]
	v_mfma_f32_16x16x32_bf16 v[68:71], v[172:175], v[214:217], v[68:71]
	v_mfma_f32_16x16x32_bf16 v[64:67], v[180:183], v[214:217], v[64:67]
	v_mfma_f32_16x16x32_bf16 v[116:119], v[176:179], v[192:195], v[116:119]
	v_mfma_f32_16x16x32_bf16 v[112:115], v[184:187], v[192:195], v[112:115]
	v_mfma_f32_16x16x32_bf16 v[100:103], v[176:179], v[200:203], v[100:103]
	v_mfma_f32_16x16x32_bf16 v[96:99], v[184:187], v[200:203], v[96:99]
	v_mfma_f32_16x16x32_bf16 v[84:87], v[176:179], v[210:213], v[84:87]
	v_mfma_f32_16x16x32_bf16 v[80:83], v[184:187], v[210:213], v[80:83]
	v_mfma_f32_16x16x32_bf16 v[68:71], v[176:179], v[218:221], v[68:71]
	v_mfma_f32_16x16x32_bf16 v[64:67], v[184:187], v[218:221], v[64:67]
	s_barrier
	s_setprio 0
	s_add_i32 s95, s95, s11
	s_mov_b64 s[98:99], s[96:97]
	s_mov_b32 m0, s95
	ds_read_b128 v[188:191], v154 offset:16384
	ds_read_b128 v[192:195], v154 offset:17408
	ds_read_b128 v[196:199], v154 offset:18432
	ds_read_b128 v[200:203], v154 offset:19456
	ds_read_b128 v[206:209], v154 offset:20480
	ds_read_b128 v[210:213], v154 offset:21504
	ds_read_b128 v[214:217], v154 offset:22528
	ds_read_b128 v[218:221], v154 offset:23552
	global_load_lds_dwordx4 v144, s[96:97]
	s_add_i32 m0, s95, 0x2000
	s_nop 0
	s_add_u32 s96, s96, s20
	s_addc_u32 s97, s97, 0
	s_add_i32 s71, s71, s11
	global_load_lds_dwordx4 v132, s[98:99]
	s_nop 0
	s_mov_b32 m0, s71
	s_nop 0
	global_load_lds_dwordx4 v144, s[96:97]
	s_add_i32 m0, s71, 0x2000
	s_mov_b64 s[100:101], s[26:27]
	global_load_lds_dwordx4 v132, s[96:97]
	s_mov_b32 m0, s12
	s_nop 0
	global_load_lds_dwordx4 v128, s[26:27]
	s_mov_b32 m0, s13
	s_nop 0
	global_load_lds_dwordx4 v130, s[26:27]
	s_waitcnt vmcnt(8)
	s_waitcnt lgkmcnt(0)
	s_setprio 1
	s_barrier
	v_mfma_f32_16x16x32_bf16 v[60:63], v[138:141], v[188:191], v[60:63]
	v_mfma_f32_16x16x32_bf16 v[56:59], v[160:163], v[188:191], v[56:59]
	v_mfma_f32_16x16x32_bf16 v[44:47], v[138:141], v[196:199], v[44:47]
	v_mfma_f32_16x16x32_bf16 v[40:43], v[160:163], v[196:199], v[40:43]
	v_mfma_f32_16x16x32_bf16 v[28:31], v[138:141], v[206:209], v[28:31]
	v_mfma_f32_16x16x32_bf16 v[24:27], v[160:163], v[206:209], v[24:27]
	v_mfma_f32_16x16x32_bf16 v[12:15], v[138:141], v[214:217], v[12:15]
	v_mfma_f32_16x16x32_bf16 v[8:11], v[160:163], v[214:217], v[8:11]
	v_mfma_f32_16x16x32_bf16 v[60:63], v[156:159], v[192:195], v[60:63]
	v_mfma_f32_16x16x32_bf16 v[56:59], v[168:171], v[192:195], v[56:59]
	v_mfma_f32_16x16x32_bf16 v[44:47], v[156:159], v[200:203], v[44:47]
	v_mfma_f32_16x16x32_bf16 v[40:43], v[168:171], v[200:203], v[40:43]
	v_mfma_f32_16x16x32_bf16 v[28:31], v[156:159], v[210:213], v[28:31]
	v_mfma_f32_16x16x32_bf16 v[24:27], v[168:171], v[210:213], v[24:27]
	v_mfma_f32_16x16x32_bf16 v[12:15], v[156:159], v[218:221], v[12:15]
	v_mfma_f32_16x16x32_bf16 v[8:11], v[168:171], v[218:221], v[8:11]
	v_mfma_f32_16x16x32_bf16 v[52:55], v[172:175], v[188:191], v[52:55]
	v_mfma_f32_16x16x32_bf16 v[48:51], v[180:183], v[188:191], v[48:51]
	v_mfma_f32_16x16x32_bf16 v[36:39], v[172:175], v[196:199], v[36:39]
	v_mfma_f32_16x16x32_bf16 v[32:35], v[180:183], v[196:199], v[32:35]
	v_mfma_f32_16x16x32_bf16 v[20:23], v[172:175], v[206:209], v[20:23]
	v_mfma_f32_16x16x32_bf16 v[16:19], v[180:183], v[206:209], v[16:19]
	v_mfma_f32_16x16x32_bf16 v[4:7], v[172:175], v[214:217], v[4:7]
	v_mfma_f32_16x16x32_bf16 v[0:3], v[180:183], v[214:217], v[0:3]
	v_mfma_f32_16x16x32_bf16 v[52:55], v[176:179], v[192:195], v[52:55]
	v_mfma_f32_16x16x32_bf16 v[48:51], v[184:187], v[192:195], v[48:51]
	v_mfma_f32_16x16x32_bf16 v[36:39], v[176:179], v[200:203], v[36:39]
	v_mfma_f32_16x16x32_bf16 v[32:35], v[184:187], v[200:203], v[32:35]
	v_mfma_f32_16x16x32_bf16 v[20:23], v[176:179], v[210:213], v[20:23]
	v_mfma_f32_16x16x32_bf16 v[16:19], v[184:187], v[210:213], v[16:19]
	v_mfma_f32_16x16x32_bf16 v[4:7], v[176:179], v[218:221], v[4:7]
	v_mfma_f32_16x16x32_bf16 v[0:3], v[184:187], v[218:221], v[0:3]
	s_barrier
	s_setprio 0
	s_add_i32 s71, 0, 0x18000
	v_add_u32_e32 v155, s71, v143
	s_add_i32 s95, 0, 0x1c000
	ds_read_b128 v[138:141], v155
	ds_read_b128 v[156:159], v155 offset:1024
	ds_read_b128 v[160:163], v155 offset:2048
	ds_read_b128 v[168:171], v155 offset:3072
	v_add_u32_e32 v155, s95, v143
	ds_read_b128 v[172:175], v155
	ds_read_b128 v[176:179], v155 offset:1024
	ds_read_b128 v[180:183], v155 offset:2048
	ds_read_b128 v[184:187], v155 offset:3072
	s_add_u32 s26, s26, s20
	s_addc_u32 s27, s27, 0
	s_mov_b32 m0, s28
	s_nop 0
	ds_read_b128 v[188:191], v154 offset:32768
	ds_read_b128 v[192:195], v154 offset:33792
	ds_read_b128 v[196:199], v154 offset:34816
	ds_read_b128 v[200:203], v154 offset:35840
	ds_read_b128 v[206:209], v154 offset:36864
	ds_read_b128 v[210:213], v154 offset:37888
	ds_read_b128 v[214:217], v154 offset:38912
	ds_read_b128 v[218:221], v154 offset:39936
	global_load_lds_dwordx4 v128, s[26:27]
	s_nop 0
	s_mov_b32 m0, s29
	s_nop 0
	global_load_lds_dwordx4 v130, s[26:27]
	s_waitcnt vmcnt(8)
	s_waitcnt lgkmcnt(0)
	s_setprio 1
	s_barrier
	v_mfma_f32_16x16x32_bf16 v[124:127], v[138:141], v[188:191], v[124:127]
	v_mfma_f32_16x16x32_bf16 v[120:123], v[160:163], v[188:191], v[120:123]
	v_mfma_f32_16x16x32_bf16 v[108:111], v[138:141], v[196:199], v[108:111]
	v_mfma_f32_16x16x32_bf16 v[104:107], v[160:163], v[196:199], v[104:107]
	v_mfma_f32_16x16x32_bf16 v[92:95], v[138:141], v[206:209], v[92:95]
	v_mfma_f32_16x16x32_bf16 v[88:91], v[160:163], v[206:209], v[88:91]
	v_mfma_f32_16x16x32_bf16 v[76:79], v[138:141], v[214:217], v[76:79]
	v_mfma_f32_16x16x32_bf16 v[72:75], v[160:163], v[214:217], v[72:75]
	v_mfma_f32_16x16x32_bf16 v[124:127], v[156:159], v[192:195], v[124:127]
	v_mfma_f32_16x16x32_bf16 v[120:123], v[168:171], v[192:195], v[120:123]
	v_mfma_f32_16x16x32_bf16 v[108:111], v[156:159], v[200:203], v[108:111]
	v_mfma_f32_16x16x32_bf16 v[104:107], v[168:171], v[200:203], v[104:107]
	v_mfma_f32_16x16x32_bf16 v[92:95], v[156:159], v[210:213], v[92:95]
	v_mfma_f32_16x16x32_bf16 v[88:91], v[168:171], v[210:213], v[88:91]
	v_mfma_f32_16x16x32_bf16 v[76:79], v[156:159], v[218:221], v[76:79]
	v_mfma_f32_16x16x32_bf16 v[72:75], v[168:171], v[218:221], v[72:75]
	v_mfma_f32_16x16x32_bf16 v[116:119], v[172:175], v[188:191], v[116:119]
	v_mfma_f32_16x16x32_bf16 v[112:115], v[180:183], v[188:191], v[112:115]
	v_mfma_f32_16x16x32_bf16 v[100:103], v[172:175], v[196:199], v[100:103]
	v_mfma_f32_16x16x32_bf16 v[96:99], v[180:183], v[196:199], v[96:99]
	v_mfma_f32_16x16x32_bf16 v[84:87], v[172:175], v[206:209], v[84:87]
	v_mfma_f32_16x16x32_bf16 v[80:83], v[180:183], v[206:209], v[80:83]
	v_mfma_f32_16x16x32_bf16 v[68:71], v[172:175], v[214:217], v[68:71]
	v_mfma_f32_16x16x32_bf16 v[64:67], v[180:183], v[214:217], v[64:67]
	v_mfma_f32_16x16x32_bf16 v[116:119], v[176:179], v[192:195], v[116:119]
	v_mfma_f32_16x16x32_bf16 v[112:115], v[184:187], v[192:195], v[112:115]
	v_mfma_f32_16x16x32_bf16 v[100:103], v[176:179], v[200:203], v[100:103]
	v_mfma_f32_16x16x32_bf16 v[96:99], v[184:187], v[200:203], v[96:99]
	v_mfma_f32_16x16x32_bf16 v[84:87], v[176:179], v[210:213], v[84:87]
	v_mfma_f32_16x16x32_bf16 v[80:83], v[184:187], v[210:213], v[80:83]
	v_mfma_f32_16x16x32_bf16 v[68:71], v[176:179], v[218:221], v[68:71]
	v_mfma_f32_16x16x32_bf16 v[64:67], v[184:187], v[218:221], v[64:67]
	s_barrier
	s_setprio 0
	s_add_i32 s26, s71, s11
	s_nop 0
	s_add_i32 m0, s26, 0xffffff80
	ds_read_b128 v[188:191], v154 offset:49152
	ds_read_b128 v[192:195], v154 offset:50176
	ds_read_b128 v[196:199], v154 offset:51200
	ds_read_b128 v[200:203], v154 offset:52224
	ds_read_b128 v[206:209], v154 offset:53248
	ds_read_b128 v[210:213], v154 offset:54272
	ds_read_b128 v[214:217], v154 offset:55296
	ds_read_b128 v[218:221], v154 offset:56320
	global_load_lds_dwordx4 v144, s[98:99] offset:128
	s_nop 0
	s_add_i32 m0, s26, 0x1f80
	s_add_i32 s26, s95, s11
	global_load_lds_dwordx4 v132, s[98:99] offset:128
	s_nop 0
	s_add_i32 m0, s26, 0xffffff80
	s_nop 0
	global_load_lds_dwordx4 v144, s[96:97] offset:128
	s_nop 0
	s_add_i32 m0, s26, 0x1f80
	s_nop 0
	global_load_lds_dwordx4 v132, s[96:97] offset:128
	s_nop 0
	s_add_i32 m0, s62, 0xffffff80
	s_nop 0
	global_load_lds_dwordx4 v128, s[100:101] offset:128
	s_nop 0
	s_add_i32 m0, s63, 0xffffff80
	s_nop 0
	global_load_lds_dwordx4 v130, s[100:101] offset:128
	s_waitcnt vmcnt(8)
	s_waitcnt lgkmcnt(0)
	s_setprio 1
	s_barrier
	v_mfma_f32_16x16x32_bf16 v[60:63], v[138:141], v[188:191], v[60:63]
	v_mfma_f32_16x16x32_bf16 v[56:59], v[160:163], v[188:191], v[56:59]
	v_mfma_f32_16x16x32_bf16 v[44:47], v[138:141], v[196:199], v[44:47]
	v_mfma_f32_16x16x32_bf16 v[40:43], v[160:163], v[196:199], v[40:43]
	v_mfma_f32_16x16x32_bf16 v[28:31], v[138:141], v[206:209], v[28:31]
	v_mfma_f32_16x16x32_bf16 v[24:27], v[160:163], v[206:209], v[24:27]
	v_mfma_f32_16x16x32_bf16 v[12:15], v[138:141], v[214:217], v[12:15]
	v_mfma_f32_16x16x32_bf16 v[8:11], v[160:163], v[214:217], v[8:11]
	v_mfma_f32_16x16x32_bf16 v[60:63], v[156:159], v[192:195], v[60:63]
	v_mfma_f32_16x16x32_bf16 v[56:59], v[168:171], v[192:195], v[56:59]
	v_mfma_f32_16x16x32_bf16 v[44:47], v[156:159], v[200:203], v[44:47]
	v_mfma_f32_16x16x32_bf16 v[40:43], v[168:171], v[200:203], v[40:43]
	v_mfma_f32_16x16x32_bf16 v[28:31], v[156:159], v[210:213], v[28:31]
	v_mfma_f32_16x16x32_bf16 v[24:27], v[168:171], v[210:213], v[24:27]
	v_mfma_f32_16x16x32_bf16 v[12:15], v[156:159], v[218:221], v[12:15]
	v_mfma_f32_16x16x32_bf16 v[8:11], v[168:171], v[218:221], v[8:11]
	v_mfma_f32_16x16x32_bf16 v[52:55], v[172:175], v[188:191], v[52:55]
	v_mfma_f32_16x16x32_bf16 v[48:51], v[180:183], v[188:191], v[48:51]
	v_mfma_f32_16x16x32_bf16 v[36:39], v[172:175], v[196:199], v[36:39]
	v_mfma_f32_16x16x32_bf16 v[32:35], v[180:183], v[196:199], v[32:35]
	v_mfma_f32_16x16x32_bf16 v[20:23], v[172:175], v[206:209], v[20:23]
	v_mfma_f32_16x16x32_bf16 v[16:19], v[180:183], v[206:209], v[16:19]
	v_mfma_f32_16x16x32_bf16 v[4:7], v[172:175], v[214:217], v[4:7]
	v_mfma_f32_16x16x32_bf16 v[0:3], v[180:183], v[214:217], v[0:3]
	v_mfma_f32_16x16x32_bf16 v[52:55], v[176:179], v[192:195], v[52:55]
	v_mfma_f32_16x16x32_bf16 v[48:51], v[184:187], v[192:195], v[48:51]
	v_mfma_f32_16x16x32_bf16 v[36:39], v[176:179], v[200:203], v[36:39]
	v_mfma_f32_16x16x32_bf16 v[32:35], v[184:187], v[200:203], v[32:35]
	v_mfma_f32_16x16x32_bf16 v[20:23], v[176:179], v[210:213], v[20:23]
	v_mfma_f32_16x16x32_bf16 v[16:19], v[184:187], v[210:213], v[16:19]
	v_mfma_f32_16x16x32_bf16 v[4:7], v[176:179], v[218:221], v[4:7]
	v_mfma_f32_16x16x32_bf16 v[0:3], v[184:187], v[218:221], v[0:3]
	s_barrier
	s_setprio 0
	s_add_u32 s68, s68, 0x100
	s_addc_u32 s69, s69, 0
	s_add_u32 s22, s22, 0x100
	s_addc_u32 s23, s23, 0
	s_cmp_ge_i32 s70, s1
	s_mov_b32 s26, s70
	s_cbranch_scc0 .LBB0_3613
	s_and_b64 vcc, exec, s[46:47]
	s_cbranch_vccz .LBB0_3616
	s_barrier

.LBB0_3760:
	s_or_b32 s40, s63, 1
	s_lshl_b64 s[80:81], s[40:41], 7
	s_add_i32 s40, s63, 2
	s_lshl_b64 s[82:83], s[40:41], 7
	v_add_u32_e32 v140, s30, v177
	v_add_u32_e32 v180, s31, v177
	s_add_u32 s79, s58, s82
	ds_read_b128 v[128:131], v140
	ds_read_b128 v[132:135], v140 offset:1024
	ds_read_b128 v[136:139], v140 offset:2048
	ds_read_b128 v[140:143], v140 offset:3072
	ds_read_b128 v[162:165], v180
	ds_read_b128 v[166:169], v180 offset:1024
	ds_read_b128 v[170:173], v180 offset:2048
	ds_read_b128 v[180:183], v180 offset:3072
	s_addc_u32 s84, s59, s83
	s_and_b64 s[70:71], s[68:69], exec
	s_cselect_b32 s71, s84, s51
	s_cselect_b32 s70, s79, s50
	s_add_u32 s79, s60, s82
	s_addc_u32 s82, s61, s83
	s_and_b64 s[68:69], s[68:69], exec
	s_cselect_b32 s69, s82, s53
	s_cselect_b32 s68, s79, s52
	s_add_u32 s79, s58, s80
	s_addc_u32 s81, s59, s81
	s_add_u32 s80, s79, 0x80000
	s_addc_u32 s81, s81, 0
	s_nop 0
	s_add_i32 m0, s7, 0xc000
	ds_read_b128 v[184:187], v152
	ds_read_b128 v[188:191], v152 offset:1024
	ds_read_b128 v[192:195], v152 offset:2048
	ds_read_b128 v[196:199], v152 offset:3072
	ds_read_b128 v[200:203], v152 offset:4096
	ds_read_b128 v[206:209], v152 offset:5120
	ds_read_b128 v[210:213], v152 offset:6144
	ds_read_b128 v[214:217], v152 offset:7168
	global_load_lds_dwordx4 v144, s[80:81]
	s_nop 0
	s_add_i32 m0, s7, 0xe000
	s_nop 0
	global_load_lds_dwordx4 v148, s[80:81]
	s_waitcnt vmcnt(8)
	s_waitcnt lgkmcnt(0)
	s_setprio 1
	s_barrier
	v_mfma_f32_16x16x32_bf16 v[124:127], v[128:131], v[184:187], v[124:127]
	v_mfma_f32_16x16x32_bf16 v[120:123], v[136:139], v[184:187], v[120:123]
	v_mfma_f32_16x16x32_bf16 v[112:115], v[128:131], v[192:195], v[112:115]
	v_mfma_f32_16x16x32_bf16 v[104:107], v[136:139], v[192:195], v[104:107]
	v_mfma_f32_16x16x32_bf16 v[96:99], v[128:131], v[200:203], v[96:99]
	v_mfma_f32_16x16x32_bf16 v[88:91], v[136:139], v[200:203], v[88:91]
	v_mfma_f32_16x16x32_bf16 v[80:83], v[128:131], v[210:213], v[80:83]
	v_mfma_f32_16x16x32_bf16 v[72:75], v[136:139], v[210:213], v[72:75]
	v_mfma_f32_16x16x32_bf16 v[124:127], v[132:135], v[188:191], v[124:127]
	v_mfma_f32_16x16x32_bf16 v[120:123], v[140:143], v[188:191], v[120:123]
	v_mfma_f32_16x16x32_bf16 v[112:115], v[132:135], v[196:199], v[112:115]
	v_mfma_f32_16x16x32_bf16 v[104:107], v[140:143], v[196:199], v[104:107]
	v_mfma_f32_16x16x32_bf16 v[96:99], v[132:135], v[206:209], v[96:99]
	v_mfma_f32_16x16x32_bf16 v[88:91], v[140:143], v[206:209], v[88:91]
	v_mfma_f32_16x16x32_bf16 v[80:83], v[132:135], v[214:217], v[80:83]
	v_mfma_f32_16x16x32_bf16 v[72:75], v[140:143], v[214:217], v[72:75]
	v_mfma_f32_16x16x32_bf16 v[116:119], v[162:165], v[184:187], v[116:119]
	v_mfma_f32_16x16x32_bf16 v[108:111], v[170:173], v[184:187], v[108:111]
	v_mfma_f32_16x16x32_bf16 v[100:103], v[162:165], v[192:195], v[100:103]
	v_mfma_f32_16x16x32_bf16 v[92:95], v[170:173], v[192:195], v[92:95]
	v_mfma_f32_16x16x32_bf16 v[84:87], v[162:165], v[200:203], v[84:87]
	v_mfma_f32_16x16x32_bf16 v[76:79], v[170:173], v[200:203], v[76:79]
	v_mfma_f32_16x16x32_bf16 v[68:71], v[162:165], v[210:213], v[68:71]
	v_mfma_f32_16x16x32_bf16 v[64:67], v[170:173], v[210:213], v[64:67]
	v_mfma_f32_16x16x32_bf16 v[116:119], v[166:169], v[188:191], v[116:119]
	v_mfma_f32_16x16x32_bf16 v[108:111], v[180:183], v[188:191], v[108:111]
	v_mfma_f32_16x16x32_bf16 v[100:103], v[166:169], v[196:199], v[100:103]
	v_mfma_f32_16x16x32_bf16 v[92:95], v[180:183], v[196:199], v[92:95]
	v_mfma_f32_16x16x32_bf16 v[84:87], v[166:169], v[206:209], v[84:87]
	v_mfma_f32_16x16x32_bf16 v[76:79], v[180:183], v[206:209], v[76:79]
	v_mfma_f32_16x16x32_bf16 v[68:71], v[166:169], v[214:217], v[68:71]
	v_mfma_f32_16x16x32_bf16 v[64:67], v[180:183], v[214:217], v[64:67]
	s_barrier
	s_setprio 0
	s_add_i32 s79, s30, s6
	s_nop 0
	s_mov_b32 m0, s79
	ds_read_b128 v[184:187], v152 offset:16384
	ds_read_b128 v[188:191], v152 offset:17408
	ds_read_b128 v[192:195], v152 offset:18432
	ds_read_b128 v[196:199], v152 offset:19456
	ds_read_b128 v[200:203], v152 offset:20480
	ds_read_b128 v[206:209], v152 offset:21504
	ds_read_b128 v[210:213], v152 offset:22528
	ds_read_b128 v[214:217], v152 offset:23552
	global_load_lds_dwordx4 v146, s[68:69]
	s_add_i32 m0, s79, 0x2000
	s_add_u32 s80, s68, 0x80000
	s_mov_b64 s[98:99], s[68:69]
	s_addc_u32 s81, s69, 0
	s_add_i32 s79, s31, s6
	global_load_lds_dwordx4 v150, s[68:69]
	s_nop 0
	s_mov_b32 m0, s79
	s_mov_b64 s[100:101], s[70:71]
	global_load_lds_dwordx4 v146, s[80:81]
	s_nop 0
	s_add_i32 m0, s79, 0x2000
	s_nop 0
	global_load_lds_dwordx4 v150, s[80:81]
	s_nop 0
	s_mov_b32 m0, s7
	s_nop 0
	global_load_lds_dwordx4 v144, s[70:71]
	s_mov_b32 m0, s8
	s_nop 0
	global_load_lds_dwordx4 v148, s[70:71]
	s_waitcnt vmcnt(8)
	s_waitcnt lgkmcnt(0)
	s_setprio 1
	s_barrier
	v_mfma_f32_16x16x32_bf16 v[60:63], v[128:131], v[184:187], v[60:63]
	v_mfma_f32_16x16x32_bf16 v[56:59], v[136:139], v[184:187], v[56:59]
	v_mfma_f32_16x16x32_bf16 v[48:51], v[128:131], v[192:195], v[48:51]
	v_mfma_f32_16x16x32_bf16 v[32:35], v[136:139], v[192:195], v[32:35]
	v_mfma_f32_16x16x32_bf16 v[16:19], v[128:131], v[200:203], v[16:19]
	v_mfma_f32_16x16x32_bf16 v[12:15], v[136:139], v[200:203], v[12:15]
	v_mfma_f32_16x16x32_bf16 v[4:7], v[128:131], v[210:213], v[4:7]
	v_mfma_f32_16x16x32_bf16 v[0:3], v[136:139], v[210:213], v[0:3]
	v_mfma_f32_16x16x32_bf16 v[60:63], v[132:135], v[188:191], v[60:63]
	v_mfma_f32_16x16x32_bf16 v[56:59], v[140:143], v[188:191], v[56:59]
	v_mfma_f32_16x16x32_bf16 v[48:51], v[132:135], v[196:199], v[48:51]
	v_mfma_f32_16x16x32_bf16 v[32:35], v[140:143], v[196:199], v[32:35]
	v_mfma_f32_16x16x32_bf16 v[16:19], v[132:135], v[206:209], v[16:19]
	v_mfma_f32_16x16x32_bf16 v[12:15], v[140:143], v[206:209], v[12:15]
	v_mfma_f32_16x16x32_bf16 v[4:7], v[132:135], v[214:217], v[4:7]
	v_mfma_f32_16x16x32_bf16 v[0:3], v[140:143], v[214:217], v[0:3]
	v_mfma_f32_16x16x32_bf16 v[52:55], v[162:165], v[184:187], v[52:55]
	v_mfma_f32_16x16x32_bf16 v[36:39], v[170:173], v[184:187], v[36:39]
	v_mfma_f32_16x16x32_bf16 v[20:23], v[162:165], v[192:195], v[20:23]
	v_mfma_f32_16x16x32_bf16 v[8:11], v[170:173], v[192:195], v[8:11]
	v_mfma_f32_16x16x32_bf16 v[40:43], v[162:165], v[200:203], v[40:43]
	v_mfma_f32_16x16x32_bf16 v[44:47], v[170:173], v[200:203], v[44:47]
	v_mfma_f32_16x16x32_bf16 v[24:27], v[162:165], v[210:213], v[24:27]
	v_mfma_f32_16x16x32_bf16 v[28:31], v[170:173], v[210:213], v[28:31]
	v_mfma_f32_16x16x32_bf16 v[52:55], v[166:169], v[188:191], v[52:55]
	v_mfma_f32_16x16x32_bf16 v[36:39], v[180:183], v[188:191], v[36:39]
	v_mfma_f32_16x16x32_bf16 v[20:23], v[166:169], v[196:199], v[20:23]
	v_mfma_f32_16x16x32_bf16 v[8:11], v[180:183], v[196:199], v[8:11]
	v_mfma_f32_16x16x32_bf16 v[40:43], v[166:169], v[206:209], v[40:43]
	v_mfma_f32_16x16x32_bf16 v[44:47], v[180:183], v[206:209], v[44:47]
	v_mfma_f32_16x16x32_bf16 v[24:27], v[166:169], v[214:217], v[24:27]
	v_mfma_f32_16x16x32_bf16 v[28:31], v[180:183], v[214:217], v[28:31]
	s_barrier
	s_setprio 0
	v_add_u32_e32 v140, s55, v177
	v_add_u32_e32 v180, s57, v177
	ds_read_b128 v[128:131], v140
	ds_read_b128 v[132:135], v140 offset:1024
	ds_read_b128 v[136:139], v140 offset:2048
	ds_read_b128 v[140:143], v140 offset:3072
	ds_read_b128 v[162:165], v180
	ds_read_b128 v[166:169], v180 offset:1024
	ds_read_b128 v[170:173], v180 offset:2048
	ds_read_b128 v[180:183], v180 offset:3072
	s_add_u32 s70, s70, 0x80000
	s_addc_u32 s71, s71, 0
	s_mov_b32 m0, s9
	s_nop 0
	ds_read_b128 v[184:187], v152 offset:32768
	ds_read_b128 v[188:191], v152 offset:33792
	ds_read_b128 v[192:195], v152 offset:34816
	ds_read_b128 v[196:199], v152 offset:35840
	ds_read_b128 v[200:203], v152 offset:36864
	ds_read_b128 v[206:209], v152 offset:37888
	ds_read_b128 v[210:213], v152 offset:38912
	ds_read_b128 v[214:217], v152 offset:39936
	global_load_lds_dwordx4 v144, s[70:71]
	s_nop 0
	s_mov_b32 m0, s10
	s_nop 0
	global_load_lds_dwordx4 v148, s[70:71]
	s_waitcnt vmcnt(8)
	s_waitcnt lgkmcnt(0)
	s_setprio 1
	s_barrier
	v_mfma_f32_16x16x32_bf16 v[124:127], v[128:131], v[184:187], v[124:127]
	v_mfma_f32_16x16x32_bf16 v[120:123], v[136:139], v[184:187], v[120:123]
	v_mfma_f32_16x16x32_bf16 v[112:115], v[128:131], v[192:195], v[112:115]
	v_mfma_f32_16x16x32_bf16 v[104:107], v[136:139], v[192:195], v[104:107]
	v_mfma_f32_16x16x32_bf16 v[96:99], v[128:131], v[200:203], v[96:99]
	v_mfma_f32_16x16x32_bf16 v[88:91], v[136:139], v[200:203], v[88:91]
	v_mfma_f32_16x16x32_bf16 v[80:83], v[128:131], v[210:213], v[80:83]
	v_mfma_f32_16x16x32_bf16 v[72:75], v[136:139], v[210:213], v[72:75]
	v_mfma_f32_16x16x32_bf16 v[124:127], v[132:135], v[188:191], v[124:127]
	v_mfma_f32_16x16x32_bf16 v[120:123], v[140:143], v[188:191], v[120:123]
	v_mfma_f32_16x16x32_bf16 v[112:115], v[132:135], v[196:199], v[112:115]
	v_mfma_f32_16x16x32_bf16 v[104:107], v[140:143], v[196:199], v[104:107]
	v_mfma_f32_16x16x32_bf16 v[96:99], v[132:135], v[206:209], v[96:99]
	v_mfma_f32_16x16x32_bf16 v[88:91], v[140:143], v[206:209], v[88:91]
	v_mfma_f32_16x16x32_bf16 v[80:83], v[132:135], v[214:217], v[80:83]
	v_mfma_f32_16x16x32_bf16 v[72:75], v[140:143], v[214:217], v[72:75]
	v_mfma_f32_16x16x32_bf16 v[116:119], v[162:165], v[184:187], v[116:119]
	v_mfma_f32_16x16x32_bf16 v[108:111], v[170:173], v[184:187], v[108:111]
	v_mfma_f32_16x16x32_bf16 v[100:103], v[162:165], v[192:195], v[100:103]
	v_mfma_f32_16x16x32_bf16 v[92:95], v[170:173], v[192:195], v[92:95]
	v_mfma_f32_16x16x32_bf16 v[84:87], v[162:165], v[200:203], v[84:87]
	v_mfma_f32_16x16x32_bf16 v[76:79], v[170:173], v[200:203], v[76:79]
	v_mfma_f32_16x16x32_bf16 v[68:71], v[162:165], v[210:213], v[68:71]
	v_mfma_f32_16x16x32_bf16 v[64:67], v[170:173], v[210:213], v[64:67]
	v_mfma_f32_16x16x32_bf16 v[116:119], v[166:169], v[188:191], v[116:119]
	v_mfma_f32_16x16x32_bf16 v[108:111], v[180:183], v[188:191], v[108:111]
	v_mfma_f32_16x16x32_bf16 v[100:103], v[166:169], v[196:199], v[100:103]
	v_mfma_f32_16x16x32_bf16 v[92:95], v[180:183], v[196:199], v[92:95]
	v_mfma_f32_16x16x32_bf16 v[84:87], v[166:169], v[206:209], v[84:87]
	v_mfma_f32_16x16x32_bf16 v[76:79], v[180:183], v[206:209], v[76:79]
	v_mfma_f32_16x16x32_bf16 v[68:71], v[166:169], v[214:217], v[68:71]
	v_mfma_f32_16x16x32_bf16 v[64:67], v[180:183], v[214:217], v[64:67]
	s_barrier
	s_setprio 0
	s_add_i32 s70, s55, s6
	s_nop 0
	s_add_i32 m0, s70, 0xffffff80
	ds_read_b128 v[184:187], v152 offset:49152
	ds_read_b128 v[188:191], v152 offset:50176
	ds_read_b128 v[192:195], v152 offset:51200
	ds_read_b128 v[196:199], v152 offset:52224
	ds_read_b128 v[200:203], v152 offset:53248
	ds_read_b128 v[206:209], v152 offset:54272
	ds_read_b128 v[210:213], v152 offset:55296
	ds_read_b128 v[214:217], v152 offset:56320
	global_load_lds_dwordx4 v146, s[68:69] offset:128
	s_add_i32 m0, s70, 0x1f80
	s_add_u32 s68, s68, 0x80080
	s_nop 0
	s_addc_u32 s69, s69, 0
	s_add_i32 s70, s57, s6
	global_load_lds_dwordx4 v150, s[98:99] offset:128
	s_nop 0
	s_mov_b32 m0, s70
	s_nop 0
	global_load_lds_dwordx4 v146, s[68:69]
	s_nop 0
	s_add_i32 m0, s70, 0x2000
	s_nop 0
	global_load_lds_dwordx4 v150, s[68:69]
	s_nop 0
	s_add_i32 m0, s11, 0xffffff80
	s_nop 0
	global_load_lds_dwordx4 v144, s[100:101] offset:128
	s_nop 0
	s_add_i32 m0, s12, 0xffffff80
	s_nop 0
	global_load_lds_dwordx4 v148, s[100:101] offset:128
	s_waitcnt vmcnt(8)
	s_waitcnt lgkmcnt(0)
	s_setprio 1
	s_barrier
	v_mfma_f32_16x16x32_bf16 v[60:63], v[128:131], v[184:187], v[60:63]
	v_mfma_f32_16x16x32_bf16 v[56:59], v[136:139], v[184:187], v[56:59]
	v_mfma_f32_16x16x32_bf16 v[48:51], v[128:131], v[192:195], v[48:51]
	v_mfma_f32_16x16x32_bf16 v[32:35], v[136:139], v[192:195], v[32:35]
	v_mfma_f32_16x16x32_bf16 v[16:19], v[128:131], v[200:203], v[16:19]
	v_mfma_f32_16x16x32_bf16 v[12:15], v[136:139], v[200:203], v[12:15]
	v_mfma_f32_16x16x32_bf16 v[4:7], v[128:131], v[210:213], v[4:7]
	v_mfma_f32_16x16x32_bf16 v[0:3], v[136:139], v[210:213], v[0:3]
	v_mfma_f32_16x16x32_bf16 v[60:63], v[132:135], v[188:191], v[60:63]
	v_mfma_f32_16x16x32_bf16 v[56:59], v[140:143], v[188:191], v[56:59]
	v_mfma_f32_16x16x32_bf16 v[48:51], v[132:135], v[196:199], v[48:51]
	v_mfma_f32_16x16x32_bf16 v[32:35], v[140:143], v[196:199], v[32:35]
	v_mfma_f32_16x16x32_bf16 v[16:19], v[132:135], v[206:209], v[16:19]
	v_mfma_f32_16x16x32_bf16 v[12:15], v[140:143], v[206:209], v[12:15]
	v_mfma_f32_16x16x32_bf16 v[4:7], v[132:135], v[214:217], v[4:7]
	v_mfma_f32_16x16x32_bf16 v[0:3], v[140:143], v[214:217], v[0:3]
	v_mfma_f32_16x16x32_bf16 v[52:55], v[162:165], v[184:187], v[52:55]
	v_mfma_f32_16x16x32_bf16 v[36:39], v[170:173], v[184:187], v[36:39]
	v_mfma_f32_16x16x32_bf16 v[20:23], v[162:165], v[192:195], v[20:23]
	v_mfma_f32_16x16x32_bf16 v[8:11], v[170:173], v[192:195], v[8:11]
	v_mfma_f32_16x16x32_bf16 v[40:43], v[162:165], v[200:203], v[40:43]
	v_mfma_f32_16x16x32_bf16 v[44:47], v[170:173], v[200:203], v[44:47]
	v_mfma_f32_16x16x32_bf16 v[24:27], v[162:165], v[210:213], v[24:27]
	v_mfma_f32_16x16x32_bf16 v[28:31], v[170:173], v[210:213], v[28:31]
	v_mfma_f32_16x16x32_bf16 v[52:55], v[166:169], v[188:191], v[52:55]
	v_mfma_f32_16x16x32_bf16 v[36:39], v[180:183], v[188:191], v[36:39]
	v_mfma_f32_16x16x32_bf16 v[20:23], v[166:169], v[196:199], v[20:23]
	v_mfma_f32_16x16x32_bf16 v[8:11], v[180:183], v[196:199], v[8:11]
	v_mfma_f32_16x16x32_bf16 v[40:43], v[166:169], v[206:209], v[40:43]
	v_mfma_f32_16x16x32_bf16 v[44:47], v[180:183], v[206:209], v[44:47]
	v_mfma_f32_16x16x32_bf16 v[24:27], v[166:169], v[214:217], v[24:27]
	v_mfma_f32_16x16x32_bf16 v[28:31], v[180:183], v[214:217], v[28:31]
	s_barrier
	s_setprio 0
	s_cmp_gt_u32 s63, 29
	s_cbranch_scc1 .LBB0_3762
	s_mov_b32 s63, s40
	s_branch .LBB0_3748

.LBB0_6333:
	s_or_b32 s62, s23, 1
	s_lshl_b64 vcc, s[62:63], 7
	s_add_i32 s62, s23, 2
	s_lshl_b64 s[76:77], s[62:63], 7
	v_add_u32_e32 v12, s53, v201
	v_add_u32_e32 v157, s57, v201
	s_add_u32 s28, s0, s76
	ds_read_b128 v[0:3], v12
	ds_read_b128 v[4:7], v12 offset:1024
	ds_read_b128 v[8:11], v12 offset:2048
	ds_read_b128 v[12:15], v12 offset:3072
	ds_read_b128 v[144:147], v157
	ds_read_b128 v[166:169], v157 offset:1024
	ds_read_b128 v[170:173], v157 offset:2048
	ds_read_b128 v[174:177], v157 offset:3072
	s_addc_u32 s93, s1, s77
	s_and_b64 s[44:45], s[42:43], exec
	s_cselect_b32 s45, s93, s81
	s_cselect_b32 s44, s28, s80
	s_add_u32 s28, s20, s76
	s_addc_u32 s76, s21, s77
	s_and_b64 s[42:43], s[42:43], exec
	s_cselect_b32 s43, s76, s83
	s_cselect_b32 s42, s28, s82
	s_add_u32 s28, s0, vcc_lo
	s_addc_u32 s77, s1, vcc_hi
	s_add_u32 s76, s28, 0x80000
	s_addc_u32 s77, s77, 0
	s_nop 0
	s_add_i32 m0, s5, 0xc000
	ds_read_b128 v[178:181], v209
	ds_read_b128 v[182:185], v209 offset:1024
	ds_read_b128 v[186:189], v209 offset:2048
	ds_read_b128 v[190:193], v209 offset:3072
	ds_read_b128 v[194:197], v209 offset:4096
	ds_read_b128 v[212:215], v209 offset:5120
	ds_read_b128 v[216:219], v209 offset:6144
	ds_read_b128 v[220:223], v209 offset:7168
	global_load_lds_dwordx4 v148, s[76:77]
	s_nop 0
	s_add_i32 m0, s5, 0xe000
	s_nop 0
	global_load_lds_dwordx4 v152, s[76:77]
	s_waitcnt vmcnt(8)
	s_waitcnt lgkmcnt(0)
	s_setprio 1
	s_barrier
	v_mfma_f32_16x16x32_bf16 v[108:111], v[0:3], v[178:181], v[108:111]
	v_mfma_f32_16x16x32_bf16 v[104:107], v[8:11], v[178:181], v[104:107]
	v_mfma_f32_16x16x32_bf16 v[124:127], v[0:3], v[186:189], v[124:127]
	v_mfma_f32_16x16x32_bf16 v[116:119], v[8:11], v[186:189], v[116:119]
	v_mfma_f32_16x16x32_bf16 v[120:123], v[0:3], v[194:197], v[120:123]
	v_mfma_f32_16x16x32_bf16 v[112:115], v[8:11], v[194:197], v[112:115]
	v_mfma_f32_16x16x32_bf16 v[92:95], v[0:3], v[216:219], v[92:95]
	v_mfma_f32_16x16x32_bf16 v[88:91], v[8:11], v[216:219], v[88:91]
	v_mfma_f32_16x16x32_bf16 v[108:111], v[4:7], v[182:185], v[108:111]
	v_mfma_f32_16x16x32_bf16 v[104:107], v[12:15], v[182:185], v[104:107]
	v_mfma_f32_16x16x32_bf16 v[124:127], v[4:7], v[190:193], v[124:127]
	v_mfma_f32_16x16x32_bf16 v[116:119], v[12:15], v[190:193], v[116:119]
	v_mfma_f32_16x16x32_bf16 v[120:123], v[4:7], v[212:215], v[120:123]
	v_mfma_f32_16x16x32_bf16 v[112:115], v[12:15], v[212:215], v[112:115]
	v_mfma_f32_16x16x32_bf16 v[92:95], v[4:7], v[220:223], v[92:95]
	v_mfma_f32_16x16x32_bf16 v[88:91], v[12:15], v[220:223], v[88:91]
	v_mfma_f32_16x16x32_bf16 v[140:143], v[144:147], v[178:181], v[140:143]
	v_mfma_f32_16x16x32_bf16 v[136:139], v[170:173], v[178:181], v[136:139]
	v_mfma_f32_16x16x32_bf16 v[132:135], v[144:147], v[186:189], v[132:135]
	v_mfma_f32_16x16x32_bf16 v[128:131], v[170:173], v[186:189], v[128:131]
	v_mfma_f32_16x16x32_bf16 v[100:103], v[144:147], v[194:197], v[100:103]
	v_mfma_f32_16x16x32_bf16 v[96:99], v[170:173], v[194:197], v[96:99]
	v_mfma_f32_16x16x32_bf16 v[84:87], v[144:147], v[216:219], v[84:87]
	v_mfma_f32_16x16x32_bf16 v[80:83], v[170:173], v[216:219], v[80:83]
	v_mfma_f32_16x16x32_bf16 v[140:143], v[166:169], v[182:185], v[140:143]
	v_mfma_f32_16x16x32_bf16 v[136:139], v[174:177], v[182:185], v[136:139]
	v_mfma_f32_16x16x32_bf16 v[132:135], v[166:169], v[190:193], v[132:135]
	v_mfma_f32_16x16x32_bf16 v[128:131], v[174:177], v[190:193], v[128:131]
	v_mfma_f32_16x16x32_bf16 v[100:103], v[166:169], v[212:215], v[100:103]
	v_mfma_f32_16x16x32_bf16 v[96:99], v[174:177], v[212:215], v[96:99]
	v_mfma_f32_16x16x32_bf16 v[84:87], v[166:169], v[220:223], v[84:87]
	v_mfma_f32_16x16x32_bf16 v[80:83], v[174:177], v[220:223], v[80:83]
	s_barrier
	s_setprio 0
	s_add_i32 s28, s53, s4
	s_nop 0
	s_mov_b32 m0, s28
	ds_read_b128 v[178:181], v209 offset:16384
	ds_read_b128 v[182:185], v209 offset:17408
	ds_read_b128 v[186:189], v209 offset:18432
	ds_read_b128 v[190:193], v209 offset:19456
	ds_read_b128 v[194:197], v209 offset:20480
	ds_read_b128 v[212:215], v209 offset:21504
	ds_read_b128 v[216:219], v209 offset:22528
	ds_read_b128 v[220:223], v209 offset:23552
	global_load_lds_dwordx4 v150, s[42:43]
	s_add_i32 m0, s28, 0x2000
	s_add_u32 s76, s42, 0x80000
	s_mov_b64 s[98:99], s[42:43]
	s_addc_u32 s77, s43, 0
	s_add_i32 s28, s57, s4
	global_load_lds_dwordx4 v154, s[42:43]
	s_nop 0
	s_mov_b32 m0, s28
	s_mov_b64 s[100:101], s[44:45]
	global_load_lds_dwordx4 v150, s[76:77]
	s_nop 0
	s_add_i32 m0, s28, 0x2000
	s_nop 0
	global_load_lds_dwordx4 v154, s[76:77]
	s_nop 0
	s_mov_b32 m0, s5
	s_nop 0
	global_load_lds_dwordx4 v148, s[44:45]
	s_mov_b32 m0, s6
	s_nop 0
	global_load_lds_dwordx4 v152, s[44:45]
	s_waitcnt vmcnt(8)
	s_waitcnt lgkmcnt(0)
	s_setprio 1
	s_barrier
	v_mfma_f32_16x16x32_bf16 v[76:79], v[0:3], v[178:181], v[76:79]
	v_mfma_f32_16x16x32_bf16 v[72:75], v[8:11], v[178:181], v[72:75]
	v_mfma_f32_16x16x32_bf16 v[60:63], v[0:3], v[186:189], v[60:63]
	v_mfma_f32_16x16x32_bf16 v[56:59], v[8:11], v[186:189], v[56:59]
	v_mfma_f32_16x16x32_bf16 v[44:47], v[0:3], v[194:197], v[44:47]
	v_mfma_f32_16x16x32_bf16 v[40:43], v[8:11], v[194:197], v[40:43]
	v_mfma_f32_16x16x32_bf16 v[0:3], v[0:3], v[216:219], v[28:31]
	v_mfma_f32_16x16x32_bf16 v[76:79], v[4:7], v[182:185], v[76:79]
	v_mfma_f32_16x16x32_bf16 v[72:75], v[12:15], v[182:185], v[72:75]
	v_mfma_f32_16x16x32_bf16 v[60:63], v[4:7], v[190:193], v[60:63]
	v_mfma_f32_16x16x32_bf16 v[56:59], v[12:15], v[190:193], v[56:59]
	v_mfma_f32_16x16x32_bf16 v[44:47], v[4:7], v[212:215], v[44:47]
	v_mfma_f32_16x16x32_bf16 v[40:43], v[12:15], v[212:215], v[40:43]
	v_mfma_f32_16x16x32_bf16 v[0:3], v[4:7], v[220:223], v[0:3]
	v_mfma_f32_16x16x32_bf16 v[4:7], v[8:11], v[216:219], v[20:23]
	v_mfma_f32_16x16x32_bf16 v[4:7], v[12:15], v[220:223], v[4:7]
	v_mfma_f32_16x16x32_bf16 v[20:23], v[144:147], v[186:189], v[52:55]
	v_mfma_f32_16x16x32_bf16 v[52:55], v[166:169], v[190:193], v[20:23]
	v_mfma_f32_16x16x32_bf16 v[20:23], v[170:173], v[186:189], v[48:51]
	v_mfma_f32_16x16x32_bf16 v[48:51], v[174:177], v[190:193], v[20:23]
	v_mfma_f32_16x16x32_bf16 v[20:23], v[144:147], v[194:197], v[36:39]
	v_mfma_f32_16x16x32_bf16 v[36:39], v[166:169], v[212:215], v[20:23]
	v_mfma_f32_16x16x32_bf16 v[20:23], v[170:173], v[194:197], v[32:35]
	v_mfma_f32_16x16x32_bf16 v[32:35], v[174:177], v[212:215], v[20:23]
	v_mfma_f32_16x16x32_bf16 v[20:23], v[144:147], v[216:219], v[24:27]
	v_mfma_f32_16x16x32_bf16 v[16:19], v[170:173], v[216:219], v[16:19]
	v_mfma_f32_16x16x32_bf16 v[8:11], v[144:147], v[178:181], v[68:71]
	v_mfma_f32_16x16x32_bf16 v[12:15], v[170:173], v[178:181], v[64:67]
	v_mfma_f32_16x16x32_bf16 v[24:27], v[166:169], v[220:223], v[20:23]
	v_mfma_f32_16x16x32_bf16 v[16:19], v[174:177], v[220:223], v[16:19]
	v_mfma_f32_16x16x32_bf16 v[8:11], v[166:169], v[182:185], v[8:11]
	v_mfma_f32_16x16x32_bf16 v[12:15], v[174:177], v[182:185], v[12:15]
	s_barrier
	s_setprio 0
	v_add_u32_e32 v68, s86, v201
	v_add_u32_e32 v157, s87, v201
	ds_read_b128 v[20:23], v68
	ds_read_b128 v[28:31], v68 offset:1024
	ds_read_b128 v[64:67], v68 offset:2048
	ds_read_b128 v[68:71], v68 offset:3072
	ds_read_b128 v[144:147], v157
	ds_read_b128 v[166:169], v157 offset:1024
	ds_read_b128 v[170:173], v157 offset:2048
	ds_read_b128 v[174:177], v157 offset:3072
	s_add_u32 s44, s44, 0x80000
	s_addc_u32 s45, s45, 0
	s_mov_b32 m0, s7
	s_nop 0
	ds_read_b128 v[178:181], v209 offset:32768
	ds_read_b128 v[182:185], v209 offset:33792
	ds_read_b128 v[186:189], v209 offset:34816
	ds_read_b128 v[190:193], v209 offset:35840
	ds_read_b128 v[194:197], v209 offset:36864
	ds_read_b128 v[212:215], v209 offset:37888
	ds_read_b128 v[216:219], v209 offset:38912
	ds_read_b128 v[220:223], v209 offset:39936
	global_load_lds_dwordx4 v148, s[44:45]
	s_nop 0
	s_mov_b32 m0, s8
	s_nop 0
	global_load_lds_dwordx4 v152, s[44:45]
	s_waitcnt vmcnt(8)
	s_waitcnt lgkmcnt(0)
	s_setprio 1
	s_barrier
	v_mfma_f32_16x16x32_bf16 v[108:111], v[20:23], v[178:181], v[108:111]
	v_mfma_f32_16x16x32_bf16 v[104:107], v[64:67], v[178:181], v[104:107]
	v_mfma_f32_16x16x32_bf16 v[124:127], v[20:23], v[186:189], v[124:127]
	v_mfma_f32_16x16x32_bf16 v[116:119], v[64:67], v[186:189], v[116:119]
	v_mfma_f32_16x16x32_bf16 v[120:123], v[20:23], v[194:197], v[120:123]
	v_mfma_f32_16x16x32_bf16 v[112:115], v[64:67], v[194:197], v[112:115]
	v_mfma_f32_16x16x32_bf16 v[92:95], v[20:23], v[216:219], v[92:95]
	v_mfma_f32_16x16x32_bf16 v[88:91], v[64:67], v[216:219], v[88:91]
	v_mfma_f32_16x16x32_bf16 v[108:111], v[28:31], v[182:185], v[108:111]
	v_mfma_f32_16x16x32_bf16 v[104:107], v[68:71], v[182:185], v[104:107]
	v_mfma_f32_16x16x32_bf16 v[124:127], v[28:31], v[190:193], v[124:127]
	v_mfma_f32_16x16x32_bf16 v[116:119], v[68:71], v[190:193], v[116:119]
	v_mfma_f32_16x16x32_bf16 v[120:123], v[28:31], v[212:215], v[120:123]
	v_mfma_f32_16x16x32_bf16 v[112:115], v[68:71], v[212:215], v[112:115]
	v_mfma_f32_16x16x32_bf16 v[92:95], v[28:31], v[220:223], v[92:95]
	v_mfma_f32_16x16x32_bf16 v[88:91], v[68:71], v[220:223], v[88:91]
	v_mfma_f32_16x16x32_bf16 v[140:143], v[144:147], v[178:181], v[140:143]
	v_mfma_f32_16x16x32_bf16 v[136:139], v[170:173], v[178:181], v[136:139]
	v_mfma_f32_16x16x32_bf16 v[132:135], v[144:147], v[186:189], v[132:135]
	v_mfma_f32_16x16x32_bf16 v[128:131], v[170:173], v[186:189], v[128:131]
	v_mfma_f32_16x16x32_bf16 v[100:103], v[144:147], v[194:197], v[100:103]
	v_mfma_f32_16x16x32_bf16 v[96:99], v[170:173], v[194:197], v[96:99]
	v_mfma_f32_16x16x32_bf16 v[84:87], v[144:147], v[216:219], v[84:87]
	v_mfma_f32_16x16x32_bf16 v[80:83], v[170:173], v[216:219], v[80:83]
	v_mfma_f32_16x16x32_bf16 v[140:143], v[166:169], v[182:185], v[140:143]
	v_mfma_f32_16x16x32_bf16 v[136:139], v[174:177], v[182:185], v[136:139]
	v_mfma_f32_16x16x32_bf16 v[132:135], v[166:169], v[190:193], v[132:135]
	v_mfma_f32_16x16x32_bf16 v[128:131], v[174:177], v[190:193], v[128:131]
	v_mfma_f32_16x16x32_bf16 v[100:103], v[166:169], v[212:215], v[100:103]
	v_mfma_f32_16x16x32_bf16 v[96:99], v[174:177], v[212:215], v[96:99]
	v_mfma_f32_16x16x32_bf16 v[84:87], v[166:169], v[220:223], v[84:87]
	v_mfma_f32_16x16x32_bf16 v[80:83], v[174:177], v[220:223], v[80:83]
	s_barrier
	s_setprio 0
	s_add_i32 s28, s86, s4
	s_nop 0
	s_add_i32 m0, s28, 0xffffff80
	ds_read_b128 v[178:181], v209 offset:49152
	ds_read_b128 v[182:185], v209 offset:50176
	ds_read_b128 v[186:189], v209 offset:51200
	ds_read_b128 v[190:193], v209 offset:52224
	ds_read_b128 v[194:197], v209 offset:53248
	ds_read_b128 v[212:215], v209 offset:54272
	ds_read_b128 v[216:219], v209 offset:55296
	ds_read_b128 v[220:223], v209 offset:56320
	global_load_lds_dwordx4 v150, s[42:43] offset:128
	s_add_i32 m0, s28, 0x1f80
	s_add_u32 s42, s42, 0x80080
	s_nop 0
	s_addc_u32 s43, s43, 0
	s_add_i32 s28, s87, s4
	global_load_lds_dwordx4 v154, s[98:99] offset:128
	s_nop 0
	s_mov_b32 m0, s28
	s_nop 0
	global_load_lds_dwordx4 v150, s[42:43]
	s_nop 0
	s_add_i32 m0, s28, 0x2000
	s_nop 0
	global_load_lds_dwordx4 v154, s[42:43]
	s_nop 0
	s_add_i32 m0, s9, 0xffffff80
	s_nop 0
	global_load_lds_dwordx4 v148, s[100:101] offset:128
	s_nop 0
	s_add_i32 m0, s10, 0xffffff80
	s_nop 0
	global_load_lds_dwordx4 v152, s[100:101] offset:128
	s_waitcnt vmcnt(8)
	s_waitcnt lgkmcnt(0)
	s_setprio 1
	s_barrier
	v_mfma_f32_16x16x32_bf16 v[76:79], v[20:23], v[178:181], v[76:79]
	v_mfma_f32_16x16x32_bf16 v[60:63], v[20:23], v[186:189], v[60:63]
	v_mfma_f32_16x16x32_bf16 v[44:47], v[20:23], v[194:197], v[44:47]
	v_mfma_f32_16x16x32_bf16 v[0:3], v[20:23], v[216:219], v[0:3]
	v_mfma_f32_16x16x32_bf16 v[76:79], v[28:31], v[182:185], v[76:79]
	v_mfma_f32_16x16x32_bf16 v[72:75], v[64:67], v[178:181], v[72:75]
	v_mfma_f32_16x16x32_bf16 v[60:63], v[28:31], v[190:193], v[60:63]
	v_mfma_f32_16x16x32_bf16 v[56:59], v[64:67], v[186:189], v[56:59]
	v_mfma_f32_16x16x32_bf16 v[44:47], v[28:31], v[212:215], v[44:47]
	v_mfma_f32_16x16x32_bf16 v[40:43], v[64:67], v[194:197], v[40:43]
	v_mfma_f32_16x16x32_bf16 v[28:31], v[28:31], v[220:223], v[0:3]
	v_mfma_f32_16x16x32_bf16 v[0:3], v[64:67], v[216:219], v[4:7]
	v_mfma_f32_16x16x32_bf16 v[72:75], v[68:71], v[182:185], v[72:75]
	v_mfma_f32_16x16x32_bf16 v[56:59], v[68:71], v[190:193], v[56:59]
	v_mfma_f32_16x16x32_bf16 v[40:43], v[68:71], v[212:215], v[40:43]
	v_mfma_f32_16x16x32_bf16 v[20:23], v[68:71], v[220:223], v[0:3]
	v_mfma_f32_16x16x32_bf16 v[0:3], v[144:147], v[178:181], v[8:11]
	v_mfma_f32_16x16x32_bf16 v[68:71], v[166:169], v[182:185], v[0:3]
	v_mfma_f32_16x16x32_bf16 v[0:3], v[170:173], v[178:181], v[12:15]
	v_mfma_f32_16x16x32_bf16 v[64:67], v[174:177], v[182:185], v[0:3]
	v_mfma_f32_16x16x32_bf16 v[0:3], v[144:147], v[186:189], v[52:55]
	v_mfma_f32_16x16x32_bf16 v[52:55], v[166:169], v[190:193], v[0:3]
	v_mfma_f32_16x16x32_bf16 v[0:3], v[170:173], v[186:189], v[48:51]
	v_mfma_f32_16x16x32_bf16 v[48:51], v[174:177], v[190:193], v[0:3]
	v_mfma_f32_16x16x32_bf16 v[0:3], v[144:147], v[194:197], v[36:39]
	v_mfma_f32_16x16x32_bf16 v[36:39], v[166:169], v[212:215], v[0:3]
	v_mfma_f32_16x16x32_bf16 v[0:3], v[170:173], v[194:197], v[32:35]
	v_mfma_f32_16x16x32_bf16 v[32:35], v[174:177], v[212:215], v[0:3]
	v_mfma_f32_16x16x32_bf16 v[0:3], v[144:147], v[216:219], v[24:27]
	v_mfma_f32_16x16x32_bf16 v[24:27], v[166:169], v[220:223], v[0:3]
	v_mfma_f32_16x16x32_bf16 v[0:3], v[170:173], v[216:219], v[16:19]
	v_mfma_f32_16x16x32_bf16 v[16:19], v[174:177], v[220:223], v[0:3]
	s_barrier
	s_setprio 0
	s_cmp_gt_u32 s23, 29
	s_cbranch_scc1 .LBB0_6335
	s_mov_b32 s23, s62
	s_branch .LBB0_6321

.LBB0_7545:
	s_or_b32 s44, s69, 1
	s_lshl_b64 s[94:95], s[44:45], 7
	s_add_i32 s44, s69, 2
	s_lshl_b64 vcc, s[44:45], 7
	s_add_u32 s42, s64, vcc_lo
	s_addc_u32 s93, s65, vcc_hi
	s_and_b64 s[74:75], s[72:73], exec
	s_cselect_b32 s75, s93, s59
	s_cselect_b32 s74, s42, s58
	s_add_u32 s42, s66, vcc_lo
	s_addc_u32 s93, s67, vcc_hi
	s_add_i32 vcc_lo, 0, 0x10000
	s_and_b64 s[72:73], s[72:73], exec
	s_cselect_b32 s73, s93, s61
	s_cselect_b32 s72, s42, s60
	s_add_i32 s42, 0, 0x14000
	v_add_u32_e32 v140, vcc_lo, v168
	v_add_u32_e32 v173, s42, v168
	ds_read_b128 v[128:131], v140
	ds_read_b128 v[132:135], v140 offset:1024
	ds_read_b128 v[136:139], v140 offset:2048
	ds_read_b128 v[140:143], v140 offset:3072
	ds_read_b128 v[160:163], v173
	ds_read_b128 v[174:177], v173 offset:1024
	ds_read_b128 v[178:181], v173 offset:2048
	ds_read_b128 v[182:185], v173 offset:3072
	s_add_u32 s93, s64, s94
	s_addc_u32 s95, s65, s95
	s_add_u32 s94, s93, 0x80000
	s_addc_u32 s95, s95, 0
	s_nop 0
	s_add_i32 m0, s63, 0xc000
	ds_read_b128 v[186:189], v172
	ds_read_b128 v[190:193], v172 offset:1024
	ds_read_b128 v[194:197], v172 offset:2048
	ds_read_b128 v[198:201], v172 offset:3072
	ds_read_b128 v[206:209], v172 offset:4096
	ds_read_b128 v[210:213], v172 offset:5120
	ds_read_b128 v[214:217], v172 offset:6144
	ds_read_b128 v[218:221], v172 offset:7168
	global_load_lds_dwordx4 v152, s[94:95]
	s_nop 0
	s_add_i32 m0, s63, 0xe000
	s_nop 0
	global_load_lds_dwordx4 v154, s[94:95]
	s_waitcnt vmcnt(8)
	s_waitcnt lgkmcnt(0)
	s_setprio 1
	s_barrier
	v_mfma_f32_16x16x32_bf16 v[124:127], v[128:131], v[186:189], v[124:127]
	v_mfma_f32_16x16x32_bf16 v[120:123], v[136:139], v[186:189], v[120:123]
	v_mfma_f32_16x16x32_bf16 v[108:111], v[128:131], v[194:197], v[108:111]
	v_mfma_f32_16x16x32_bf16 v[104:107], v[136:139], v[194:197], v[104:107]
	v_mfma_f32_16x16x32_bf16 v[92:95], v[128:131], v[206:209], v[92:95]
	v_mfma_f32_16x16x32_bf16 v[88:91], v[136:139], v[206:209], v[88:91]
	v_mfma_f32_16x16x32_bf16 v[76:79], v[128:131], v[214:217], v[76:79]
	v_mfma_f32_16x16x32_bf16 v[72:75], v[136:139], v[214:217], v[72:75]
	v_mfma_f32_16x16x32_bf16 v[124:127], v[132:135], v[190:193], v[124:127]
	v_mfma_f32_16x16x32_bf16 v[120:123], v[140:143], v[190:193], v[120:123]
	v_mfma_f32_16x16x32_bf16 v[108:111], v[132:135], v[198:201], v[108:111]
	v_mfma_f32_16x16x32_bf16 v[104:107], v[140:143], v[198:201], v[104:107]
	v_mfma_f32_16x16x32_bf16 v[92:95], v[132:135], v[210:213], v[92:95]
	v_mfma_f32_16x16x32_bf16 v[88:91], v[140:143], v[210:213], v[88:91]
	v_mfma_f32_16x16x32_bf16 v[76:79], v[132:135], v[218:221], v[76:79]
	v_mfma_f32_16x16x32_bf16 v[72:75], v[140:143], v[218:221], v[72:75]
	v_mfma_f32_16x16x32_bf16 v[116:119], v[160:163], v[186:189], v[116:119]
	v_mfma_f32_16x16x32_bf16 v[112:115], v[178:181], v[186:189], v[112:115]
	v_mfma_f32_16x16x32_bf16 v[100:103], v[160:163], v[194:197], v[100:103]
	v_mfma_f32_16x16x32_bf16 v[96:99], v[178:181], v[194:197], v[96:99]
	v_mfma_f32_16x16x32_bf16 v[84:87], v[160:163], v[206:209], v[84:87]
	v_mfma_f32_16x16x32_bf16 v[80:83], v[178:181], v[206:209], v[80:83]
	v_mfma_f32_16x16x32_bf16 v[68:71], v[160:163], v[214:217], v[68:71]
	v_mfma_f32_16x16x32_bf16 v[64:67], v[178:181], v[214:217], v[64:67]
	v_mfma_f32_16x16x32_bf16 v[116:119], v[174:177], v[190:193], v[116:119]
	v_mfma_f32_16x16x32_bf16 v[112:115], v[182:185], v[190:193], v[112:115]
	v_mfma_f32_16x16x32_bf16 v[100:103], v[174:177], v[198:201], v[100:103]
	v_mfma_f32_16x16x32_bf16 v[96:99], v[182:185], v[198:201], v[96:99]
	v_mfma_f32_16x16x32_bf16 v[84:87], v[174:177], v[210:213], v[84:87]
	v_mfma_f32_16x16x32_bf16 v[80:83], v[182:185], v[210:213], v[80:83]
	v_mfma_f32_16x16x32_bf16 v[68:71], v[174:177], v[218:221], v[68:71]
	v_mfma_f32_16x16x32_bf16 v[64:67], v[182:185], v[218:221], v[64:67]
	s_barrier
	s_setprio 0
	s_add_i32 s93, vcc_lo, s83
	s_nop 0
	s_mov_b32 m0, s93
	ds_read_b128 v[186:189], v172 offset:16384
	ds_read_b128 v[190:193], v172 offset:17408
	ds_read_b128 v[194:197], v172 offset:18432
	ds_read_b128 v[198:201], v172 offset:19456
	ds_read_b128 v[206:209], v172 offset:20480
	ds_read_b128 v[210:213], v172 offset:21504
	ds_read_b128 v[214:217], v172 offset:22528
	ds_read_b128 v[218:221], v172 offset:23552
	global_load_lds_dwordx4 v144, s[72:73]
	s_add_i32 m0, s93, 0x2000
	s_add_u32 s94, s72, 0x80000
	s_mov_b64 s[98:99], s[72:73]
	s_addc_u32 s95, s73, 0
	s_add_i32 s42, s42, s83
	global_load_lds_dwordx4 v156, s[72:73]
	s_nop 0
	s_mov_b32 m0, s42
	s_mov_b64 s[100:101], s[74:75]
	global_load_lds_dwordx4 v144, s[94:95]
	s_nop 0
	s_add_i32 m0, s42, 0x2000
	s_nop 0
	global_load_lds_dwordx4 v156, s[94:95]
	s_nop 0
	s_mov_b32 m0, s63
	s_nop 0
	global_load_lds_dwordx4 v152, s[74:75]
	s_mov_b32 m0, s84
	s_nop 0
	global_load_lds_dwordx4 v154, s[74:75]
	s_waitcnt vmcnt(8)
	s_waitcnt lgkmcnt(0)
	s_setprio 1
	s_barrier
	v_mfma_f32_16x16x32_bf16 v[60:63], v[128:131], v[186:189], v[60:63]
	v_mfma_f32_16x16x32_bf16 v[56:59], v[136:139], v[186:189], v[56:59]
	v_mfma_f32_16x16x32_bf16 v[44:47], v[128:131], v[194:197], v[44:47]
	v_mfma_f32_16x16x32_bf16 v[40:43], v[136:139], v[194:197], v[40:43]
	v_mfma_f32_16x16x32_bf16 v[24:27], v[128:131], v[206:209], v[24:27]
	v_mfma_f32_16x16x32_bf16 v[16:19], v[136:139], v[206:209], v[16:19]
	v_mfma_f32_16x16x32_bf16 v[4:7], v[128:131], v[214:217], v[4:7]
	v_mfma_f32_16x16x32_bf16 v[0:3], v[136:139], v[214:217], v[0:3]
	v_mfma_f32_16x16x32_bf16 v[60:63], v[132:135], v[190:193], v[60:63]
	v_mfma_f32_16x16x32_bf16 v[56:59], v[140:143], v[190:193], v[56:59]
	v_mfma_f32_16x16x32_bf16 v[44:47], v[132:135], v[198:201], v[44:47]
	v_mfma_f32_16x16x32_bf16 v[40:43], v[140:143], v[198:201], v[40:43]
	v_mfma_f32_16x16x32_bf16 v[24:27], v[132:135], v[210:213], v[24:27]
	v_mfma_f32_16x16x32_bf16 v[16:19], v[140:143], v[210:213], v[16:19]
	v_mfma_f32_16x16x32_bf16 v[4:7], v[132:135], v[218:221], v[4:7]
	v_mfma_f32_16x16x32_bf16 v[0:3], v[140:143], v[218:221], v[0:3]
	v_mfma_f32_16x16x32_bf16 v[52:55], v[160:163], v[186:189], v[52:55]
	v_mfma_f32_16x16x32_bf16 v[48:51], v[178:181], v[186:189], v[48:51]
	v_mfma_f32_16x16x32_bf16 v[28:31], v[160:163], v[194:197], v[28:31]
	v_mfma_f32_16x16x32_bf16 v[20:23], v[178:181], v[194:197], v[20:23]
	v_mfma_f32_16x16x32_bf16 v[32:35], v[160:163], v[206:209], v[32:35]
	v_mfma_f32_16x16x32_bf16 v[36:39], v[178:181], v[206:209], v[36:39]
	v_mfma_f32_16x16x32_bf16 v[8:11], v[160:163], v[214:217], v[8:11]
	v_mfma_f32_16x16x32_bf16 v[12:15], v[178:181], v[214:217], v[12:15]
	v_mfma_f32_16x16x32_bf16 v[52:55], v[174:177], v[190:193], v[52:55]
	v_mfma_f32_16x16x32_bf16 v[48:51], v[182:185], v[190:193], v[48:51]
	v_mfma_f32_16x16x32_bf16 v[28:31], v[174:177], v[198:201], v[28:31]
	v_mfma_f32_16x16x32_bf16 v[20:23], v[182:185], v[198:201], v[20:23]
	v_mfma_f32_16x16x32_bf16 v[32:35], v[174:177], v[210:213], v[32:35]
	v_mfma_f32_16x16x32_bf16 v[36:39], v[182:185], v[210:213], v[36:39]
	v_mfma_f32_16x16x32_bf16 v[8:11], v[174:177], v[218:221], v[8:11]
	v_mfma_f32_16x16x32_bf16 v[12:15], v[182:185], v[218:221], v[12:15]
	s_barrier
	s_setprio 0
	s_add_i32 s42, 0, 0x18000
	s_add_i32 s93, 0, 0x1c000
	v_add_u32_e32 v140, s42, v168
	v_add_u32_e32 v173, s93, v168
	ds_read_b128 v[128:131], v140
	ds_read_b128 v[132:135], v140 offset:1024
	ds_read_b128 v[136:139], v140 offset:2048
	ds_read_b128 v[140:143], v140 offset:3072
	ds_read_b128 v[160:163], v173
	ds_read_b128 v[174:177], v173 offset:1024
	ds_read_b128 v[178:181], v173 offset:2048
	ds_read_b128 v[182:185], v173 offset:3072
	s_add_u32 s74, s74, 0x80000
	s_addc_u32 s75, s75, 0
	s_mov_b32 m0, s85
	s_nop 0
	ds_read_b128 v[186:189], v172 offset:32768
	ds_read_b128 v[190:193], v172 offset:33792
	ds_read_b128 v[194:197], v172 offset:34816
	ds_read_b128 v[198:201], v172 offset:35840
	ds_read_b128 v[206:209], v172 offset:36864
	ds_read_b128 v[210:213], v172 offset:37888
	ds_read_b128 v[214:217], v172 offset:38912
	ds_read_b128 v[218:221], v172 offset:39936
	global_load_lds_dwordx4 v152, s[74:75]
	s_nop 0
	s_mov_b32 m0, s86
	s_nop 0
	global_load_lds_dwordx4 v154, s[74:75]
	s_waitcnt vmcnt(8)
	s_waitcnt lgkmcnt(0)
	s_setprio 1
	s_barrier
	v_mfma_f32_16x16x32_bf16 v[124:127], v[128:131], v[186:189], v[124:127]
	v_mfma_f32_16x16x32_bf16 v[120:123], v[136:139], v[186:189], v[120:123]
	v_mfma_f32_16x16x32_bf16 v[108:111], v[128:131], v[194:197], v[108:111]
	v_mfma_f32_16x16x32_bf16 v[104:107], v[136:139], v[194:197], v[104:107]
	v_mfma_f32_16x16x32_bf16 v[92:95], v[128:131], v[206:209], v[92:95]
	v_mfma_f32_16x16x32_bf16 v[88:91], v[136:139], v[206:209], v[88:91]
	v_mfma_f32_16x16x32_bf16 v[76:79], v[128:131], v[214:217], v[76:79]
	v_mfma_f32_16x16x32_bf16 v[72:75], v[136:139], v[214:217], v[72:75]
	v_mfma_f32_16x16x32_bf16 v[124:127], v[132:135], v[190:193], v[124:127]
	v_mfma_f32_16x16x32_bf16 v[120:123], v[140:143], v[190:193], v[120:123]
	v_mfma_f32_16x16x32_bf16 v[108:111], v[132:135], v[198:201], v[108:111]
	v_mfma_f32_16x16x32_bf16 v[104:107], v[140:143], v[198:201], v[104:107]
	v_mfma_f32_16x16x32_bf16 v[92:95], v[132:135], v[210:213], v[92:95]
	v_mfma_f32_16x16x32_bf16 v[88:91], v[140:143], v[210:213], v[88:91]
	v_mfma_f32_16x16x32_bf16 v[76:79], v[132:135], v[218:221], v[76:79]
	v_mfma_f32_16x16x32_bf16 v[72:75], v[140:143], v[218:221], v[72:75]
	v_mfma_f32_16x16x32_bf16 v[116:119], v[160:163], v[186:189], v[116:119]
	v_mfma_f32_16x16x32_bf16 v[112:115], v[178:181], v[186:189], v[112:115]
	v_mfma_f32_16x16x32_bf16 v[100:103], v[160:163], v[194:197], v[100:103]
	v_mfma_f32_16x16x32_bf16 v[96:99], v[178:181], v[194:197], v[96:99]
	v_mfma_f32_16x16x32_bf16 v[84:87], v[160:163], v[206:209], v[84:87]
	v_mfma_f32_16x16x32_bf16 v[80:83], v[178:181], v[206:209], v[80:83]
	v_mfma_f32_16x16x32_bf16 v[68:71], v[160:163], v[214:217], v[68:71]
	v_mfma_f32_16x16x32_bf16 v[64:67], v[178:181], v[214:217], v[64:67]
	v_mfma_f32_16x16x32_bf16 v[116:119], v[174:177], v[190:193], v[116:119]
	v_mfma_f32_16x16x32_bf16 v[112:115], v[182:185], v[190:193], v[112:115]
	v_mfma_f32_16x16x32_bf16 v[100:103], v[174:177], v[198:201], v[100:103]
	v_mfma_f32_16x16x32_bf16 v[96:99], v[182:185], v[198:201], v[96:99]
	v_mfma_f32_16x16x32_bf16 v[84:87], v[174:177], v[210:213], v[84:87]
	v_mfma_f32_16x16x32_bf16 v[80:83], v[182:185], v[210:213], v[80:83]
	v_mfma_f32_16x16x32_bf16 v[68:71], v[174:177], v[218:221], v[68:71]
	v_mfma_f32_16x16x32_bf16 v[64:67], v[182:185], v[218:221], v[64:67]
	s_barrier
	s_setprio 0
	s_add_i32 s42, s42, s83
	s_nop 0
	s_add_i32 m0, s42, 0xffffff80
	ds_read_b128 v[186:189], v172 offset:49152
	ds_read_b128 v[190:193], v172 offset:50176
	ds_read_b128 v[194:197], v172 offset:51200
	ds_read_b128 v[198:201], v172 offset:52224
	ds_read_b128 v[206:209], v172 offset:53248
	ds_read_b128 v[210:213], v172 offset:54272
	ds_read_b128 v[214:217], v172 offset:55296
	ds_read_b128 v[218:221], v172 offset:56320
	global_load_lds_dwordx4 v144, s[72:73] offset:128
	s_add_i32 m0, s42, 0x1f80
	s_add_u32 s72, s72, 0x80080
	s_nop 0
	s_addc_u32 s73, s73, 0
	s_add_i32 s42, s93, s83
	global_load_lds_dwordx4 v156, s[98:99] offset:128
	s_nop 0
	s_mov_b32 m0, s42
	s_nop 0
	global_load_lds_dwordx4 v144, s[72:73]
	s_nop 0
	s_add_i32 m0, s42, 0x2000
	s_nop 0
	global_load_lds_dwordx4 v156, s[72:73]
	s_nop 0
	s_add_i32 m0, s87, 0xffffff80
	s_nop 0
	global_load_lds_dwordx4 v152, s[100:101] offset:128
	s_nop 0
	s_add_i32 m0, s88, 0xffffff80
	s_nop 0
	global_load_lds_dwordx4 v154, s[100:101] offset:128
	s_waitcnt vmcnt(8)
	s_waitcnt lgkmcnt(0)
	s_setprio 1
	s_barrier
	v_mfma_f32_16x16x32_bf16 v[60:63], v[128:131], v[186:189], v[60:63]
	v_mfma_f32_16x16x32_bf16 v[56:59], v[136:139], v[186:189], v[56:59]
	v_mfma_f32_16x16x32_bf16 v[44:47], v[128:131], v[194:197], v[44:47]
	v_mfma_f32_16x16x32_bf16 v[40:43], v[136:139], v[194:197], v[40:43]
	v_mfma_f32_16x16x32_bf16 v[24:27], v[128:131], v[206:209], v[24:27]
	v_mfma_f32_16x16x32_bf16 v[16:19], v[136:139], v[206:209], v[16:19]
	v_mfma_f32_16x16x32_bf16 v[4:7], v[128:131], v[214:217], v[4:7]
	v_mfma_f32_16x16x32_bf16 v[0:3], v[136:139], v[214:217], v[0:3]
	v_mfma_f32_16x16x32_bf16 v[60:63], v[132:135], v[190:193], v[60:63]
	v_mfma_f32_16x16x32_bf16 v[56:59], v[140:143], v[190:193], v[56:59]
	v_mfma_f32_16x16x32_bf16 v[44:47], v[132:135], v[198:201], v[44:47]
	v_mfma_f32_16x16x32_bf16 v[40:43], v[140:143], v[198:201], v[40:43]
	v_mfma_f32_16x16x32_bf16 v[24:27], v[132:135], v[210:213], v[24:27]
	v_mfma_f32_16x16x32_bf16 v[16:19], v[140:143], v[210:213], v[16:19]
	v_mfma_f32_16x16x32_bf16 v[4:7], v[132:135], v[218:221], v[4:7]
	v_mfma_f32_16x16x32_bf16 v[0:3], v[140:143], v[218:221], v[0:3]
	v_mfma_f32_16x16x32_bf16 v[52:55], v[160:163], v[186:189], v[52:55]
	v_mfma_f32_16x16x32_bf16 v[48:51], v[178:181], v[186:189], v[48:51]
	v_mfma_f32_16x16x32_bf16 v[28:31], v[160:163], v[194:197], v[28:31]
	v_mfma_f32_16x16x32_bf16 v[20:23], v[178:181], v[194:197], v[20:23]
	v_mfma_f32_16x16x32_bf16 v[32:35], v[160:163], v[206:209], v[32:35]
	v_mfma_f32_16x16x32_bf16 v[36:39], v[178:181], v[206:209], v[36:39]
	v_mfma_f32_16x16x32_bf16 v[8:11], v[160:163], v[214:217], v[8:11]
	v_mfma_f32_16x16x32_bf16 v[12:15], v[178:181], v[214:217], v[12:15]
	v_mfma_f32_16x16x32_bf16 v[52:55], v[174:177], v[190:193], v[52:55]
	v_mfma_f32_16x16x32_bf16 v[48:51], v[182:185], v[190:193], v[48:51]
	v_mfma_f32_16x16x32_bf16 v[28:31], v[174:177], v[198:201], v[28:31]
	v_mfma_f32_16x16x32_bf16 v[20:23], v[182:185], v[198:201], v[20:23]
	v_mfma_f32_16x16x32_bf16 v[32:35], v[174:177], v[210:213], v[32:35]
	v_mfma_f32_16x16x32_bf16 v[36:39], v[182:185], v[210:213], v[36:39]
	v_mfma_f32_16x16x32_bf16 v[8:11], v[174:177], v[218:221], v[8:11]
	v_mfma_f32_16x16x32_bf16 v[12:15], v[182:185], v[218:221], v[12:15]
	s_barrier
	s_setprio 0
	s_cmp_gt_u32 s69, 29
	s_cbranch_scc1 .LBB0_7547
	s_mov_b32 s69, s44
	s_branch .LBB0_7533

.LBB0_7633:
	s_add_i32 vcc_hi, s26, 2
	s_add_u32 s94, s22, 0x80
	s_addc_u32 s27, s23, 0
	s_add_i32 s93, 0, 0x10000
	s_cmp_eq_u32 s90, s26
	s_cselect_b32 s27, s44, s27
	s_cselect_b32 s26, s57, s94
	v_add_u32_e32 v155, s93, v143
	s_cselect_b32 s95, s62, vcc_lo
	s_cselect_b32 s94, s63, s91
	s_add_i32 s42, 0, 0x14000
	ds_read_b128 v[138:141], v155
	ds_read_b128 v[156:159], v155 offset:1024
	ds_read_b128 v[160:163], v155 offset:2048
	ds_read_b128 v[166:169], v155 offset:3072
	v_add_u32_e32 v155, s42, v143
	ds_read_b128 v[170:173], v155
	ds_read_b128 v[174:177], v155 offset:1024
	ds_read_b128 v[178:181], v155 offset:2048
	ds_read_b128 v[182:185], v155 offset:3072
	s_nop 0
	s_add_i32 m0, s73, 0xc000
	ds_read_b128 v[186:189], v154
	ds_read_b128 v[190:193], v154 offset:1024
	ds_read_b128 v[194:197], v154 offset:2048
	ds_read_b128 v[198:201], v154 offset:3072
	ds_read_b128 v[206:209], v154 offset:4096
	ds_read_b128 v[210:213], v154 offset:5120
	ds_read_b128 v[214:217], v154 offset:6144
	ds_read_b128 v[218:221], v154 offset:7168
	global_load_lds_dwordx4 v136, s[22:23]
	s_nop 0
	s_add_i32 m0, s73, 0xe000
	s_nop 0
	global_load_lds_dwordx4 v134, s[22:23]
	s_waitcnt vmcnt(8)
	s_waitcnt lgkmcnt(0)
	s_setprio 1
	s_barrier
	v_mfma_f32_16x16x32_bf16 v[124:127], v[138:141], v[186:189], v[124:127]
	v_mfma_f32_16x16x32_bf16 v[120:123], v[160:163], v[186:189], v[120:123]
	v_mfma_f32_16x16x32_bf16 v[108:111], v[138:141], v[194:197], v[108:111]
	v_mfma_f32_16x16x32_bf16 v[104:107], v[160:163], v[194:197], v[104:107]
	v_mfma_f32_16x16x32_bf16 v[92:95], v[138:141], v[206:209], v[92:95]
	v_mfma_f32_16x16x32_bf16 v[88:91], v[160:163], v[206:209], v[88:91]
	v_mfma_f32_16x16x32_bf16 v[76:79], v[138:141], v[214:217], v[76:79]
	v_mfma_f32_16x16x32_bf16 v[72:75], v[160:163], v[214:217], v[72:75]
	v_mfma_f32_16x16x32_bf16 v[124:127], v[156:159], v[190:193], v[124:127]
	v_mfma_f32_16x16x32_bf16 v[120:123], v[166:169], v[190:193], v[120:123]
	v_mfma_f32_16x16x32_bf16 v[108:111], v[156:159], v[198:201], v[108:111]
	v_mfma_f32_16x16x32_bf16 v[104:107], v[166:169], v[198:201], v[104:107]
	v_mfma_f32_16x16x32_bf16 v[92:95], v[156:159], v[210:213], v[92:95]
	v_mfma_f32_16x16x32_bf16 v[88:91], v[166:169], v[210:213], v[88:91]
	v_mfma_f32_16x16x32_bf16 v[76:79], v[156:159], v[218:221], v[76:79]
	v_mfma_f32_16x16x32_bf16 v[72:75], v[166:169], v[218:221], v[72:75]
	v_mfma_f32_16x16x32_bf16 v[116:119], v[170:173], v[186:189], v[116:119]
	v_mfma_f32_16x16x32_bf16 v[112:115], v[178:181], v[186:189], v[112:115]
	v_mfma_f32_16x16x32_bf16 v[100:103], v[170:173], v[194:197], v[100:103]
	v_mfma_f32_16x16x32_bf16 v[96:99], v[178:181], v[194:197], v[96:99]
	v_mfma_f32_16x16x32_bf16 v[84:87], v[170:173], v[206:209], v[84:87]
	v_mfma_f32_16x16x32_bf16 v[80:83], v[178:181], v[206:209], v[80:83]
	v_mfma_f32_16x16x32_bf16 v[68:71], v[170:173], v[214:217], v[68:71]
	v_mfma_f32_16x16x32_bf16 v[64:67], v[178:181], v[214:217], v[64:67]
	v_mfma_f32_16x16x32_bf16 v[116:119], v[174:177], v[190:193], v[116:119]
	v_mfma_f32_16x16x32_bf16 v[112:115], v[182:185], v[190:193], v[112:115]
	v_mfma_f32_16x16x32_bf16 v[100:103], v[174:177], v[198:201], v[100:103]
	v_mfma_f32_16x16x32_bf16 v[96:99], v[182:185], v[198:201], v[96:99]
	v_mfma_f32_16x16x32_bf16 v[84:87], v[174:177], v[210:213], v[84:87]
	v_mfma_f32_16x16x32_bf16 v[80:83], v[182:185], v[210:213], v[80:83]
	v_mfma_f32_16x16x32_bf16 v[68:71], v[174:177], v[218:221], v[68:71]
	v_mfma_f32_16x16x32_bf16 v[64:67], v[182:185], v[218:221], v[64:67]
	s_barrier
	s_setprio 0
	s_add_i32 s93, s93, s72
	s_mov_b64 s[98:99], s[94:95]
	s_mov_b32 m0, s93
	ds_read_b128 v[186:189], v154 offset:16384
	ds_read_b128 v[190:193], v154 offset:17408
	ds_read_b128 v[194:197], v154 offset:18432
	ds_read_b128 v[198:201], v154 offset:19456
	ds_read_b128 v[206:209], v154 offset:20480
	ds_read_b128 v[210:213], v154 offset:21504
	ds_read_b128 v[214:217], v154 offset:22528
	ds_read_b128 v[218:221], v154 offset:23552
	global_load_lds_dwordx4 v144, s[94:95]
	s_add_i32 m0, s93, 0x2000
	s_nop 0
	s_add_u32 s94, s94, s20
	s_addc_u32 s95, s95, 0
	s_add_i32 s42, s42, s72
	global_load_lds_dwordx4 v132, s[98:99]
	s_nop 0
	s_mov_b32 m0, s42
	s_nop 0
	global_load_lds_dwordx4 v144, s[94:95]
	s_add_i32 m0, s42, 0x2000
	s_mov_b64 s[100:101], s[26:27]
	global_load_lds_dwordx4 v132, s[94:95]
	s_mov_b32 m0, s73
	s_nop 0
	global_load_lds_dwordx4 v128, s[26:27]
	s_mov_b32 m0, s74
	s_nop 0
	global_load_lds_dwordx4 v130, s[26:27]
	s_waitcnt vmcnt(8)
	s_waitcnt lgkmcnt(0)
	s_setprio 1
	s_barrier
	v_mfma_f32_16x16x32_bf16 v[60:63], v[138:141], v[186:189], v[60:63]
	v_mfma_f32_16x16x32_bf16 v[56:59], v[160:163], v[186:189], v[56:59]
	v_mfma_f32_16x16x32_bf16 v[44:47], v[138:141], v[194:197], v[44:47]
	v_mfma_f32_16x16x32_bf16 v[40:43], v[160:163], v[194:197], v[40:43]
	v_mfma_f32_16x16x32_bf16 v[28:31], v[138:141], v[206:209], v[28:31]
	v_mfma_f32_16x16x32_bf16 v[24:27], v[160:163], v[206:209], v[24:27]
	v_mfma_f32_16x16x32_bf16 v[12:15], v[138:141], v[214:217], v[12:15]
	v_mfma_f32_16x16x32_bf16 v[8:11], v[160:163], v[214:217], v[8:11]
	v_mfma_f32_16x16x32_bf16 v[60:63], v[156:159], v[190:193], v[60:63]
	v_mfma_f32_16x16x32_bf16 v[56:59], v[166:169], v[190:193], v[56:59]
	v_mfma_f32_16x16x32_bf16 v[44:47], v[156:159], v[198:201], v[44:47]
	v_mfma_f32_16x16x32_bf16 v[40:43], v[166:169], v[198:201], v[40:43]
	v_mfma_f32_16x16x32_bf16 v[28:31], v[156:159], v[210:213], v[28:31]
	v_mfma_f32_16x16x32_bf16 v[24:27], v[166:169], v[210:213], v[24:27]
	v_mfma_f32_16x16x32_bf16 v[12:15], v[156:159], v[218:221], v[12:15]
	v_mfma_f32_16x16x32_bf16 v[8:11], v[166:169], v[218:221], v[8:11]
	v_mfma_f32_16x16x32_bf16 v[52:55], v[170:173], v[186:189], v[52:55]
	v_mfma_f32_16x16x32_bf16 v[48:51], v[178:181], v[186:189], v[48:51]
	v_mfma_f32_16x16x32_bf16 v[36:39], v[170:173], v[194:197], v[36:39]
	v_mfma_f32_16x16x32_bf16 v[32:35], v[178:181], v[194:197], v[32:35]
	v_mfma_f32_16x16x32_bf16 v[20:23], v[170:173], v[206:209], v[20:23]
	v_mfma_f32_16x16x32_bf16 v[16:19], v[178:181], v[206:209], v[16:19]
	v_mfma_f32_16x16x32_bf16 v[4:7], v[170:173], v[214:217], v[4:7]
	v_mfma_f32_16x16x32_bf16 v[0:3], v[178:181], v[214:217], v[0:3]
	v_mfma_f32_16x16x32_bf16 v[52:55], v[174:177], v[190:193], v[52:55]
	v_mfma_f32_16x16x32_bf16 v[48:51], v[182:185], v[190:193], v[48:51]
	v_mfma_f32_16x16x32_bf16 v[36:39], v[174:177], v[198:201], v[36:39]
	v_mfma_f32_16x16x32_bf16 v[32:35], v[182:185], v[198:201], v[32:35]
	v_mfma_f32_16x16x32_bf16 v[20:23], v[174:177], v[210:213], v[20:23]
	v_mfma_f32_16x16x32_bf16 v[16:19], v[182:185], v[210:213], v[16:19]
	v_mfma_f32_16x16x32_bf16 v[4:7], v[174:177], v[218:221], v[4:7]
	v_mfma_f32_16x16x32_bf16 v[0:3], v[182:185], v[218:221], v[0:3]
	s_barrier
	s_setprio 0
	s_add_i32 s42, 0, 0x18000
	v_add_u32_e32 v155, s42, v143
	s_add_i32 s93, 0, 0x1c000
	ds_read_b128 v[138:141], v155
	ds_read_b128 v[156:159], v155 offset:1024
	ds_read_b128 v[160:163], v155 offset:2048
	ds_read_b128 v[166:169], v155 offset:3072
	v_add_u32_e32 v155, s93, v143
	ds_read_b128 v[170:173], v155
	ds_read_b128 v[174:177], v155 offset:1024
	ds_read_b128 v[178:181], v155 offset:2048
	ds_read_b128 v[182:185], v155 offset:3072
	s_add_u32 s26, s26, s20
	s_addc_u32 s27, s27, 0
	s_mov_b32 m0, s75
	s_nop 0
	ds_read_b128 v[186:189], v154 offset:32768
	ds_read_b128 v[190:193], v154 offset:33792
	ds_read_b128 v[194:197], v154 offset:34816
	ds_read_b128 v[198:201], v154 offset:35840
	ds_read_b128 v[206:209], v154 offset:36864
	ds_read_b128 v[210:213], v154 offset:37888
	ds_read_b128 v[214:217], v154 offset:38912
	ds_read_b128 v[218:221], v154 offset:39936
	global_load_lds_dwordx4 v128, s[26:27]
	s_nop 0
	s_mov_b32 m0, s80
	s_nop 0
	global_load_lds_dwordx4 v130, s[26:27]
	s_waitcnt vmcnt(8)
	s_waitcnt lgkmcnt(0)
	s_setprio 1
	s_barrier
	v_mfma_f32_16x16x32_bf16 v[124:127], v[138:141], v[186:189], v[124:127]
	v_mfma_f32_16x16x32_bf16 v[120:123], v[160:163], v[186:189], v[120:123]
	v_mfma_f32_16x16x32_bf16 v[108:111], v[138:141], v[194:197], v[108:111]
	v_mfma_f32_16x16x32_bf16 v[104:107], v[160:163], v[194:197], v[104:107]
	v_mfma_f32_16x16x32_bf16 v[92:95], v[138:141], v[206:209], v[92:95]
	v_mfma_f32_16x16x32_bf16 v[88:91], v[160:163], v[206:209], v[88:91]
	v_mfma_f32_16x16x32_bf16 v[76:79], v[138:141], v[214:217], v[76:79]
	v_mfma_f32_16x16x32_bf16 v[72:75], v[160:163], v[214:217], v[72:75]
	v_mfma_f32_16x16x32_bf16 v[124:127], v[156:159], v[190:193], v[124:127]
	v_mfma_f32_16x16x32_bf16 v[120:123], v[166:169], v[190:193], v[120:123]
	v_mfma_f32_16x16x32_bf16 v[108:111], v[156:159], v[198:201], v[108:111]
	v_mfma_f32_16x16x32_bf16 v[104:107], v[166:169], v[198:201], v[104:107]
	v_mfma_f32_16x16x32_bf16 v[92:95], v[156:159], v[210:213], v[92:95]
	v_mfma_f32_16x16x32_bf16 v[88:91], v[166:169], v[210:213], v[88:91]
	v_mfma_f32_16x16x32_bf16 v[76:79], v[156:159], v[218:221], v[76:79]
	v_mfma_f32_16x16x32_bf16 v[72:75], v[166:169], v[218:221], v[72:75]
	v_mfma_f32_16x16x32_bf16 v[116:119], v[170:173], v[186:189], v[116:119]
	v_mfma_f32_16x16x32_bf16 v[112:115], v[178:181], v[186:189], v[112:115]
	v_mfma_f32_16x16x32_bf16 v[100:103], v[170:173], v[194:197], v[100:103]
	v_mfma_f32_16x16x32_bf16 v[96:99], v[178:181], v[194:197], v[96:99]
	v_mfma_f32_16x16x32_bf16 v[84:87], v[170:173], v[206:209], v[84:87]
	v_mfma_f32_16x16x32_bf16 v[80:83], v[178:181], v[206:209], v[80:83]
	v_mfma_f32_16x16x32_bf16 v[68:71], v[170:173], v[214:217], v[68:71]
	v_mfma_f32_16x16x32_bf16 v[64:67], v[178:181], v[214:217], v[64:67]
	v_mfma_f32_16x16x32_bf16 v[116:119], v[174:177], v[190:193], v[116:119]
	v_mfma_f32_16x16x32_bf16 v[112:115], v[182:185], v[190:193], v[112:115]
	v_mfma_f32_16x16x32_bf16 v[100:103], v[174:177], v[198:201], v[100:103]
	v_mfma_f32_16x16x32_bf16 v[96:99], v[182:185], v[198:201], v[96:99]
	v_mfma_f32_16x16x32_bf16 v[84:87], v[174:177], v[210:213], v[84:87]
	v_mfma_f32_16x16x32_bf16 v[80:83], v[182:185], v[210:213], v[80:83]
	v_mfma_f32_16x16x32_bf16 v[68:71], v[174:177], v[218:221], v[68:71]
	v_mfma_f32_16x16x32_bf16 v[64:67], v[182:185], v[218:221], v[64:67]
	s_barrier
	s_setprio 0
	s_add_i32 s26, s42, s72
	s_nop 0
	s_add_i32 m0, s26, 0xffffff80
	ds_read_b128 v[186:189], v154 offset:49152
	ds_read_b128 v[190:193], v154 offset:50176
	ds_read_b128 v[194:197], v154 offset:51200
	ds_read_b128 v[198:201], v154 offset:52224
	ds_read_b128 v[206:209], v154 offset:53248
	ds_read_b128 v[210:213], v154 offset:54272
	ds_read_b128 v[214:217], v154 offset:55296
	ds_read_b128 v[218:221], v154 offset:56320
	global_load_lds_dwordx4 v144, s[98:99] offset:128
	s_nop 0
	s_add_i32 m0, s26, 0x1f80
	s_add_i32 s26, s93, s72
	global_load_lds_dwordx4 v132, s[98:99] offset:128
	s_nop 0
	s_add_i32 m0, s26, 0xffffff80
	s_nop 0
	global_load_lds_dwordx4 v144, s[94:95] offset:128
	s_nop 0
	s_add_i32 m0, s26, 0x1f80
	s_nop 0
	global_load_lds_dwordx4 v132, s[94:95] offset:128
	s_nop 0
	s_add_i32 m0, s85, 0xffffff80
	s_nop 0
	global_load_lds_dwordx4 v128, s[100:101] offset:128
	s_nop 0
	s_add_i32 m0, s86, 0xffffff80
	s_nop 0
	global_load_lds_dwordx4 v130, s[100:101] offset:128
	s_waitcnt vmcnt(8)
	s_waitcnt lgkmcnt(0)
	s_setprio 1
	s_barrier
	v_mfma_f32_16x16x32_bf16 v[60:63], v[138:141], v[186:189], v[60:63]
	v_mfma_f32_16x16x32_bf16 v[56:59], v[160:163], v[186:189], v[56:59]
	v_mfma_f32_16x16x32_bf16 v[44:47], v[138:141], v[194:197], v[44:47]
	v_mfma_f32_16x16x32_bf16 v[40:43], v[160:163], v[194:197], v[40:43]
	v_mfma_f32_16x16x32_bf16 v[28:31], v[138:141], v[206:209], v[28:31]
	v_mfma_f32_16x16x32_bf16 v[24:27], v[160:163], v[206:209], v[24:27]
	v_mfma_f32_16x16x32_bf16 v[12:15], v[138:141], v[214:217], v[12:15]
	v_mfma_f32_16x16x32_bf16 v[8:11], v[160:163], v[214:217], v[8:11]
	v_mfma_f32_16x16x32_bf16 v[60:63], v[156:159], v[190:193], v[60:63]
	v_mfma_f32_16x16x32_bf16 v[56:59], v[166:169], v[190:193], v[56:59]
	v_mfma_f32_16x16x32_bf16 v[44:47], v[156:159], v[198:201], v[44:47]
	v_mfma_f32_16x16x32_bf16 v[40:43], v[166:169], v[198:201], v[40:43]
	v_mfma_f32_16x16x32_bf16 v[28:31], v[156:159], v[210:213], v[28:31]
	v_mfma_f32_16x16x32_bf16 v[24:27], v[166:169], v[210:213], v[24:27]
	v_mfma_f32_16x16x32_bf16 v[12:15], v[156:159], v[218:221], v[12:15]
	v_mfma_f32_16x16x32_bf16 v[8:11], v[166:169], v[218:221], v[8:11]
	v_mfma_f32_16x16x32_bf16 v[52:55], v[170:173], v[186:189], v[52:55]
	v_mfma_f32_16x16x32_bf16 v[48:51], v[178:181], v[186:189], v[48:51]
	v_mfma_f32_16x16x32_bf16 v[36:39], v[170:173], v[194:197], v[36:39]
	v_mfma_f32_16x16x32_bf16 v[32:35], v[178:181], v[194:197], v[32:35]
	v_mfma_f32_16x16x32_bf16 v[20:23], v[170:173], v[206:209], v[20:23]
	v_mfma_f32_16x16x32_bf16 v[16:19], v[178:181], v[206:209], v[16:19]
	v_mfma_f32_16x16x32_bf16 v[4:7], v[170:173], v[214:217], v[4:7]
	v_mfma_f32_16x16x32_bf16 v[0:3], v[178:181], v[214:217], v[0:3]
	v_mfma_f32_16x16x32_bf16 v[52:55], v[174:177], v[190:193], v[52:55]
	v_mfma_f32_16x16x32_bf16 v[48:51], v[182:185], v[190:193], v[48:51]
	v_mfma_f32_16x16x32_bf16 v[36:39], v[174:177], v[198:201], v[36:39]
	v_mfma_f32_16x16x32_bf16 v[32:35], v[182:185], v[198:201], v[32:35]
	v_mfma_f32_16x16x32_bf16 v[20:23], v[174:177], v[210:213], v[20:23]
	v_mfma_f32_16x16x32_bf16 v[16:19], v[182:185], v[210:213], v[16:19]
	v_mfma_f32_16x16x32_bf16 v[4:7], v[174:177], v[218:221], v[4:7]
	v_mfma_f32_16x16x32_bf16 v[0:3], v[182:185], v[218:221], v[0:3]
	s_barrier
	s_setprio 0
	s_add_u32 s91, s91, 0x100
	s_addc_u32 vcc_lo, vcc_lo, 0
	s_add_u32 s22, s22, 0x100
	s_addc_u32 s23, s23, 0
	s_cmp_ge_i32 vcc_hi, s1
	s_mov_b32 s26, vcc_hi
	s_cbranch_scc0 .LBB0_7633
	s_and_b64 vcc, exec, s[50:51]
	s_cbranch_vccz .LBB0_7636
	s_barrier

	.amdhsa_kernel _Z9trunk_fwd4Args
		.amdhsa_group_segment_fixed_size 0
		.amdhsa_private_segment_fixed_size 0
		.amdhsa_kernarg_size 512
		.amdhsa_user_sgpr_count 2
		.amdhsa_user_sgpr_dispatch_ptr 0
		.amdhsa_user_sgpr_queue_ptr 0
		.amdhsa_user_sgpr_kernarg_segment_ptr 1
		.amdhsa_user_sgpr_dispatch_id 0
		.amdhsa_user_sgpr_kernarg_preload_length 0
		.amdhsa_user_sgpr_kernarg_preload_offset 0
		.amdhsa_user_sgpr_private_segment_size 0
		.amdhsa_uses_dynamic_stack 0
		.amdhsa_enable_private_segment 0
		.amdhsa_system_sgpr_workgroup_id_x 1
		.amdhsa_system_sgpr_workgroup_id_y 0
		.amdhsa_system_sgpr_workgroup_id_z 0
		.amdhsa_system_sgpr_workgroup_info 0
		.amdhsa_system_vgpr_workitem_id 0
		.amdhsa_next_free_vgpr 255
		.amdhsa_next_free_sgpr 102
		.amdhsa_accum_offset 256
		.amdhsa_reserve_vcc 1
		.amdhsa_float_round_mode_32 0
		.amdhsa_float_round_mode_16_64 0
		.amdhsa_float_denorm_mode_32 3
		.amdhsa_float_denorm_mode_16_64 3
		.amdhsa_dx10_clamp 1
		.amdhsa_ieee_mode 1
		.amdhsa_fp16_overflow 0
		.amdhsa_tg_split 0
		.amdhsa_exception_fp_ieee_invalid_op 0
		.amdhsa_exception_fp_denorm_src 0
		.amdhsa_exception_fp_ieee_div_zero 0
		.amdhsa_exception_fp_ieee_overflow 0
		.amdhsa_exception_fp_ieee_underflow 0
		.amdhsa_exception_fp_ieee_inexact 0
		.amdhsa_exception_int_div_zero 0
	.end_amdhsa_kernel

amdhsa.kernels:
  - .agpr_count:     0
    .args:
      - .offset:         0
        .size:           256
        .value_kind:     by_value
      - .offset:         256
        .size:           4
        .value_kind:     hidden_block_count_x
      - .offset:         260
        .size:           4
        .value_kind:     hidden_block_count_y
      - .offset:         264
        .size:           4
        .value_kind:     hidden_block_count_z
      - .offset:         268
        .size:           2
        .value_kind:     hidden_group_size_x
      - .offset:         270
        .size:           2
        .value_kind:     hidden_group_size_y
      - .offset:         272
        .size:           2
        .value_kind:     hidden_group_size_z
      - .offset:         274
        .size:           2
        .value_kind:     hidden_remainder_x
      - .offset:         276
        .size:           2
        .value_kind:     hidden_remainder_y
      - .offset:         278
        .size:           2
        .value_kind:     hidden_remainder_z
      - .offset:         296
        .size:           8
        .value_kind:     hidden_global_offset_x
      - .offset:         304
        .size:           8
        .value_kind:     hidden_global_offset_y
      - .offset:         312
        .size:           8
        .value_kind:     hidden_global_offset_z
      - .offset:         320
        .size:           2
        .value_kind:     hidden_grid_dims
      - .offset:         376
        .size:           4
        .value_kind:     hidden_dynamic_lds_size
    .group_segment_fixed_size: 0
    .kernarg_segment_align: 8
    .kernarg_segment_size: 512
    .language:       OpenCL C
    .language_version:
      - 2
      - 0
    .max_flat_workgroup_size: 512
    .name:           _Z9trunk_fwd4Args
    .private_segment_fixed_size: 0
    .sgpr_count:     108
    .sgpr_spill_count: 204
    .symbol:         _Z9trunk_fwd4Args.kd
    .uniform_work_group_size: 1
    .uses_dynamic_stack: false
    .vgpr_count:     255
    .vgpr_spill_count: 0
    .wavefront_size: 64
